# v19 with the loop-carried SALU block hoisted above the loop-back barrier in the ten GEMM K-loops (7.11-lite)
# baseline (speedup 1.0000x reference)
; #define PG8_STAGE(bufoff, gbase, voff) do { _Pragma("unroll") for (int _i = 0; _i < 2; ++_i) \
;         __builtin_amdgcn_global_load_lds((const unsigned*)((const char*)(gbase) + (voff)[_i]), (PG8_LAS unsigned*)(lds + (bufoff) + ldsw + _i * 8192), 16, 0, 0); } while (0)
; #define PG8_LDA(dst, b, h) do { _Pragma("unroll") for (int m = 0; m < 4; ++m) _Pragma("unroll") for (int k = 0; k < 2; ++k) dst[m][k] = *(const PG8_LAS bf16x8*)(lds + PG8_SA(b, h) + aoff + m * 2048 + k * 1024); } while (0)
; #define PG8_LDB(dst, b, h) do { _Pragma("unroll") for (int n = 0; n < 2; ++n) _Pragma("unroll") for (int k = 0; k < 2; ++k) dst[n][k] = *(const PG8_LAS bf16x8*)(lds + PG8_SB(b, h) + boff + n * 2048 + k * 1024); } while (0)
; #define PG8_MMA(ai, bj, At, Bt) do { __builtin_amdgcn_s_setprio(1); _Pragma("unroll") for (int m = 0; m < 4; ++m) _Pragma("unroll") for (int n = 0; n < 2; ++n) _Pragma("unroll") for (int k = 0; k < 2; ++k) \
;         acc[ai][bj][m][n] = __builtin_amdgcn_mfma_f32_16x16x32_bf16(Bt[n][k], At[m][k], acc[ai][bj][m][n], 0, 0, 0); __builtin_amdgcn_s_setprio(0); } while (0)
; #define PG8_WAIT_V(n) asm volatile("s_waitcnt vmcnt(" #n ")" ::: "memory")
; #define PG8_WAIT_L(n) asm volatile("s_waitcnt lgkmcnt(" #n ")" ::: "memory")
; #define PG8_BAR __builtin_amdgcn_s_barrier()
; #define PG8_SCHED __builtin_amdgcn_sched_barrier(0)
; template <class Epi, class Sched, bool ALIGN_EPI = false, bool SP2 = false>
; __device__ __forceinline__ void gemm_phase(PG8_LAS unsigned char* lds, const Gemm g, const Sched& S, const Epi& E) {
;     ...
;             PG8_LDB(B0, 0, 0); PG8_LDB(B1, 0, 1); PG8_SCHED; PG8_LDA(At, 0, 0); PG8_STAGE(PG8_SA(1, 1), a1 + hstep, voffA);
;             PG8_WAIT_V(8); PG8_WAIT_L(0); PG8_BAR; PG8_MMA(0, 0, At, B0); PG8_MMA(0, 1, At, B1); PG8_BAR; PG8_SCHED;
;             PG8_LDA(At, 0, 1); PG8_STAGE(PG8_SB(0, 0), b2, voffB); PG8_STAGE(PG8_SB(0, 1), b2 + hstep, voffB); PG8_STAGE(PG8_SA(0, 0), a2, voffA);
;             PG8_WAIT_V(8); PG8_WAIT_L(0); PG8_BAR; PG8_MMA(1, 0, At, B0); PG8_MMA(1, 1, At, B1); PG8_BAR; PG8_SCHED;
.LBB0_213:
	ds_read_b128 v[180:183], v173
	ds_read_b128 v[184:187], v173 offset:1024
	ds_read_b128 v[188:191], v173 offset:2048
	ds_read_b128 v[192:195], v173 offset:3072
	ds_read_b128 v[196:199], v174
	ds_read_b128 v[200:203], v174 offset:1024
	ds_read_b128 v[204:207], v174 offset:2048
	ds_read_b128 v[208:211], v174 offset:3072
	s_add_u32 s2, s36, 0xfffc0080
	s_addc_u32 s3, s37, -1
	s_cmp_eq_u32 s69, 12
	s_cselect_b32 s19, s0, s3
	s_cselect_b32 s18, s27, s2
	s_cselect_b32 s3, s25, s68
	s_cselect_b32 s2, s66, s67
	v_lshl_add_u64 v[154:155], s[36:37], 0, v[128:129]
	s_add_i32 m0, s35, 0xc000
	ds_read_b128 v[212:215], v175
	ds_read_b128 v[216:219], v175 offset:1024
	ds_read_b128 v[220:223], v175 offset:2048
	ds_read_b128 v[224:227], v175 offset:3072
	ds_read_b128 v[228:231], v175 offset:4096
	ds_read_b128 v[232:235], v175 offset:5120
	ds_read_b128 v[236:239], v175 offset:6144
	ds_read_b128 v[240:243], v175 offset:7168
	global_load_lds_dwordx4 v[154:155], off
	v_lshl_add_u64 v[154:155], s[36:37], 0, v[130:131]
	s_add_i32 m0, s35, 0xe000
	s_nop 0
	global_load_lds_dwordx4 v[154:155], off
	s_waitcnt vmcnt(8)
	s_waitcnt lgkmcnt(0)
	s_barrier
	s_setprio 1
	s_waitcnt lgkmcnt(0)
	v_mfma_f32_16x16x32_bf16 v[124:127], v[180:183], v[212:215], v[124:127]
	v_mfma_f32_16x16x32_bf16 v[120:123], v[188:191], v[212:215], v[120:123]
	v_mfma_f32_16x16x32_bf16 v[116:119], v[180:183], v[220:223], v[116:119]
	v_mfma_f32_16x16x32_bf16 v[108:111], v[188:191], v[220:223], v[108:111]
	v_mfma_f32_16x16x32_bf16 v[100:103], v[180:183], v[228:231], v[100:103]
	v_mfma_f32_16x16x32_bf16 v[92:95], v[188:191], v[228:231], v[92:95]
	v_mfma_f32_16x16x32_bf16 v[84:87], v[180:183], v[236:239], v[84:87]
	v_mfma_f32_16x16x32_bf16 v[76:79], v[188:191], v[236:239], v[76:79]
	v_mfma_f32_16x16x32_bf16 v[124:127], v[184:187], v[216:219], v[124:127]
	v_mfma_f32_16x16x32_bf16 v[120:123], v[192:195], v[216:219], v[120:123]
	v_mfma_f32_16x16x32_bf16 v[116:119], v[184:187], v[224:227], v[116:119]
	v_mfma_f32_16x16x32_bf16 v[108:111], v[192:195], v[224:227], v[108:111]
	v_mfma_f32_16x16x32_bf16 v[100:103], v[184:187], v[232:235], v[100:103]
	v_mfma_f32_16x16x32_bf16 v[92:95], v[192:195], v[232:235], v[92:95]
	v_mfma_f32_16x16x32_bf16 v[84:87], v[184:187], v[240:243], v[84:87]
	v_mfma_f32_16x16x32_bf16 v[76:79], v[192:195], v[240:243], v[76:79]
	s_setprio 0
	s_setprio 1
	v_mfma_f32_16x16x32_bf16 v[112:115], v[196:199], v[212:215], v[112:115]
	v_mfma_f32_16x16x32_bf16 v[104:107], v[204:207], v[212:215], v[104:107]
	v_mfma_f32_16x16x32_bf16 v[96:99], v[196:199], v[220:223], v[96:99]
	v_mfma_f32_16x16x32_bf16 v[88:91], v[204:207], v[220:223], v[88:91]
	v_mfma_f32_16x16x32_bf16 v[80:83], v[196:199], v[228:231], v[80:83]
	v_mfma_f32_16x16x32_bf16 v[72:75], v[204:207], v[228:231], v[72:75]
	v_mfma_f32_16x16x32_bf16 v[68:71], v[196:199], v[236:239], v[68:71]
	v_mfma_f32_16x16x32_bf16 v[64:67], v[204:207], v[236:239], v[64:67]
	v_mfma_f32_16x16x32_bf16 v[112:115], v[200:203], v[216:219], v[112:115]
	v_mfma_f32_16x16x32_bf16 v[104:107], v[208:211], v[216:219], v[104:107]
	v_mfma_f32_16x16x32_bf16 v[96:99], v[200:203], v[224:227], v[96:99]
	v_mfma_f32_16x16x32_bf16 v[88:91], v[208:211], v[224:227], v[88:91]
	v_mfma_f32_16x16x32_bf16 v[80:83], v[200:203], v[232:235], v[80:83]
	v_mfma_f32_16x16x32_bf16 v[72:75], v[208:211], v[232:235], v[72:75]
	v_mfma_f32_16x16x32_bf16 v[68:71], v[200:203], v[240:243], v[68:71]
	v_mfma_f32_16x16x32_bf16 v[64:67], v[208:211], v[240:243], v[64:67]
	s_setprio 0
	s_barrier
	s_add_i32 s64, s55, s42
	v_lshl_add_u64 v[154:155], s[2:3], 0, v[146:147]
	s_mov_b32 m0, s64
	ds_read_b128 v[212:215], v175 offset:16384
	ds_read_b128 v[216:219], v175 offset:17408
	ds_read_b128 v[220:223], v175 offset:18432
	ds_read_b128 v[224:227], v175 offset:19456
	ds_read_b128 v[228:231], v175 offset:20480
	ds_read_b128 v[232:235], v175 offset:21504
	ds_read_b128 v[236:239], v175 offset:22528
	ds_read_b128 v[240:243], v175 offset:23552
	global_load_lds_dwordx4 v[154:155], off
	s_add_i32 m0, s64, 0x2000
	s_add_u32 s70, s2, 0x40000
	v_lshl_add_u64 v[158:159], s[2:3], 0, v[150:151]
	s_addc_u32 s71, s3, 0
	s_add_i32 s64, s58, s42
	global_load_lds_dwordx4 v[158:159], off
	v_lshl_add_u64 v[162:163], s[70:71], 0, v[146:147]
	s_mov_b32 m0, s64
	v_lshl_add_u64 v[166:167], s[18:19], 0, v[148:149]
	global_load_lds_dwordx4 v[162:163], off
	v_lshl_add_u64 v[162:163], s[70:71], 0, v[150:151]
	s_add_i32 m0, s64, 0x2000
	s_nop 0
	global_load_lds_dwordx4 v[162:163], off
	v_lshl_add_u64 v[162:163], s[18:19], 0, v[144:145]
	s_mov_b32 m0, s35
	s_nop 0
	global_load_lds_dwordx4 v[162:163], off
	s_mov_b32 m0, s43
	s_nop 0
	global_load_lds_dwordx4 v[166:167], off
	s_waitcnt vmcnt(8)
	s_waitcnt lgkmcnt(0)
	s_barrier
; #define PG8_STAGE(bufoff, gbase, voff) do { _Pragma("unroll") for (int _i = 0; _i < 2; ++_i) \
;         __builtin_amdgcn_global_load_lds((const unsigned*)((const char*)(gbase) + (voff)[_i]), (PG8_LAS unsigned*)(lds + (bufoff) + ldsw + _i * 8192), 16, 0, 0); } while (0)
; #define PG8_LDA(dst, b, h) do { _Pragma("unroll") for (int m = 0; m < 4; ++m) _Pragma("unroll") for (int k = 0; k < 2; ++k) dst[m][k] = *(const PG8_LAS bf16x8*)(lds + PG8_SA(b, h) + aoff + m * 2048 + k * 1024); } while (0)
; #define PG8_LDB(dst, b, h) do { _Pragma("unroll") for (int n = 0; n < 2; ++n) _Pragma("unroll") for (int k = 0; k < 2; ++k) dst[n][k] = *(const PG8_LAS bf16x8*)(lds + PG8_SB(b, h) + boff + n * 2048 + k * 1024); } while (0)
; #define PG8_MMA(ai, bj, At, Bt) do { __builtin_amdgcn_s_setprio(1); _Pragma("unroll") for (int m = 0; m < 4; ++m) _Pragma("unroll") for (int n = 0; n < 2; ++n) _Pragma("unroll") for (int k = 0; k < 2; ++k) \
;         acc[ai][bj][m][n] = __builtin_amdgcn_mfma_f32_16x16x32_bf16(Bt[n][k], At[m][k], acc[ai][bj][m][n], 0, 0, 0); __builtin_amdgcn_s_setprio(0); } while (0)
; #define PG8_WAIT_V(n) asm volatile("s_waitcnt vmcnt(" #n ")" ::: "memory")
; #define PG8_WAIT_L(n) asm volatile("s_waitcnt lgkmcnt(" #n ")" ::: "memory")
; #define PG8_BAR __builtin_amdgcn_s_barrier()
; #define PG8_SCHED __builtin_amdgcn_sched_barrier(0)
; template <class Epi, class Sched, bool ALIGN_EPI = false, bool SP2 = false>
; __device__ __forceinline__ void gemm_phase(PG8_LAS unsigned char* lds, const Gemm g, const Sched& S, const Epi& E) {
;     ...
;             PG8_WAIT_V(8); PG8_WAIT_L(0); PG8_BAR; PG8_MMA(1, 0, At, B0); PG8_MMA(1, 1, At, B1); PG8_BAR; PG8_SCHED;
;             PG8_LDB(B0, 1, 0); PG8_LDB(B1, 1, 1); PG8_SCHED; PG8_LDA(At, 1, 0); PG8_STAGE(PG8_SA(0, 1), a2 + hstep, voffA);
;             PG8_WAIT_V(8); PG8_WAIT_L(0); PG8_BAR; PG8_MMA(0, 0, At, B0); PG8_MMA(0, 1, At, B1); PG8_BAR; PG8_SCHED;
	s_setprio 1
	s_waitcnt lgkmcnt(0)
	v_mfma_f32_16x16x32_bf16 v[60:63], v[180:183], v[212:215], v[60:63]
	v_mfma_f32_16x16x32_bf16 v[56:59], v[188:191], v[212:215], v[56:59]
	v_mfma_f32_16x16x32_bf16 v[52:55], v[180:183], v[220:223], v[52:55]
	v_mfma_f32_16x16x32_bf16 v[44:47], v[188:191], v[220:223], v[44:47]
	v_mfma_f32_16x16x32_bf16 v[36:39], v[180:183], v[228:231], v[36:39]
	v_mfma_f32_16x16x32_bf16 v[28:31], v[188:191], v[228:231], v[28:31]
	v_mfma_f32_16x16x32_bf16 v[20:23], v[180:183], v[236:239], v[20:23]
	v_mfma_f32_16x16x32_bf16 v[12:15], v[188:191], v[236:239], v[12:15]
	v_mfma_f32_16x16x32_bf16 v[60:63], v[184:187], v[216:219], v[60:63]
	v_mfma_f32_16x16x32_bf16 v[56:59], v[192:195], v[216:219], v[56:59]
	v_mfma_f32_16x16x32_bf16 v[52:55], v[184:187], v[224:227], v[52:55]
	v_mfma_f32_16x16x32_bf16 v[44:47], v[192:195], v[224:227], v[44:47]
	v_mfma_f32_16x16x32_bf16 v[36:39], v[184:187], v[232:235], v[36:39]
	v_mfma_f32_16x16x32_bf16 v[28:31], v[192:195], v[232:235], v[28:31]
	v_mfma_f32_16x16x32_bf16 v[20:23], v[184:187], v[240:243], v[20:23]
	v_mfma_f32_16x16x32_bf16 v[12:15], v[192:195], v[240:243], v[12:15]
	s_setprio 0
	s_setprio 1
	v_mfma_f32_16x16x32_bf16 v[48:51], v[196:199], v[212:215], v[48:51]
	v_mfma_f32_16x16x32_bf16 v[40:43], v[204:207], v[212:215], v[40:43]
	v_mfma_f32_16x16x32_bf16 v[32:35], v[196:199], v[220:223], v[32:35]
	v_mfma_f32_16x16x32_bf16 v[24:27], v[204:207], v[220:223], v[24:27]
	v_mfma_f32_16x16x32_bf16 v[16:19], v[196:199], v[228:231], v[16:19]
	v_mfma_f32_16x16x32_bf16 v[8:11], v[204:207], v[228:231], v[8:11]
	v_mfma_f32_16x16x32_bf16 v[4:7], v[196:199], v[236:239], v[4:7]
	v_mfma_f32_16x16x32_bf16 v[0:3], v[204:207], v[236:239], v[0:3]
	v_mfma_f32_16x16x32_bf16 v[48:51], v[200:203], v[216:219], v[48:51]
	v_mfma_f32_16x16x32_bf16 v[40:43], v[208:211], v[216:219], v[40:43]
	v_mfma_f32_16x16x32_bf16 v[32:35], v[200:203], v[224:227], v[32:35]
	v_mfma_f32_16x16x32_bf16 v[24:27], v[208:211], v[224:227], v[24:27]
	v_mfma_f32_16x16x32_bf16 v[16:19], v[200:203], v[232:235], v[16:19]
	v_mfma_f32_16x16x32_bf16 v[8:11], v[208:211], v[232:235], v[8:11]
	v_mfma_f32_16x16x32_bf16 v[4:7], v[200:203], v[240:243], v[4:7]
	v_mfma_f32_16x16x32_bf16 v[0:3], v[208:211], v[240:243], v[0:3]
	s_setprio 0
	s_barrier
	s_add_i32 s64, 0, 0x18000
	v_add_u32_e32 v136, s64, v171
	s_add_i32 s70, 0, 0x1c000
	ds_read_b128 v[180:183], v136
	ds_read_b128 v[184:187], v136 offset:1024
	ds_read_b128 v[188:191], v136 offset:2048
	ds_read_b128 v[192:195], v136 offset:3072
	v_add_u32_e32 v136, s70, v171
	ds_read_b128 v[196:199], v136
	ds_read_b128 v[200:203], v136 offset:1024
	ds_read_b128 v[204:207], v136 offset:2048
	ds_read_b128 v[208:211], v136 offset:3072
	s_add_u32 s18, s18, 0x40000
	s_addc_u32 s19, s19, 0
	s_mov_b32 m0, s46
	v_lshl_add_u64 v[244:245], s[18:19], 0, v[144:145]
	ds_read_b128 v[212:215], v175 offset:32768
	ds_read_b128 v[216:219], v175 offset:33792
	ds_read_b128 v[220:223], v175 offset:34816
	ds_read_b128 v[224:227], v175 offset:35840
	ds_read_b128 v[228:231], v175 offset:36864
	ds_read_b128 v[232:235], v175 offset:37888
	ds_read_b128 v[236:239], v175 offset:38912
	ds_read_b128 v[240:243], v175 offset:39936
	global_load_lds_dwordx4 v[244:245], off
	v_lshl_add_u64 v[244:245], s[18:19], 0, v[148:149]
	s_mov_b32 m0, s47
	s_nop 0
	global_load_lds_dwordx4 v[244:245], off
	s_waitcnt vmcnt(8)
	s_waitcnt lgkmcnt(0)
	s_barrier
	s_setprio 1
	s_waitcnt lgkmcnt(0)
	v_mfma_f32_16x16x32_bf16 v[124:127], v[180:183], v[212:215], v[124:127]
	v_mfma_f32_16x16x32_bf16 v[120:123], v[188:191], v[212:215], v[120:123]
	v_mfma_f32_16x16x32_bf16 v[116:119], v[180:183], v[220:223], v[116:119]
	v_mfma_f32_16x16x32_bf16 v[108:111], v[188:191], v[220:223], v[108:111]
	v_mfma_f32_16x16x32_bf16 v[100:103], v[180:183], v[228:231], v[100:103]
	v_mfma_f32_16x16x32_bf16 v[92:95], v[188:191], v[228:231], v[92:95]
	v_mfma_f32_16x16x32_bf16 v[84:87], v[180:183], v[236:239], v[84:87]
	v_mfma_f32_16x16x32_bf16 v[76:79], v[188:191], v[236:239], v[76:79]
	v_mfma_f32_16x16x32_bf16 v[124:127], v[184:187], v[216:219], v[124:127]
	v_mfma_f32_16x16x32_bf16 v[120:123], v[192:195], v[216:219], v[120:123]
	v_mfma_f32_16x16x32_bf16 v[116:119], v[184:187], v[224:227], v[116:119]
	v_mfma_f32_16x16x32_bf16 v[108:111], v[192:195], v[224:227], v[108:111]
	v_mfma_f32_16x16x32_bf16 v[100:103], v[184:187], v[232:235], v[100:103]
	v_mfma_f32_16x16x32_bf16 v[92:95], v[192:195], v[232:235], v[92:95]
	v_mfma_f32_16x16x32_bf16 v[84:87], v[184:187], v[240:243], v[84:87]
	v_mfma_f32_16x16x32_bf16 v[76:79], v[192:195], v[240:243], v[76:79]
	s_setprio 0
	s_setprio 1
	v_mfma_f32_16x16x32_bf16 v[112:115], v[196:199], v[212:215], v[112:115]
	v_mfma_f32_16x16x32_bf16 v[104:107], v[204:207], v[212:215], v[104:107]
	v_mfma_f32_16x16x32_bf16 v[96:99], v[196:199], v[220:223], v[96:99]
	v_mfma_f32_16x16x32_bf16 v[88:91], v[204:207], v[220:223], v[88:91]
	v_mfma_f32_16x16x32_bf16 v[80:83], v[196:199], v[228:231], v[80:83]
	v_mfma_f32_16x16x32_bf16 v[72:75], v[204:207], v[228:231], v[72:75]
	v_mfma_f32_16x16x32_bf16 v[68:71], v[196:199], v[236:239], v[68:71]
	v_mfma_f32_16x16x32_bf16 v[64:67], v[204:207], v[236:239], v[64:67]
	v_mfma_f32_16x16x32_bf16 v[112:115], v[200:203], v[216:219], v[112:115]
	v_mfma_f32_16x16x32_bf16 v[104:107], v[208:211], v[216:219], v[104:107]
	v_mfma_f32_16x16x32_bf16 v[96:99], v[200:203], v[224:227], v[96:99]
	v_mfma_f32_16x16x32_bf16 v[88:91], v[208:211], v[224:227], v[88:91]
	v_mfma_f32_16x16x32_bf16 v[80:83], v[200:203], v[232:235], v[80:83]
	v_mfma_f32_16x16x32_bf16 v[72:75], v[208:211], v[232:235], v[72:75]
	v_mfma_f32_16x16x32_bf16 v[68:71], v[200:203], v[240:243], v[68:71]
	v_mfma_f32_16x16x32_bf16 v[64:67], v[208:211], v[240:243], v[64:67]
	s_setprio 0
	s_barrier
; #define PG8_STAGE(bufoff, gbase, voff) do { _Pragma("unroll") for (int _i = 0; _i < 2; ++_i) \
;         __builtin_amdgcn_global_load_lds((const unsigned*)((const char*)(gbase) + (voff)[_i]), (PG8_LAS unsigned*)(lds + (bufoff) + ldsw + _i * 8192), 16, 0, 0); } while (0)
; #define PG8_LDA(dst, b, h) do { _Pragma("unroll") for (int m = 0; m < 4; ++m) _Pragma("unroll") for (int k = 0; k < 2; ++k) dst[m][k] = *(const PG8_LAS bf16x8*)(lds + PG8_SA(b, h) + aoff + m * 2048 + k * 1024); } while (0)
; #define PG8_MMA(ai, bj, At, Bt) do { __builtin_amdgcn_s_setprio(1); _Pragma("unroll") for (int m = 0; m < 4; ++m) _Pragma("unroll") for (int n = 0; n < 2; ++n) _Pragma("unroll") for (int k = 0; k < 2; ++k) \
;         acc[ai][bj][m][n] = __builtin_amdgcn_mfma_f32_16x16x32_bf16(Bt[n][k], At[m][k], acc[ai][bj][m][n], 0, 0, 0); __builtin_amdgcn_s_setprio(0); } while (0)
; #define PG8_WAIT_V(n) asm volatile("s_waitcnt vmcnt(" #n ")" ::: "memory")
; #define PG8_WAIT_L(n) asm volatile("s_waitcnt lgkmcnt(" #n ")" ::: "memory")
; #define PG8_BAR __builtin_amdgcn_s_barrier()
; #define PG8_SCHED __builtin_amdgcn_sched_barrier(0)
; template <class Epi, class Sched, bool ALIGN_EPI = false, bool SP2 = false>
; __device__ __forceinline__ void gemm_phase(PG8_LAS unsigned char* lds, const Gemm g, const Sched& S, const Epi& E) {
;     ...
;         for (int t = 0; t < nt; t += 2) {
;     ...
;             PG8_LDA(At, 1, 1); PG8_STAGE(PG8_SB(1, 0), b3, voffB); PG8_STAGE(PG8_SB(1, 1), b3 + hstep, voffB); PG8_STAGE(PG8_SA(1, 0), a3, voffA);
;             PG8_WAIT_V(8); PG8_WAIT_L(0); PG8_BAR; PG8_MMA(1, 0, At, B0); PG8_MMA(1, 1, At, B1); PG8_BAR; PG8_SCHED;
	s_add_i32 s18, s64, s42
	v_lshl_add_u64 v[154:155], v[154:155], 0, s[10:11]
	s_mov_b32 m0, s18
	ds_read_b128 v[212:215], v175 offset:49152
	ds_read_b128 v[216:219], v175 offset:50176
	ds_read_b128 v[220:223], v175 offset:51200
	ds_read_b128 v[224:227], v175 offset:52224
	ds_read_b128 v[228:231], v175 offset:53248
	ds_read_b128 v[232:235], v175 offset:54272
	ds_read_b128 v[236:239], v175 offset:55296
	ds_read_b128 v[240:243], v175 offset:56320
	global_load_lds_dwordx4 v[154:155], off
	s_add_i32 m0, s18, 0x2000
	s_add_u32 s2, s2, 0x40080
	v_lshl_add_u64 v[154:155], v[158:159], 0, s[10:11]
	s_addc_u32 s3, s3, 0
	s_add_i32 s18, s70, s42
	global_load_lds_dwordx4 v[154:155], off
	v_lshl_add_u64 v[154:155], s[2:3], 0, v[146:147]
	s_mov_b32 m0, s18
	s_nop 0
	global_load_lds_dwordx4 v[154:155], off
	v_lshl_add_u64 v[154:155], s[2:3], 0, v[150:151]
	s_add_i32 m0, s18, 0x2000
	s_nop 0
	global_load_lds_dwordx4 v[154:155], off
	v_lshl_add_u64 v[154:155], v[162:163], 0, s[10:11]
	s_mov_b32 m0, s51
	s_nop 0
	global_load_lds_dwordx4 v[154:155], off
	v_lshl_add_u64 v[154:155], v[166:167], 0, s[10:11]
	s_mov_b32 m0, s52
	s_nop 0
	global_load_lds_dwordx4 v[154:155], off
	s_waitcnt vmcnt(8)
	s_waitcnt lgkmcnt(0)
	s_barrier
	s_setprio 1
	s_waitcnt lgkmcnt(0)
	v_mfma_f32_16x16x32_bf16 v[60:63], v[180:183], v[212:215], v[60:63]
	v_mfma_f32_16x16x32_bf16 v[56:59], v[188:191], v[212:215], v[56:59]
	v_mfma_f32_16x16x32_bf16 v[52:55], v[180:183], v[220:223], v[52:55]
	v_mfma_f32_16x16x32_bf16 v[44:47], v[188:191], v[220:223], v[44:47]
	v_mfma_f32_16x16x32_bf16 v[36:39], v[180:183], v[228:231], v[36:39]
	v_mfma_f32_16x16x32_bf16 v[28:31], v[188:191], v[228:231], v[28:31]
	v_mfma_f32_16x16x32_bf16 v[20:23], v[180:183], v[236:239], v[20:23]
	v_mfma_f32_16x16x32_bf16 v[12:15], v[188:191], v[236:239], v[12:15]
	v_mfma_f32_16x16x32_bf16 v[60:63], v[184:187], v[216:219], v[60:63]
	v_mfma_f32_16x16x32_bf16 v[56:59], v[192:195], v[216:219], v[56:59]
	v_mfma_f32_16x16x32_bf16 v[52:55], v[184:187], v[224:227], v[52:55]
	v_mfma_f32_16x16x32_bf16 v[44:47], v[192:195], v[224:227], v[44:47]
	v_mfma_f32_16x16x32_bf16 v[36:39], v[184:187], v[232:235], v[36:39]
	v_mfma_f32_16x16x32_bf16 v[28:31], v[192:195], v[232:235], v[28:31]
	v_mfma_f32_16x16x32_bf16 v[20:23], v[184:187], v[240:243], v[20:23]
	v_mfma_f32_16x16x32_bf16 v[12:15], v[192:195], v[240:243], v[12:15]
	s_setprio 0
	s_setprio 1
	v_mfma_f32_16x16x32_bf16 v[48:51], v[196:199], v[212:215], v[48:51]
	v_mfma_f32_16x16x32_bf16 v[40:43], v[204:207], v[212:215], v[40:43]
	v_mfma_f32_16x16x32_bf16 v[32:35], v[196:199], v[220:223], v[32:35]
	v_mfma_f32_16x16x32_bf16 v[24:27], v[204:207], v[220:223], v[24:27]
	v_mfma_f32_16x16x32_bf16 v[16:19], v[196:199], v[228:231], v[16:19]
	v_mfma_f32_16x16x32_bf16 v[8:11], v[204:207], v[228:231], v[8:11]
	v_mfma_f32_16x16x32_bf16 v[4:7], v[196:199], v[236:239], v[4:7]
	v_mfma_f32_16x16x32_bf16 v[0:3], v[204:207], v[236:239], v[0:3]
	v_mfma_f32_16x16x32_bf16 v[48:51], v[200:203], v[216:219], v[48:51]
	v_mfma_f32_16x16x32_bf16 v[40:43], v[208:211], v[216:219], v[40:43]
	v_mfma_f32_16x16x32_bf16 v[32:35], v[200:203], v[224:227], v[32:35]
	v_mfma_f32_16x16x32_bf16 v[24:27], v[208:211], v[224:227], v[24:27]
	v_mfma_f32_16x16x32_bf16 v[16:19], v[200:203], v[232:235], v[16:19]
	v_mfma_f32_16x16x32_bf16 v[8:11], v[208:211], v[232:235], v[8:11]
	v_mfma_f32_16x16x32_bf16 v[4:7], v[200:203], v[240:243], v[4:7]
	v_mfma_f32_16x16x32_bf16 v[0:3], v[208:211], v[240:243], v[0:3]
	s_setprio 0
	s_add_i32 s69, s69, 2
	s_add_u32 s36, s36, 0x100
	s_addc_u32 s37, s37, 0
	s_add_u32 s67, s67, 0x100
	s_addc_u32 s68, s68, 0
	s_cmp_gt_u32 s69, 13
	s_barrier
	s_cbranch_scc0 .LBB0_213
	s_and_b64 vcc, exec, s[12:13]
	s_cbranch_vccz .LBB0_216
	s_barrier

; #define PG8_STAGE(bufoff, gbase, voff) do { _Pragma("unroll") for (int _i = 0; _i < 2; ++_i) \
;         __builtin_amdgcn_global_load_lds((const unsigned*)((const char*)(gbase) + (voff)[_i]), (PG8_LAS unsigned*)(lds + (bufoff) + ldsw + _i * 8192), 16, 0, 0); } while (0)
; #define PG8_LDA(dst, b, h) do { _Pragma("unroll") for (int m = 0; m < 4; ++m) _Pragma("unroll") for (int k = 0; k < 2; ++k) dst[m][k] = *(const PG8_LAS bf16x8*)(lds + PG8_SA(b, h) + aoff + m * 2048 + k * 1024); } while (0)
; #define PG8_LDB(dst, b, h) do { _Pragma("unroll") for (int n = 0; n < 2; ++n) _Pragma("unroll") for (int k = 0; k < 2; ++k) dst[n][k] = *(const PG8_LAS bf16x8*)(lds + PG8_SB(b, h) + boff + n * 2048 + k * 1024); } while (0)
; #define PG8_MMA(ai, bj, At, Bt) do { __builtin_amdgcn_s_setprio(1); _Pragma("unroll") for (int m = 0; m < 4; ++m) _Pragma("unroll") for (int n = 0; n < 2; ++n) _Pragma("unroll") for (int k = 0; k < 2; ++k) \
;         acc[ai][bj][m][n] = __builtin_amdgcn_mfma_f32_16x16x32_bf16(Bt[n][k], At[m][k], acc[ai][bj][m][n], 0, 0, 0); __builtin_amdgcn_s_setprio(0); } while (0)
; #define PG8_WAIT_V(n) asm volatile("s_waitcnt vmcnt(" #n ")" ::: "memory")
; #define PG8_WAIT_L(n) asm volatile("s_waitcnt lgkmcnt(" #n ")" ::: "memory")
; #define PG8_BAR __builtin_amdgcn_s_barrier()
; #define PG8_SCHED __builtin_amdgcn_sched_barrier(0)
; template <class Epi, class Sched, bool ALIGN_EPI = false, bool SP2 = false>
; __device__ __forceinline__ void gemm_phase(PG8_LAS unsigned char* lds, const Gemm g, const Sched& S, const Epi& E) {
;     ...
;             PG8_LDB(B0, 0, 0); PG8_LDB(B1, 0, 1); PG8_SCHED; PG8_LDA(At, 0, 0); PG8_STAGE(PG8_SA(1, 1), a1 + hstep, voffA);
;             PG8_WAIT_V(8); PG8_WAIT_L(0); PG8_BAR; PG8_MMA(0, 0, At, B0); PG8_MMA(0, 1, At, B1); PG8_BAR; PG8_SCHED;
;             PG8_LDA(At, 0, 1); PG8_STAGE(PG8_SB(0, 0), b2, voffB); PG8_STAGE(PG8_SB(0, 1), b2 + hstep, voffB); PG8_STAGE(PG8_SA(0, 0), a2, voffA);
;             PG8_WAIT_V(8); PG8_WAIT_L(0); PG8_BAR; PG8_MMA(1, 0, At, B0); PG8_MMA(1, 1, At, B1); PG8_BAR; PG8_SCHED;
.LBB0_241:
	ds_read_b128 v[128:131], v162
	ds_read_b128 v[132:135], v162 offset:1024
	ds_read_b128 v[136:139], v162 offset:2048
	ds_read_b128 v[140:143], v162 offset:3072
	ds_read_b128 v[168:171], v163
	ds_read_b128 v[172:175], v163 offset:1024
	ds_read_b128 v[178:181], v163 offset:2048
	ds_read_b128 v[182:185], v163 offset:3072
	s_add_u32 s2, s22, 0xfffc0080
	s_addc_u32 s3, s23, -1
	s_cmp_eq_u32 s52, 12
	s_cselect_b32 s19, s13, s3
	s_cselect_b32 s18, s48, s2
	s_cselect_b32 s3, s11, s51
	s_cselect_b32 s2, s49, s50
	v_lshl_add_u64 v[218:219], s[22:23], 0, v[152:153]
	s_add_i32 m0, s21, 0xc000
	ds_read_b128 v[186:189], v164
	ds_read_b128 v[190:193], v164 offset:1024
	ds_read_b128 v[194:197], v164 offset:2048
	ds_read_b128 v[198:201], v164 offset:3072
	ds_read_b128 v[202:205], v164 offset:4096
	ds_read_b128 v[206:209], v164 offset:5120
	ds_read_b128 v[210:213], v164 offset:6144
	ds_read_b128 v[214:217], v164 offset:7168
	global_load_lds_dwordx4 v[218:219], off
	v_lshl_add_u64 v[218:219], s[22:23], 0, v[154:155]
	s_add_i32 m0, s21, 0xe000
	s_nop 0
	global_load_lds_dwordx4 v[218:219], off
	s_waitcnt vmcnt(8)
	s_waitcnt lgkmcnt(0)
	s_barrier
	s_setprio 1
	s_waitcnt lgkmcnt(0)
	v_mfma_f32_16x16x32_bf16 v[124:127], v[128:131], v[186:189], v[124:127]
	v_mfma_f32_16x16x32_bf16 v[120:123], v[136:139], v[186:189], v[120:123]
	v_mfma_f32_16x16x32_bf16 v[116:119], v[128:131], v[194:197], v[116:119]
	v_mfma_f32_16x16x32_bf16 v[112:115], v[136:139], v[194:197], v[112:115]
	v_mfma_f32_16x16x32_bf16 v[100:103], v[128:131], v[202:205], v[100:103]
	v_mfma_f32_16x16x32_bf16 v[92:95], v[136:139], v[202:205], v[92:95]
	v_mfma_f32_16x16x32_bf16 v[84:87], v[128:131], v[210:213], v[84:87]
	v_mfma_f32_16x16x32_bf16 v[76:79], v[136:139], v[210:213], v[76:79]
	v_mfma_f32_16x16x32_bf16 v[124:127], v[132:135], v[190:193], v[124:127]
	v_mfma_f32_16x16x32_bf16 v[120:123], v[140:143], v[190:193], v[120:123]
	v_mfma_f32_16x16x32_bf16 v[116:119], v[132:135], v[198:201], v[116:119]
	v_mfma_f32_16x16x32_bf16 v[112:115], v[140:143], v[198:201], v[112:115]
	v_mfma_f32_16x16x32_bf16 v[100:103], v[132:135], v[206:209], v[100:103]
	v_mfma_f32_16x16x32_bf16 v[92:95], v[140:143], v[206:209], v[92:95]
	v_mfma_f32_16x16x32_bf16 v[84:87], v[132:135], v[214:217], v[84:87]
	v_mfma_f32_16x16x32_bf16 v[76:79], v[140:143], v[214:217], v[76:79]
	s_setprio 0
	s_setprio 1
	v_mfma_f32_16x16x32_bf16 v[108:111], v[168:171], v[186:189], v[108:111]
	v_mfma_f32_16x16x32_bf16 v[104:107], v[178:181], v[186:189], v[104:107]
	v_mfma_f32_16x16x32_bf16 v[96:99], v[168:171], v[194:197], v[96:99]
	v_mfma_f32_16x16x32_bf16 v[88:91], v[178:181], v[194:197], v[88:91]
	v_mfma_f32_16x16x32_bf16 v[80:83], v[168:171], v[202:205], v[80:83]
	v_mfma_f32_16x16x32_bf16 v[72:75], v[178:181], v[202:205], v[72:75]
	v_mfma_f32_16x16x32_bf16 v[68:71], v[168:171], v[210:213], v[68:71]
	v_mfma_f32_16x16x32_bf16 v[64:67], v[178:181], v[210:213], v[64:67]
	v_mfma_f32_16x16x32_bf16 v[108:111], v[172:175], v[190:193], v[108:111]
	v_mfma_f32_16x16x32_bf16 v[104:107], v[182:185], v[190:193], v[104:107]
	v_mfma_f32_16x16x32_bf16 v[96:99], v[172:175], v[198:201], v[96:99]
	v_mfma_f32_16x16x32_bf16 v[88:91], v[182:185], v[198:201], v[88:91]
	v_mfma_f32_16x16x32_bf16 v[80:83], v[172:175], v[206:209], v[80:83]
	v_mfma_f32_16x16x32_bf16 v[72:75], v[182:185], v[206:209], v[72:75]
	v_mfma_f32_16x16x32_bf16 v[68:71], v[172:175], v[214:217], v[68:71]
	v_mfma_f32_16x16x32_bf16 v[64:67], v[182:185], v[214:217], v[64:67]
	s_setprio 0
	s_barrier
	s_add_i32 s53, s43, s26
	v_lshl_add_u64 v[218:219], s[2:3], 0, v[146:147]
	s_mov_b32 m0, s53
	ds_read_b128 v[186:189], v164 offset:16384
	ds_read_b128 v[190:193], v164 offset:17408
	ds_read_b128 v[194:197], v164 offset:18432
	ds_read_b128 v[198:201], v164 offset:19456
	ds_read_b128 v[202:205], v164 offset:20480
	ds_read_b128 v[206:209], v164 offset:21504
	ds_read_b128 v[210:213], v164 offset:22528
	ds_read_b128 v[214:217], v164 offset:23552
	global_load_lds_dwordx4 v[218:219], off
	s_add_i32 m0, s53, 0x2000
	s_add_u32 s54, s2, 0x40000
	v_lshl_add_u64 v[220:221], s[2:3], 0, v[150:151]
	s_addc_u32 s55, s3, 0
	s_add_i32 s53, s46, s26
	global_load_lds_dwordx4 v[220:221], off
	v_lshl_add_u64 v[222:223], s[54:55], 0, v[146:147]
	s_mov_b32 m0, s53
	v_lshl_add_u64 v[224:225], s[18:19], 0, v[148:149]
	global_load_lds_dwordx4 v[222:223], off
	v_lshl_add_u64 v[222:223], s[54:55], 0, v[150:151]
	s_add_i32 m0, s53, 0x2000
	s_nop 0
	global_load_lds_dwordx4 v[222:223], off
	v_lshl_add_u64 v[222:223], s[18:19], 0, v[144:145]
	s_mov_b32 m0, s21
	s_nop 0
	global_load_lds_dwordx4 v[222:223], off
	s_mov_b32 m0, s28
	s_nop 0
	global_load_lds_dwordx4 v[224:225], off
	s_waitcnt vmcnt(8)
	s_waitcnt lgkmcnt(0)
	s_barrier
; #define PG8_STAGE(bufoff, gbase, voff) do { _Pragma("unroll") for (int _i = 0; _i < 2; ++_i) \
;         __builtin_amdgcn_global_load_lds((const unsigned*)((const char*)(gbase) + (voff)[_i]), (PG8_LAS unsigned*)(lds + (bufoff) + ldsw + _i * 8192), 16, 0, 0); } while (0)
; #define PG8_LDA(dst, b, h) do { _Pragma("unroll") for (int m = 0; m < 4; ++m) _Pragma("unroll") for (int k = 0; k < 2; ++k) dst[m][k] = *(const PG8_LAS bf16x8*)(lds + PG8_SA(b, h) + aoff + m * 2048 + k * 1024); } while (0)
; #define PG8_LDB(dst, b, h) do { _Pragma("unroll") for (int n = 0; n < 2; ++n) _Pragma("unroll") for (int k = 0; k < 2; ++k) dst[n][k] = *(const PG8_LAS bf16x8*)(lds + PG8_SB(b, h) + boff + n * 2048 + k * 1024); } while (0)
; #define PG8_MMA(ai, bj, At, Bt) do { __builtin_amdgcn_s_setprio(1); _Pragma("unroll") for (int m = 0; m < 4; ++m) _Pragma("unroll") for (int n = 0; n < 2; ++n) _Pragma("unroll") for (int k = 0; k < 2; ++k) \
;         acc[ai][bj][m][n] = __builtin_amdgcn_mfma_f32_16x16x32_bf16(Bt[n][k], At[m][k], acc[ai][bj][m][n], 0, 0, 0); __builtin_amdgcn_s_setprio(0); } while (0)
; #define PG8_WAIT_V(n) asm volatile("s_waitcnt vmcnt(" #n ")" ::: "memory")
; #define PG8_WAIT_L(n) asm volatile("s_waitcnt lgkmcnt(" #n ")" ::: "memory")
; #define PG8_BAR __builtin_amdgcn_s_barrier()
; #define PG8_SCHED __builtin_amdgcn_sched_barrier(0)
; template <class Epi, class Sched, bool ALIGN_EPI = false, bool SP2 = false>
; __device__ __forceinline__ void gemm_phase(PG8_LAS unsigned char* lds, const Gemm g, const Sched& S, const Epi& E) {
;     ...
;             PG8_WAIT_V(8); PG8_WAIT_L(0); PG8_BAR; PG8_MMA(1, 0, At, B0); PG8_MMA(1, 1, At, B1); PG8_BAR; PG8_SCHED;
;             PG8_LDB(B0, 1, 0); PG8_LDB(B1, 1, 1); PG8_SCHED; PG8_LDA(At, 1, 0); PG8_STAGE(PG8_SA(0, 1), a2 + hstep, voffA);
;             PG8_WAIT_V(8); PG8_WAIT_L(0); PG8_BAR; PG8_MMA(0, 0, At, B0); PG8_MMA(0, 1, At, B1); PG8_BAR; PG8_SCHED;
	s_setprio 1
	s_waitcnt lgkmcnt(0)
	v_mfma_f32_16x16x32_bf16 v[60:63], v[128:131], v[186:189], v[60:63]
	v_mfma_f32_16x16x32_bf16 v[56:59], v[136:139], v[186:189], v[56:59]
	v_mfma_f32_16x16x32_bf16 v[48:51], v[128:131], v[194:197], v[48:51]
	v_mfma_f32_16x16x32_bf16 v[40:43], v[136:139], v[194:197], v[40:43]
	v_mfma_f32_16x16x32_bf16 v[36:39], v[128:131], v[202:205], v[36:39]
	v_mfma_f32_16x16x32_bf16 v[28:31], v[136:139], v[202:205], v[28:31]
	v_mfma_f32_16x16x32_bf16 v[20:23], v[128:131], v[210:213], v[20:23]
	v_mfma_f32_16x16x32_bf16 v[12:15], v[136:139], v[210:213], v[12:15]
	v_mfma_f32_16x16x32_bf16 v[60:63], v[132:135], v[190:193], v[60:63]
	v_mfma_f32_16x16x32_bf16 v[56:59], v[140:143], v[190:193], v[56:59]
	v_mfma_f32_16x16x32_bf16 v[48:51], v[132:135], v[198:201], v[48:51]
	v_mfma_f32_16x16x32_bf16 v[40:43], v[140:143], v[198:201], v[40:43]
	v_mfma_f32_16x16x32_bf16 v[36:39], v[132:135], v[206:209], v[36:39]
	v_mfma_f32_16x16x32_bf16 v[28:31], v[140:143], v[206:209], v[28:31]
	v_mfma_f32_16x16x32_bf16 v[20:23], v[132:135], v[214:217], v[20:23]
	v_mfma_f32_16x16x32_bf16 v[12:15], v[140:143], v[214:217], v[12:15]
	s_setprio 0
	s_setprio 1
	v_mfma_f32_16x16x32_bf16 v[52:55], v[168:171], v[186:189], v[52:55]
	v_mfma_f32_16x16x32_bf16 v[44:47], v[178:181], v[186:189], v[44:47]
	v_mfma_f32_16x16x32_bf16 v[32:35], v[168:171], v[194:197], v[32:35]
	v_mfma_f32_16x16x32_bf16 v[24:27], v[178:181], v[194:197], v[24:27]
	v_mfma_f32_16x16x32_bf16 v[16:19], v[168:171], v[202:205], v[16:19]
	v_mfma_f32_16x16x32_bf16 v[8:11], v[178:181], v[202:205], v[8:11]
	v_mfma_f32_16x16x32_bf16 v[4:7], v[168:171], v[210:213], v[4:7]
	v_mfma_f32_16x16x32_bf16 v[0:3], v[178:181], v[210:213], v[0:3]
	v_mfma_f32_16x16x32_bf16 v[52:55], v[172:175], v[190:193], v[52:55]
	v_mfma_f32_16x16x32_bf16 v[44:47], v[182:185], v[190:193], v[44:47]
	v_mfma_f32_16x16x32_bf16 v[32:35], v[172:175], v[198:201], v[32:35]
	v_mfma_f32_16x16x32_bf16 v[24:27], v[182:185], v[198:201], v[24:27]
	v_mfma_f32_16x16x32_bf16 v[16:19], v[172:175], v[206:209], v[16:19]
	v_mfma_f32_16x16x32_bf16 v[8:11], v[182:185], v[206:209], v[8:11]
	v_mfma_f32_16x16x32_bf16 v[4:7], v[172:175], v[214:217], v[4:7]
	v_mfma_f32_16x16x32_bf16 v[0:3], v[182:185], v[214:217], v[0:3]
	s_setprio 0
	s_barrier
	s_add_i32 s53, 0, 0x18000
	s_add_i32 s54, 0, 0x1c000
	v_add_u32_e32 v140, s53, v160
	v_add_u32_e32 v167, s54, v160
	ds_read_b128 v[128:131], v140
	ds_read_b128 v[132:135], v140 offset:1024
	ds_read_b128 v[136:139], v140 offset:2048
	ds_read_b128 v[140:143], v140 offset:3072
	ds_read_b128 v[168:171], v167
	ds_read_b128 v[172:175], v167 offset:1024
	ds_read_b128 v[178:181], v167 offset:2048
	ds_read_b128 v[182:185], v167 offset:3072
	s_add_u32 s18, s18, 0x40000
	s_addc_u32 s19, s19, 0
	s_mov_b32 m0, s29
	v_lshl_add_u64 v[226:227], s[18:19], 0, v[144:145]
	ds_read_b128 v[186:189], v164 offset:32768
	ds_read_b128 v[190:193], v164 offset:33792
	ds_read_b128 v[194:197], v164 offset:34816
	ds_read_b128 v[198:201], v164 offset:35840
	ds_read_b128 v[202:205], v164 offset:36864
	ds_read_b128 v[206:209], v164 offset:37888
	ds_read_b128 v[210:213], v164 offset:38912
	ds_read_b128 v[214:217], v164 offset:39936
	global_load_lds_dwordx4 v[226:227], off
	v_lshl_add_u64 v[226:227], s[18:19], 0, v[148:149]
	s_mov_b32 m0, s30
	s_nop 0
	global_load_lds_dwordx4 v[226:227], off
	s_waitcnt vmcnt(8)
	s_waitcnt lgkmcnt(0)
	s_barrier
	s_setprio 1
	s_waitcnt lgkmcnt(0)
	v_mfma_f32_16x16x32_bf16 v[124:127], v[128:131], v[186:189], v[124:127]
	v_mfma_f32_16x16x32_bf16 v[120:123], v[136:139], v[186:189], v[120:123]
	v_mfma_f32_16x16x32_bf16 v[116:119], v[128:131], v[194:197], v[116:119]
	v_mfma_f32_16x16x32_bf16 v[112:115], v[136:139], v[194:197], v[112:115]
	v_mfma_f32_16x16x32_bf16 v[100:103], v[128:131], v[202:205], v[100:103]
	v_mfma_f32_16x16x32_bf16 v[92:95], v[136:139], v[202:205], v[92:95]
	v_mfma_f32_16x16x32_bf16 v[84:87], v[128:131], v[210:213], v[84:87]
	v_mfma_f32_16x16x32_bf16 v[76:79], v[136:139], v[210:213], v[76:79]
	v_mfma_f32_16x16x32_bf16 v[124:127], v[132:135], v[190:193], v[124:127]
	v_mfma_f32_16x16x32_bf16 v[120:123], v[140:143], v[190:193], v[120:123]
	v_mfma_f32_16x16x32_bf16 v[116:119], v[132:135], v[198:201], v[116:119]
	v_mfma_f32_16x16x32_bf16 v[112:115], v[140:143], v[198:201], v[112:115]
	v_mfma_f32_16x16x32_bf16 v[100:103], v[132:135], v[206:209], v[100:103]
	v_mfma_f32_16x16x32_bf16 v[92:95], v[140:143], v[206:209], v[92:95]
	v_mfma_f32_16x16x32_bf16 v[84:87], v[132:135], v[214:217], v[84:87]
	v_mfma_f32_16x16x32_bf16 v[76:79], v[140:143], v[214:217], v[76:79]
	s_setprio 0
	s_setprio 1
	v_mfma_f32_16x16x32_bf16 v[108:111], v[168:171], v[186:189], v[108:111]
	v_mfma_f32_16x16x32_bf16 v[104:107], v[178:181], v[186:189], v[104:107]
	v_mfma_f32_16x16x32_bf16 v[96:99], v[168:171], v[194:197], v[96:99]
	v_mfma_f32_16x16x32_bf16 v[88:91], v[178:181], v[194:197], v[88:91]
	v_mfma_f32_16x16x32_bf16 v[80:83], v[168:171], v[202:205], v[80:83]
	v_mfma_f32_16x16x32_bf16 v[72:75], v[178:181], v[202:205], v[72:75]
	v_mfma_f32_16x16x32_bf16 v[68:71], v[168:171], v[210:213], v[68:71]
	v_mfma_f32_16x16x32_bf16 v[64:67], v[178:181], v[210:213], v[64:67]
	v_mfma_f32_16x16x32_bf16 v[108:111], v[172:175], v[190:193], v[108:111]
	v_mfma_f32_16x16x32_bf16 v[104:107], v[182:185], v[190:193], v[104:107]
	v_mfma_f32_16x16x32_bf16 v[96:99], v[172:175], v[198:201], v[96:99]
	v_mfma_f32_16x16x32_bf16 v[88:91], v[182:185], v[198:201], v[88:91]
	v_mfma_f32_16x16x32_bf16 v[80:83], v[172:175], v[206:209], v[80:83]
	v_mfma_f32_16x16x32_bf16 v[72:75], v[182:185], v[206:209], v[72:75]
	v_mfma_f32_16x16x32_bf16 v[68:71], v[172:175], v[214:217], v[68:71]
	v_mfma_f32_16x16x32_bf16 v[64:67], v[182:185], v[214:217], v[64:67]
	s_setprio 0
	s_barrier
; #define PG8_STAGE(bufoff, gbase, voff) do { _Pragma("unroll") for (int _i = 0; _i < 2; ++_i) \
;         __builtin_amdgcn_global_load_lds((const unsigned*)((const char*)(gbase) + (voff)[_i]), (PG8_LAS unsigned*)(lds + (bufoff) + ldsw + _i * 8192), 16, 0, 0); } while (0)
; #define PG8_LDA(dst, b, h) do { _Pragma("unroll") for (int m = 0; m < 4; ++m) _Pragma("unroll") for (int k = 0; k < 2; ++k) dst[m][k] = *(const PG8_LAS bf16x8*)(lds + PG8_SA(b, h) + aoff + m * 2048 + k * 1024); } while (0)
; #define PG8_MMA(ai, bj, At, Bt) do { __builtin_amdgcn_s_setprio(1); _Pragma("unroll") for (int m = 0; m < 4; ++m) _Pragma("unroll") for (int n = 0; n < 2; ++n) _Pragma("unroll") for (int k = 0; k < 2; ++k) \
;         acc[ai][bj][m][n] = __builtin_amdgcn_mfma_f32_16x16x32_bf16(Bt[n][k], At[m][k], acc[ai][bj][m][n], 0, 0, 0); __builtin_amdgcn_s_setprio(0); } while (0)
; #define PG8_WAIT_V(n) asm volatile("s_waitcnt vmcnt(" #n ")" ::: "memory")
; #define PG8_WAIT_L(n) asm volatile("s_waitcnt lgkmcnt(" #n ")" ::: "memory")
; #define PG8_BAR __builtin_amdgcn_s_barrier()
; #define PG8_SCHED __builtin_amdgcn_sched_barrier(0)
; template <class Epi, class Sched, bool ALIGN_EPI = false, bool SP2 = false>
; __device__ __forceinline__ void gemm_phase(PG8_LAS unsigned char* lds, const Gemm g, const Sched& S, const Epi& E) {
;     ...
;         for (int t = 0; t < nt; t += 2) {
;     ...
;             PG8_LDA(At, 1, 1); PG8_STAGE(PG8_SB(1, 0), b3, voffB); PG8_STAGE(PG8_SB(1, 1), b3 + hstep, voffB); PG8_STAGE(PG8_SA(1, 0), a3, voffA);
;             PG8_WAIT_V(8); PG8_WAIT_L(0); PG8_BAR; PG8_MMA(1, 0, At, B0); PG8_MMA(1, 1, At, B1); PG8_BAR; PG8_SCHED;
	s_add_i32 s18, s53, s26
	v_lshl_add_u64 v[218:219], v[218:219], 0, s[6:7]
	s_mov_b32 m0, s18
	ds_read_b128 v[186:189], v164 offset:49152
	ds_read_b128 v[190:193], v164 offset:50176
	ds_read_b128 v[194:197], v164 offset:51200
	ds_read_b128 v[198:201], v164 offset:52224
	ds_read_b128 v[202:205], v164 offset:53248
	ds_read_b128 v[206:209], v164 offset:54272
	ds_read_b128 v[210:213], v164 offset:55296
	ds_read_b128 v[214:217], v164 offset:56320
	global_load_lds_dwordx4 v[218:219], off
	s_add_i32 m0, s18, 0x2000
	s_add_u32 s2, s2, 0x40080
	v_lshl_add_u64 v[218:219], v[220:221], 0, s[6:7]
	s_addc_u32 s3, s3, 0
	s_add_i32 s18, s54, s26
	global_load_lds_dwordx4 v[218:219], off
	v_lshl_add_u64 v[218:219], s[2:3], 0, v[146:147]
	s_mov_b32 m0, s18
	s_nop 0
	global_load_lds_dwordx4 v[218:219], off
	v_lshl_add_u64 v[218:219], s[2:3], 0, v[150:151]
	s_add_i32 m0, s18, 0x2000
	s_nop 0
	global_load_lds_dwordx4 v[218:219], off
	v_lshl_add_u64 v[218:219], v[222:223], 0, s[6:7]
	s_mov_b32 m0, s34
	s_nop 0
	global_load_lds_dwordx4 v[218:219], off
	v_lshl_add_u64 v[218:219], v[224:225], 0, s[6:7]
	s_mov_b32 m0, s35
	s_nop 0
	global_load_lds_dwordx4 v[218:219], off
	s_waitcnt vmcnt(8)
	s_waitcnt lgkmcnt(0)
	s_barrier
	s_setprio 1
	s_waitcnt lgkmcnt(0)
	v_mfma_f32_16x16x32_bf16 v[60:63], v[128:131], v[186:189], v[60:63]
	v_mfma_f32_16x16x32_bf16 v[56:59], v[136:139], v[186:189], v[56:59]
	v_mfma_f32_16x16x32_bf16 v[48:51], v[128:131], v[194:197], v[48:51]
	v_mfma_f32_16x16x32_bf16 v[40:43], v[136:139], v[194:197], v[40:43]
	v_mfma_f32_16x16x32_bf16 v[36:39], v[128:131], v[202:205], v[36:39]
	v_mfma_f32_16x16x32_bf16 v[28:31], v[136:139], v[202:205], v[28:31]
	v_mfma_f32_16x16x32_bf16 v[20:23], v[128:131], v[210:213], v[20:23]
	v_mfma_f32_16x16x32_bf16 v[12:15], v[136:139], v[210:213], v[12:15]
	v_mfma_f32_16x16x32_bf16 v[60:63], v[132:135], v[190:193], v[60:63]
	v_mfma_f32_16x16x32_bf16 v[56:59], v[140:143], v[190:193], v[56:59]
	v_mfma_f32_16x16x32_bf16 v[48:51], v[132:135], v[198:201], v[48:51]
	v_mfma_f32_16x16x32_bf16 v[40:43], v[140:143], v[198:201], v[40:43]
	v_mfma_f32_16x16x32_bf16 v[36:39], v[132:135], v[206:209], v[36:39]
	v_mfma_f32_16x16x32_bf16 v[28:31], v[140:143], v[206:209], v[28:31]
	v_mfma_f32_16x16x32_bf16 v[20:23], v[132:135], v[214:217], v[20:23]
	v_mfma_f32_16x16x32_bf16 v[12:15], v[140:143], v[214:217], v[12:15]
	s_setprio 0
	s_setprio 1
	v_mfma_f32_16x16x32_bf16 v[52:55], v[168:171], v[186:189], v[52:55]
	v_mfma_f32_16x16x32_bf16 v[44:47], v[178:181], v[186:189], v[44:47]
	v_mfma_f32_16x16x32_bf16 v[32:35], v[168:171], v[194:197], v[32:35]
	v_mfma_f32_16x16x32_bf16 v[24:27], v[178:181], v[194:197], v[24:27]
	v_mfma_f32_16x16x32_bf16 v[16:19], v[168:171], v[202:205], v[16:19]
	v_mfma_f32_16x16x32_bf16 v[8:11], v[178:181], v[202:205], v[8:11]
	v_mfma_f32_16x16x32_bf16 v[4:7], v[168:171], v[210:213], v[4:7]
	v_mfma_f32_16x16x32_bf16 v[0:3], v[178:181], v[210:213], v[0:3]
	v_mfma_f32_16x16x32_bf16 v[52:55], v[172:175], v[190:193], v[52:55]
	v_mfma_f32_16x16x32_bf16 v[44:47], v[182:185], v[190:193], v[44:47]
	v_mfma_f32_16x16x32_bf16 v[32:35], v[172:175], v[198:201], v[32:35]
	v_mfma_f32_16x16x32_bf16 v[24:27], v[182:185], v[198:201], v[24:27]
	v_mfma_f32_16x16x32_bf16 v[16:19], v[172:175], v[206:209], v[16:19]
	v_mfma_f32_16x16x32_bf16 v[8:11], v[182:185], v[206:209], v[8:11]
	v_mfma_f32_16x16x32_bf16 v[4:7], v[172:175], v[214:217], v[4:7]
	v_mfma_f32_16x16x32_bf16 v[0:3], v[182:185], v[214:217], v[0:3]
	s_setprio 0
	s_add_i32 s52, s52, 2
	s_add_u32 s22, s22, 0x100
	s_addc_u32 s23, s23, 0
	s_add_u32 s50, s50, 0x100
	s_addc_u32 s51, s51, 0
	s_cmp_gt_u32 s52, 13
	s_barrier
	s_cbranch_scc0 .LBB0_241
	s_and_b64 vcc, exec, s[8:9]
	s_cbranch_vccz .LBB0_244
	s_barrier

; #define PG8_STAGE(bufoff, gbase, voff) do { _Pragma("unroll") for (int _i = 0; _i < 2; ++_i) \
;         __builtin_amdgcn_global_load_lds((const unsigned*)((const char*)(gbase) + (voff)[_i]), (PG8_LAS unsigned*)(lds + (bufoff) + ldsw + _i * 8192), 16, 0, 0); } while (0)
; #define PG8_LDA(dst, b, h) do { _Pragma("unroll") for (int m = 0; m < 4; ++m) _Pragma("unroll") for (int k = 0; k < 2; ++k) dst[m][k] = *(const PG8_LAS bf16x8*)(lds + PG8_SA(b, h) + aoff + m * 2048 + k * 1024); } while (0)
; #define PG8_LDB(dst, b, h) do { _Pragma("unroll") for (int n = 0; n < 2; ++n) _Pragma("unroll") for (int k = 0; k < 2; ++k) dst[n][k] = *(const PG8_LAS bf16x8*)(lds + PG8_SB(b, h) + boff + n * 2048 + k * 1024); } while (0)
; #define PG8_MMA(ai, bj, At, Bt) do { __builtin_amdgcn_s_setprio(1); _Pragma("unroll") for (int m = 0; m < 4; ++m) _Pragma("unroll") for (int n = 0; n < 2; ++n) _Pragma("unroll") for (int k = 0; k < 2; ++k) \
;         acc[ai][bj][m][n] = __builtin_amdgcn_mfma_f32_16x16x32_bf16(Bt[n][k], At[m][k], acc[ai][bj][m][n], 0, 0, 0); __builtin_amdgcn_s_setprio(0); } while (0)
; #define PG8_WAIT_V(n) asm volatile("s_waitcnt vmcnt(" #n ")" ::: "memory")
; #define PG8_WAIT_L(n) asm volatile("s_waitcnt lgkmcnt(" #n ")" ::: "memory")
; #define PG8_BAR __builtin_amdgcn_s_barrier()
; #define PG8_SCHED __builtin_amdgcn_sched_barrier(0)
; template <class Epi, class Sched, bool ALIGN_EPI = false, bool SP2 = false>
; __device__ __forceinline__ void gemm_phase(PG8_LAS unsigned char* lds, const Gemm g, const Sched& S, const Epi& E) {
;     ...
;             PG8_LDB(B0, 0, 0); PG8_LDB(B1, 0, 1); PG8_SCHED; PG8_LDA(At, 0, 0); PG8_STAGE(PG8_SA(1, 1), a1 + hstep, voffA);
;             PG8_WAIT_V(8); PG8_WAIT_L(0); PG8_BAR; PG8_MMA(0, 0, At, B0); PG8_MMA(0, 1, At, B1); PG8_BAR; PG8_SCHED;
;             PG8_LDA(At, 0, 1); PG8_STAGE(PG8_SB(0, 0), b2, voffB); PG8_STAGE(PG8_SB(0, 1), b2 + hstep, voffB); PG8_STAGE(PG8_SA(0, 0), a2, voffA);
;             PG8_WAIT_V(8); PG8_WAIT_L(0); PG8_BAR; PG8_MMA(1, 0, At, B0); PG8_MMA(1, 1, At, B1); PG8_BAR; PG8_SCHED;
.LBB0_427:
	ds_read_b128 v[144:147], v151
	ds_read_b128 v[156:159], v151 offset:1024
	ds_read_b128 v[160:163], v151 offset:2048
	ds_read_b128 v[164:167], v151 offset:3072
	ds_read_b128 v[168:171], v152
	ds_read_b128 v[172:175], v152 offset:1024
	ds_read_b128 v[178:181], v152 offset:2048
	ds_read_b128 v[182:185], v152 offset:3072
	s_add_u32 s2, s28, 0xfffc0080
	s_addc_u32 s3, s29, -1
	s_cmp_eq_u32 s60, 12
	s_cselect_b32 s19, s17, s3
	s_cselect_b32 s18, s27, s2
	s_cselect_b32 s3, s15, s55
	s_cselect_b32 s2, s53, s54
	v_lshl_add_u64 v[218:219], s[28:29], 0, v[136:137]
	s_add_i32 m0, s34, 0xc000
	ds_read_b128 v[186:189], v153
	ds_read_b128 v[190:193], v153 offset:1024
	ds_read_b128 v[194:197], v153 offset:2048
	ds_read_b128 v[198:201], v153 offset:3072
	ds_read_b128 v[202:205], v153 offset:4096
	ds_read_b128 v[206:209], v153 offset:5120
	ds_read_b128 v[210:213], v153 offset:6144
	ds_read_b128 v[214:217], v153 offset:7168
	global_load_lds_dwordx4 v[218:219], off
	v_lshl_add_u64 v[218:219], s[28:29], 0, v[138:139]
	s_add_i32 m0, s34, 0xe000
	s_nop 0
	global_load_lds_dwordx4 v[218:219], off
	s_waitcnt vmcnt(8)
	s_waitcnt lgkmcnt(0)
	s_barrier
	s_setprio 1
	s_waitcnt lgkmcnt(0)
	v_mfma_f32_16x16x32_bf16 v[124:127], v[144:147], v[186:189], v[124:127]
	v_mfma_f32_16x16x32_bf16 v[120:123], v[160:163], v[186:189], v[120:123]
	v_mfma_f32_16x16x32_bf16 v[108:111], v[144:147], v[194:197], v[108:111]
	v_mfma_f32_16x16x32_bf16 v[104:107], v[160:163], v[194:197], v[104:107]
	v_mfma_f32_16x16x32_bf16 v[92:95], v[144:147], v[202:205], v[92:95]
	v_mfma_f32_16x16x32_bf16 v[88:91], v[160:163], v[202:205], v[88:91]
	v_mfma_f32_16x16x32_bf16 v[76:79], v[144:147], v[210:213], v[76:79]
	v_mfma_f32_16x16x32_bf16 v[72:75], v[160:163], v[210:213], v[72:75]
	v_mfma_f32_16x16x32_bf16 v[124:127], v[156:159], v[190:193], v[124:127]
	v_mfma_f32_16x16x32_bf16 v[120:123], v[164:167], v[190:193], v[120:123]
	v_mfma_f32_16x16x32_bf16 v[108:111], v[156:159], v[198:201], v[108:111]
	v_mfma_f32_16x16x32_bf16 v[104:107], v[164:167], v[198:201], v[104:107]
	v_mfma_f32_16x16x32_bf16 v[92:95], v[156:159], v[206:209], v[92:95]
	v_mfma_f32_16x16x32_bf16 v[88:91], v[164:167], v[206:209], v[88:91]
	v_mfma_f32_16x16x32_bf16 v[76:79], v[156:159], v[214:217], v[76:79]
	v_mfma_f32_16x16x32_bf16 v[72:75], v[164:167], v[214:217], v[72:75]
	s_setprio 0
	s_setprio 1
	v_mfma_f32_16x16x32_bf16 v[116:119], v[168:171], v[186:189], v[116:119]
	v_mfma_f32_16x16x32_bf16 v[112:115], v[178:181], v[186:189], v[112:115]
	v_mfma_f32_16x16x32_bf16 v[100:103], v[168:171], v[194:197], v[100:103]
	v_mfma_f32_16x16x32_bf16 v[96:99], v[178:181], v[194:197], v[96:99]
	v_mfma_f32_16x16x32_bf16 v[84:87], v[168:171], v[202:205], v[84:87]
	v_mfma_f32_16x16x32_bf16 v[80:83], v[178:181], v[202:205], v[80:83]
	v_mfma_f32_16x16x32_bf16 v[68:71], v[168:171], v[210:213], v[68:71]
	v_mfma_f32_16x16x32_bf16 v[64:67], v[178:181], v[210:213], v[64:67]
	v_mfma_f32_16x16x32_bf16 v[116:119], v[172:175], v[190:193], v[116:119]
	v_mfma_f32_16x16x32_bf16 v[112:115], v[182:185], v[190:193], v[112:115]
	v_mfma_f32_16x16x32_bf16 v[100:103], v[172:175], v[198:201], v[100:103]
	v_mfma_f32_16x16x32_bf16 v[96:99], v[182:185], v[198:201], v[96:99]
	v_mfma_f32_16x16x32_bf16 v[84:87], v[172:175], v[206:209], v[84:87]
	v_mfma_f32_16x16x32_bf16 v[80:83], v[182:185], v[206:209], v[80:83]
	v_mfma_f32_16x16x32_bf16 v[68:71], v[172:175], v[214:217], v[68:71]
	v_mfma_f32_16x16x32_bf16 v[64:67], v[182:185], v[214:217], v[64:67]
	s_setprio 0
	s_barrier
	s_add_i32 s61, s50, s33
	v_lshl_add_u64 v[218:219], s[2:3], 0, v[130:131]
	s_mov_b32 m0, s61
	ds_read_b128 v[186:189], v153 offset:16384
	ds_read_b128 v[190:193], v153 offset:17408
	ds_read_b128 v[194:197], v153 offset:18432
	ds_read_b128 v[198:201], v153 offset:19456
	ds_read_b128 v[202:205], v153 offset:20480
	ds_read_b128 v[206:209], v153 offset:21504
	ds_read_b128 v[210:213], v153 offset:22528
	ds_read_b128 v[214:217], v153 offset:23552
	global_load_lds_dwordx4 v[218:219], off
	s_add_i32 m0, s61, 0x2000
	s_add_u32 s62, s2, 0x40000
	v_lshl_add_u64 v[220:221], s[2:3], 0, v[134:135]
	s_addc_u32 s63, s3, 0
	s_add_i32 s61, s51, s33
	global_load_lds_dwordx4 v[220:221], off
	v_lshl_add_u64 v[222:223], s[62:63], 0, v[130:131]
	s_mov_b32 m0, s61
	v_lshl_add_u64 v[224:225], s[18:19], 0, v[132:133]
	global_load_lds_dwordx4 v[222:223], off
	v_lshl_add_u64 v[222:223], s[62:63], 0, v[134:135]
	s_add_i32 m0, s61, 0x2000
	s_nop 0
	global_load_lds_dwordx4 v[222:223], off
	v_lshl_add_u64 v[222:223], s[18:19], 0, v[128:129]
	s_mov_b32 m0, s34
	s_nop 0
	global_load_lds_dwordx4 v[222:223], off
	s_mov_b32 m0, s35
	s_nop 0
	global_load_lds_dwordx4 v[224:225], off
	s_waitcnt vmcnt(8)
	s_waitcnt lgkmcnt(0)
	s_barrier
; #define PG8_STAGE(bufoff, gbase, voff) do { _Pragma("unroll") for (int _i = 0; _i < 2; ++_i) \
;         __builtin_amdgcn_global_load_lds((const unsigned*)((const char*)(gbase) + (voff)[_i]), (PG8_LAS unsigned*)(lds + (bufoff) + ldsw + _i * 8192), 16, 0, 0); } while (0)
; #define PG8_LDA(dst, b, h) do { _Pragma("unroll") for (int m = 0; m < 4; ++m) _Pragma("unroll") for (int k = 0; k < 2; ++k) dst[m][k] = *(const PG8_LAS bf16x8*)(lds + PG8_SA(b, h) + aoff + m * 2048 + k * 1024); } while (0)
; #define PG8_LDB(dst, b, h) do { _Pragma("unroll") for (int n = 0; n < 2; ++n) _Pragma("unroll") for (int k = 0; k < 2; ++k) dst[n][k] = *(const PG8_LAS bf16x8*)(lds + PG8_SB(b, h) + boff + n * 2048 + k * 1024); } while (0)
; #define PG8_MMA(ai, bj, At, Bt) do { __builtin_amdgcn_s_setprio(1); _Pragma("unroll") for (int m = 0; m < 4; ++m) _Pragma("unroll") for (int n = 0; n < 2; ++n) _Pragma("unroll") for (int k = 0; k < 2; ++k) \
;         acc[ai][bj][m][n] = __builtin_amdgcn_mfma_f32_16x16x32_bf16(Bt[n][k], At[m][k], acc[ai][bj][m][n], 0, 0, 0); __builtin_amdgcn_s_setprio(0); } while (0)
; #define PG8_WAIT_V(n) asm volatile("s_waitcnt vmcnt(" #n ")" ::: "memory")
; #define PG8_WAIT_L(n) asm volatile("s_waitcnt lgkmcnt(" #n ")" ::: "memory")
; #define PG8_BAR __builtin_amdgcn_s_barrier()
; #define PG8_SCHED __builtin_amdgcn_sched_barrier(0)
; template <class Epi, class Sched, bool ALIGN_EPI = false, bool SP2 = false>
; __device__ __forceinline__ void gemm_phase(PG8_LAS unsigned char* lds, const Gemm g, const Sched& S, const Epi& E) {
;     ...
;             PG8_WAIT_V(8); PG8_WAIT_L(0); PG8_BAR; PG8_MMA(1, 0, At, B0); PG8_MMA(1, 1, At, B1); PG8_BAR; PG8_SCHED;
;             PG8_LDB(B0, 1, 0); PG8_LDB(B1, 1, 1); PG8_SCHED; PG8_LDA(At, 1, 0); PG8_STAGE(PG8_SA(0, 1), a2 + hstep, voffA);
;             PG8_WAIT_V(8); PG8_WAIT_L(0); PG8_BAR; PG8_MMA(0, 0, At, B0); PG8_MMA(0, 1, At, B1); PG8_BAR; PG8_SCHED;
	s_setprio 1
	s_waitcnt lgkmcnt(0)
	v_mfma_f32_16x16x32_bf16 v[60:63], v[144:147], v[186:189], v[60:63]
	v_mfma_f32_16x16x32_bf16 v[56:59], v[160:163], v[186:189], v[56:59]
	v_mfma_f32_16x16x32_bf16 v[44:47], v[144:147], v[194:197], v[44:47]
	v_mfma_f32_16x16x32_bf16 v[40:43], v[160:163], v[194:197], v[40:43]
	v_mfma_f32_16x16x32_bf16 v[28:31], v[144:147], v[202:205], v[28:31]
	v_mfma_f32_16x16x32_bf16 v[24:27], v[160:163], v[202:205], v[24:27]
	v_mfma_f32_16x16x32_bf16 v[12:15], v[144:147], v[210:213], v[12:15]
	v_mfma_f32_16x16x32_bf16 v[8:11], v[160:163], v[210:213], v[8:11]
	v_mfma_f32_16x16x32_bf16 v[60:63], v[156:159], v[190:193], v[60:63]
	v_mfma_f32_16x16x32_bf16 v[56:59], v[164:167], v[190:193], v[56:59]
	v_mfma_f32_16x16x32_bf16 v[44:47], v[156:159], v[198:201], v[44:47]
	v_mfma_f32_16x16x32_bf16 v[40:43], v[164:167], v[198:201], v[40:43]
	v_mfma_f32_16x16x32_bf16 v[28:31], v[156:159], v[206:209], v[28:31]
	v_mfma_f32_16x16x32_bf16 v[24:27], v[164:167], v[206:209], v[24:27]
	v_mfma_f32_16x16x32_bf16 v[12:15], v[156:159], v[214:217], v[12:15]
	v_mfma_f32_16x16x32_bf16 v[8:11], v[164:167], v[214:217], v[8:11]
	s_setprio 0
	s_setprio 1
	v_mfma_f32_16x16x32_bf16 v[52:55], v[168:171], v[186:189], v[52:55]
	v_mfma_f32_16x16x32_bf16 v[48:51], v[178:181], v[186:189], v[48:51]
	v_mfma_f32_16x16x32_bf16 v[36:39], v[168:171], v[194:197], v[36:39]
	v_mfma_f32_16x16x32_bf16 v[32:35], v[178:181], v[194:197], v[32:35]
	v_mfma_f32_16x16x32_bf16 v[20:23], v[168:171], v[202:205], v[20:23]
	v_mfma_f32_16x16x32_bf16 v[16:19], v[178:181], v[202:205], v[16:19]
	v_mfma_f32_16x16x32_bf16 v[4:7], v[168:171], v[210:213], v[4:7]
	v_mfma_f32_16x16x32_bf16 v[0:3], v[178:181], v[210:213], v[0:3]
	v_mfma_f32_16x16x32_bf16 v[52:55], v[172:175], v[190:193], v[52:55]
	v_mfma_f32_16x16x32_bf16 v[48:51], v[182:185], v[190:193], v[48:51]
	v_mfma_f32_16x16x32_bf16 v[36:39], v[172:175], v[198:201], v[36:39]
	v_mfma_f32_16x16x32_bf16 v[32:35], v[182:185], v[198:201], v[32:35]
	v_mfma_f32_16x16x32_bf16 v[20:23], v[172:175], v[206:209], v[20:23]
	v_mfma_f32_16x16x32_bf16 v[16:19], v[182:185], v[206:209], v[16:19]
	v_mfma_f32_16x16x32_bf16 v[4:7], v[172:175], v[214:217], v[4:7]
	v_mfma_f32_16x16x32_bf16 v[0:3], v[182:185], v[214:217], v[0:3]
	s_setprio 0
	s_barrier
	s_add_i32 s61, 0, 0x18000
	v_add_u32_e32 v155, s61, v149
	s_add_i32 s62, 0, 0x1c000
	ds_read_b128 v[144:147], v155
	ds_read_b128 v[156:159], v155 offset:1024
	ds_read_b128 v[160:163], v155 offset:2048
	ds_read_b128 v[164:167], v155 offset:3072
	v_add_u32_e32 v155, s62, v149
	ds_read_b128 v[168:171], v155
	ds_read_b128 v[172:175], v155 offset:1024
	ds_read_b128 v[178:181], v155 offset:2048
	ds_read_b128 v[182:185], v155 offset:3072
	s_add_u32 s18, s18, 0x40000
	s_addc_u32 s19, s19, 0
	s_mov_b32 m0, s36
	v_lshl_add_u64 v[226:227], s[18:19], 0, v[128:129]
	ds_read_b128 v[186:189], v153 offset:32768
	ds_read_b128 v[190:193], v153 offset:33792
	ds_read_b128 v[194:197], v153 offset:34816
	ds_read_b128 v[198:201], v153 offset:35840
	ds_read_b128 v[202:205], v153 offset:36864
	ds_read_b128 v[206:209], v153 offset:37888
	ds_read_b128 v[210:213], v153 offset:38912
	ds_read_b128 v[214:217], v153 offset:39936
	global_load_lds_dwordx4 v[226:227], off
	v_lshl_add_u64 v[226:227], s[18:19], 0, v[132:133]
	s_mov_b32 m0, s37
	s_nop 0
	global_load_lds_dwordx4 v[226:227], off
	s_waitcnt vmcnt(8)
	s_waitcnt lgkmcnt(0)
	s_barrier
	s_setprio 1
	s_waitcnt lgkmcnt(0)
	v_mfma_f32_16x16x32_bf16 v[124:127], v[144:147], v[186:189], v[124:127]
	v_mfma_f32_16x16x32_bf16 v[120:123], v[160:163], v[186:189], v[120:123]
	v_mfma_f32_16x16x32_bf16 v[108:111], v[144:147], v[194:197], v[108:111]
	v_mfma_f32_16x16x32_bf16 v[104:107], v[160:163], v[194:197], v[104:107]
	v_mfma_f32_16x16x32_bf16 v[92:95], v[144:147], v[202:205], v[92:95]
	v_mfma_f32_16x16x32_bf16 v[88:91], v[160:163], v[202:205], v[88:91]
	v_mfma_f32_16x16x32_bf16 v[76:79], v[144:147], v[210:213], v[76:79]
	v_mfma_f32_16x16x32_bf16 v[72:75], v[160:163], v[210:213], v[72:75]
	v_mfma_f32_16x16x32_bf16 v[124:127], v[156:159], v[190:193], v[124:127]
	v_mfma_f32_16x16x32_bf16 v[120:123], v[164:167], v[190:193], v[120:123]
	v_mfma_f32_16x16x32_bf16 v[108:111], v[156:159], v[198:201], v[108:111]
	v_mfma_f32_16x16x32_bf16 v[104:107], v[164:167], v[198:201], v[104:107]
	v_mfma_f32_16x16x32_bf16 v[92:95], v[156:159], v[206:209], v[92:95]
	v_mfma_f32_16x16x32_bf16 v[88:91], v[164:167], v[206:209], v[88:91]
	v_mfma_f32_16x16x32_bf16 v[76:79], v[156:159], v[214:217], v[76:79]
	v_mfma_f32_16x16x32_bf16 v[72:75], v[164:167], v[214:217], v[72:75]
	s_setprio 0
	s_setprio 1
	v_mfma_f32_16x16x32_bf16 v[116:119], v[168:171], v[186:189], v[116:119]
	v_mfma_f32_16x16x32_bf16 v[112:115], v[178:181], v[186:189], v[112:115]
	v_mfma_f32_16x16x32_bf16 v[100:103], v[168:171], v[194:197], v[100:103]
	v_mfma_f32_16x16x32_bf16 v[96:99], v[178:181], v[194:197], v[96:99]
	v_mfma_f32_16x16x32_bf16 v[84:87], v[168:171], v[202:205], v[84:87]
	v_mfma_f32_16x16x32_bf16 v[80:83], v[178:181], v[202:205], v[80:83]
	v_mfma_f32_16x16x32_bf16 v[68:71], v[168:171], v[210:213], v[68:71]
	v_mfma_f32_16x16x32_bf16 v[64:67], v[178:181], v[210:213], v[64:67]
	v_mfma_f32_16x16x32_bf16 v[116:119], v[172:175], v[190:193], v[116:119]
	v_mfma_f32_16x16x32_bf16 v[112:115], v[182:185], v[190:193], v[112:115]
	v_mfma_f32_16x16x32_bf16 v[100:103], v[172:175], v[198:201], v[100:103]
	v_mfma_f32_16x16x32_bf16 v[96:99], v[182:185], v[198:201], v[96:99]
	v_mfma_f32_16x16x32_bf16 v[84:87], v[172:175], v[206:209], v[84:87]
	v_mfma_f32_16x16x32_bf16 v[80:83], v[182:185], v[206:209], v[80:83]
	v_mfma_f32_16x16x32_bf16 v[68:71], v[172:175], v[214:217], v[68:71]
	v_mfma_f32_16x16x32_bf16 v[64:67], v[182:185], v[214:217], v[64:67]
	s_setprio 0
	s_barrier
; #define PG8_STAGE(bufoff, gbase, voff) do { _Pragma("unroll") for (int _i = 0; _i < 2; ++_i) \
;         __builtin_amdgcn_global_load_lds((const unsigned*)((const char*)(gbase) + (voff)[_i]), (PG8_LAS unsigned*)(lds + (bufoff) + ldsw + _i * 8192), 16, 0, 0); } while (0)
; #define PG8_LDA(dst, b, h) do { _Pragma("unroll") for (int m = 0; m < 4; ++m) _Pragma("unroll") for (int k = 0; k < 2; ++k) dst[m][k] = *(const PG8_LAS bf16x8*)(lds + PG8_SA(b, h) + aoff + m * 2048 + k * 1024); } while (0)
; #define PG8_MMA(ai, bj, At, Bt) do { __builtin_amdgcn_s_setprio(1); _Pragma("unroll") for (int m = 0; m < 4; ++m) _Pragma("unroll") for (int n = 0; n < 2; ++n) _Pragma("unroll") for (int k = 0; k < 2; ++k) \
;         acc[ai][bj][m][n] = __builtin_amdgcn_mfma_f32_16x16x32_bf16(Bt[n][k], At[m][k], acc[ai][bj][m][n], 0, 0, 0); __builtin_amdgcn_s_setprio(0); } while (0)
; #define PG8_WAIT_V(n) asm volatile("s_waitcnt vmcnt(" #n ")" ::: "memory")
; #define PG8_WAIT_L(n) asm volatile("s_waitcnt lgkmcnt(" #n ")" ::: "memory")
; #define PG8_BAR __builtin_amdgcn_s_barrier()
; #define PG8_SCHED __builtin_amdgcn_sched_barrier(0)
; template <class Epi, class Sched, bool ALIGN_EPI = false, bool SP2 = false>
; __device__ __forceinline__ void gemm_phase(PG8_LAS unsigned char* lds, const Gemm g, const Sched& S, const Epi& E) {
;     ...
;         for (int t = 0; t < nt; t += 2) {
;     ...
;             PG8_LDA(At, 1, 1); PG8_STAGE(PG8_SB(1, 0), b3, voffB); PG8_STAGE(PG8_SB(1, 1), b3 + hstep, voffB); PG8_STAGE(PG8_SA(1, 0), a3, voffA);
;             PG8_WAIT_V(8); PG8_WAIT_L(0); PG8_BAR; PG8_MMA(1, 0, At, B0); PG8_MMA(1, 1, At, B1); PG8_BAR; PG8_SCHED;
	s_add_i32 s18, s61, s33
	v_lshl_add_u64 v[218:219], v[218:219], 0, s[10:11]
	s_mov_b32 m0, s18
	ds_read_b128 v[186:189], v153 offset:49152
	ds_read_b128 v[190:193], v153 offset:50176
	ds_read_b128 v[194:197], v153 offset:51200
	ds_read_b128 v[198:201], v153 offset:52224
	ds_read_b128 v[202:205], v153 offset:53248
	ds_read_b128 v[206:209], v153 offset:54272
	ds_read_b128 v[210:213], v153 offset:55296
	ds_read_b128 v[214:217], v153 offset:56320
	global_load_lds_dwordx4 v[218:219], off
	s_add_i32 m0, s18, 0x2000
	s_add_u32 s2, s2, 0x40080
	v_lshl_add_u64 v[218:219], v[220:221], 0, s[10:11]
	s_addc_u32 s3, s3, 0
	s_add_i32 s18, s62, s33
	global_load_lds_dwordx4 v[218:219], off
	v_lshl_add_u64 v[218:219], s[2:3], 0, v[130:131]
	s_mov_b32 m0, s18
	s_nop 0
	global_load_lds_dwordx4 v[218:219], off
	v_lshl_add_u64 v[218:219], s[2:3], 0, v[134:135]
	s_add_i32 m0, s18, 0x2000
	s_nop 0
	global_load_lds_dwordx4 v[218:219], off
	v_lshl_add_u64 v[218:219], v[222:223], 0, s[10:11]
	s_mov_b32 m0, s43
	s_nop 0
	global_load_lds_dwordx4 v[218:219], off
	v_lshl_add_u64 v[218:219], v[224:225], 0, s[10:11]
	s_mov_b32 m0, s46
	s_nop 0
	global_load_lds_dwordx4 v[218:219], off
	s_waitcnt vmcnt(8)
	s_waitcnt lgkmcnt(0)
	s_barrier
	s_setprio 1
	s_waitcnt lgkmcnt(0)
	v_mfma_f32_16x16x32_bf16 v[60:63], v[144:147], v[186:189], v[60:63]
	v_mfma_f32_16x16x32_bf16 v[56:59], v[160:163], v[186:189], v[56:59]
	v_mfma_f32_16x16x32_bf16 v[44:47], v[144:147], v[194:197], v[44:47]
	v_mfma_f32_16x16x32_bf16 v[40:43], v[160:163], v[194:197], v[40:43]
	v_mfma_f32_16x16x32_bf16 v[28:31], v[144:147], v[202:205], v[28:31]
	v_mfma_f32_16x16x32_bf16 v[24:27], v[160:163], v[202:205], v[24:27]
	v_mfma_f32_16x16x32_bf16 v[12:15], v[144:147], v[210:213], v[12:15]
	v_mfma_f32_16x16x32_bf16 v[8:11], v[160:163], v[210:213], v[8:11]
	v_mfma_f32_16x16x32_bf16 v[60:63], v[156:159], v[190:193], v[60:63]
	v_mfma_f32_16x16x32_bf16 v[56:59], v[164:167], v[190:193], v[56:59]
	v_mfma_f32_16x16x32_bf16 v[44:47], v[156:159], v[198:201], v[44:47]
	v_mfma_f32_16x16x32_bf16 v[40:43], v[164:167], v[198:201], v[40:43]
	v_mfma_f32_16x16x32_bf16 v[28:31], v[156:159], v[206:209], v[28:31]
	v_mfma_f32_16x16x32_bf16 v[24:27], v[164:167], v[206:209], v[24:27]
	v_mfma_f32_16x16x32_bf16 v[12:15], v[156:159], v[214:217], v[12:15]
	v_mfma_f32_16x16x32_bf16 v[8:11], v[164:167], v[214:217], v[8:11]
	s_setprio 0
	s_setprio 1
	v_mfma_f32_16x16x32_bf16 v[52:55], v[168:171], v[186:189], v[52:55]
	v_mfma_f32_16x16x32_bf16 v[48:51], v[178:181], v[186:189], v[48:51]
	v_mfma_f32_16x16x32_bf16 v[36:39], v[168:171], v[194:197], v[36:39]
	v_mfma_f32_16x16x32_bf16 v[32:35], v[178:181], v[194:197], v[32:35]
	v_mfma_f32_16x16x32_bf16 v[20:23], v[168:171], v[202:205], v[20:23]
	v_mfma_f32_16x16x32_bf16 v[16:19], v[178:181], v[202:205], v[16:19]
	v_mfma_f32_16x16x32_bf16 v[4:7], v[168:171], v[210:213], v[4:7]
	v_mfma_f32_16x16x32_bf16 v[0:3], v[178:181], v[210:213], v[0:3]
	v_mfma_f32_16x16x32_bf16 v[52:55], v[172:175], v[190:193], v[52:55]
	v_mfma_f32_16x16x32_bf16 v[48:51], v[182:185], v[190:193], v[48:51]
	v_mfma_f32_16x16x32_bf16 v[36:39], v[172:175], v[198:201], v[36:39]
	v_mfma_f32_16x16x32_bf16 v[32:35], v[182:185], v[198:201], v[32:35]
	v_mfma_f32_16x16x32_bf16 v[20:23], v[172:175], v[206:209], v[20:23]
	v_mfma_f32_16x16x32_bf16 v[16:19], v[182:185], v[206:209], v[16:19]
	v_mfma_f32_16x16x32_bf16 v[4:7], v[172:175], v[214:217], v[4:7]
	v_mfma_f32_16x16x32_bf16 v[0:3], v[182:185], v[214:217], v[0:3]
	s_setprio 0
	s_add_i32 s60, s60, 2
	s_add_u32 s28, s28, 0x100
	s_addc_u32 s29, s29, 0
	s_add_u32 s54, s54, 0x100
	s_addc_u32 s55, s55, 0
	s_cmp_gt_u32 s60, 13
	s_barrier
	s_cbranch_scc0 .LBB0_427
	s_and_b64 vcc, exec, s[12:13]
	s_cbranch_vccz .LBB0_430
	s_barrier

; #define PG8_STAGE(bufoff, gbase, voff) do { _Pragma("unroll") for (int _i = 0; _i < 2; ++_i) \
;         __builtin_amdgcn_global_load_lds((const unsigned*)((const char*)(gbase) + (voff)[_i]), (PG8_LAS unsigned*)(lds + (bufoff) + ldsw + _i * 8192), 16, 0, 0); } while (0)
; #define PG8_LDA(dst, b, h) do { _Pragma("unroll") for (int m = 0; m < 4; ++m) _Pragma("unroll") for (int k = 0; k < 2; ++k) dst[m][k] = *(const PG8_LAS bf16x8*)(lds + PG8_SA(b, h) + aoff + m * 2048 + k * 1024); } while (0)
; #define PG8_LDB(dst, b, h) do { _Pragma("unroll") for (int n = 0; n < 2; ++n) _Pragma("unroll") for (int k = 0; k < 2; ++k) dst[n][k] = *(const PG8_LAS bf16x8*)(lds + PG8_SB(b, h) + boff + n * 2048 + k * 1024); } while (0)
; #define PG8_MMA(ai, bj, At, Bt) do { __builtin_amdgcn_s_setprio(1); _Pragma("unroll") for (int m = 0; m < 4; ++m) _Pragma("unroll") for (int n = 0; n < 2; ++n) _Pragma("unroll") for (int k = 0; k < 2; ++k) \
;         acc[ai][bj][m][n] = __builtin_amdgcn_mfma_f32_16x16x32_bf16(Bt[n][k], At[m][k], acc[ai][bj][m][n], 0, 0, 0); __builtin_amdgcn_s_setprio(0); } while (0)
; #define PG8_WAIT_V(n) asm volatile("s_waitcnt vmcnt(" #n ")" ::: "memory")
; #define PG8_WAIT_L(n) asm volatile("s_waitcnt lgkmcnt(" #n ")" ::: "memory")
; #define PG8_BAR __builtin_amdgcn_s_barrier()
; #define PG8_SCHED __builtin_amdgcn_sched_barrier(0)
; template <class Epi, class Sched, bool ALIGN_EPI = false, bool SP2 = false>
; __device__ __forceinline__ void gemm_phase(PG8_LAS unsigned char* lds, const Gemm g, const Sched& S, const Epi& E) {
;     ...
;             PG8_LDB(B0, 0, 0); PG8_LDB(B1, 0, 1); PG8_SCHED; PG8_LDA(At, 0, 0); PG8_STAGE(PG8_SA(1, 1), a1 + hstep, voffA);
;             PG8_WAIT_V(8); PG8_WAIT_L(0); PG8_BAR; PG8_MMA(0, 0, At, B0); PG8_MMA(0, 1, At, B1); PG8_BAR; PG8_SCHED;
;             PG8_LDA(At, 0, 1); PG8_STAGE(PG8_SB(0, 0), b2, voffB); PG8_STAGE(PG8_SB(0, 1), b2 + hstep, voffB); PG8_STAGE(PG8_SA(0, 0), a2, voffA);
;             PG8_WAIT_V(8); PG8_WAIT_L(0); PG8_BAR; PG8_MMA(1, 0, At, B0); PG8_MMA(1, 1, At, B1); PG8_BAR; PG8_SCHED;
.LBB0_537:
	ds_read_b128 v[154:157], v153
	ds_read_b128 v[160:163], v153 offset:1024
	ds_read_b128 v[164:167], v153 offset:2048
	ds_read_b128 v[168:171], v153 offset:3072
	ds_read_b128 v[172:175], v158
	ds_read_b128 v[178:181], v158 offset:1024
	ds_read_b128 v[182:185], v158 offset:2048
	ds_read_b128 v[186:189], v158 offset:3072
	s_add_u32 s2, s34, 0xfffc0080
	s_addc_u32 s3, s35, -1
	s_cmp_eq_u32 s68, 12
	s_cselect_b32 s19, s25, s3
	s_cselect_b32 s18, s63, s2
	s_cselect_b32 s3, s23, s67
	s_cselect_b32 s2, s65, s66
	v_lshl_add_u64 v[146:147], s[34:35], 0, v[136:137]
	s_add_i32 m0, s31, 0xc000
	ds_read_b128 v[190:193], v159
	ds_read_b128 v[194:197], v159 offset:1024
	ds_read_b128 v[198:201], v159 offset:2048
	ds_read_b128 v[202:205], v159 offset:3072
	ds_read_b128 v[206:209], v159 offset:4096
	ds_read_b128 v[210:213], v159 offset:5120
	ds_read_b128 v[214:217], v159 offset:6144
	ds_read_b128 v[218:221], v159 offset:7168
	global_load_lds_dwordx4 v[146:147], off
	v_lshl_add_u64 v[146:147], s[34:35], 0, v[138:139]
	s_add_i32 m0, s31, 0xe000
	s_nop 0
	global_load_lds_dwordx4 v[146:147], off
	s_waitcnt vmcnt(8)
	s_waitcnt lgkmcnt(0)
	s_barrier
	s_setprio 1
	s_waitcnt lgkmcnt(0)
	v_mfma_f32_16x16x32_bf16 v[124:127], v[154:157], v[190:193], v[124:127]
	v_mfma_f32_16x16x32_bf16 v[120:123], v[164:167], v[190:193], v[120:123]
	v_mfma_f32_16x16x32_bf16 v[116:119], v[154:157], v[198:201], v[116:119]
	v_mfma_f32_16x16x32_bf16 v[104:107], v[164:167], v[198:201], v[104:107]
	v_mfma_f32_16x16x32_bf16 v[92:95], v[154:157], v[206:209], v[92:95]
	v_mfma_f32_16x16x32_bf16 v[88:91], v[164:167], v[206:209], v[88:91]
	v_mfma_f32_16x16x32_bf16 v[76:79], v[154:157], v[214:217], v[76:79]
	v_mfma_f32_16x16x32_bf16 v[72:75], v[164:167], v[214:217], v[72:75]
	v_mfma_f32_16x16x32_bf16 v[124:127], v[160:163], v[194:197], v[124:127]
	v_mfma_f32_16x16x32_bf16 v[120:123], v[168:171], v[194:197], v[120:123]
	v_mfma_f32_16x16x32_bf16 v[116:119], v[160:163], v[202:205], v[116:119]
	v_mfma_f32_16x16x32_bf16 v[104:107], v[168:171], v[202:205], v[104:107]
	v_mfma_f32_16x16x32_bf16 v[92:95], v[160:163], v[210:213], v[92:95]
	v_mfma_f32_16x16x32_bf16 v[88:91], v[168:171], v[210:213], v[88:91]
	v_mfma_f32_16x16x32_bf16 v[76:79], v[160:163], v[218:221], v[76:79]
	v_mfma_f32_16x16x32_bf16 v[72:75], v[168:171], v[218:221], v[72:75]
	s_setprio 0
	s_setprio 1
	v_mfma_f32_16x16x32_bf16 v[112:115], v[172:175], v[190:193], v[112:115]
	v_mfma_f32_16x16x32_bf16 v[108:111], v[182:185], v[190:193], v[108:111]
	v_mfma_f32_16x16x32_bf16 v[100:103], v[172:175], v[198:201], v[100:103]
	v_mfma_f32_16x16x32_bf16 v[96:99], v[182:185], v[198:201], v[96:99]
	v_mfma_f32_16x16x32_bf16 v[84:87], v[172:175], v[206:209], v[84:87]
	v_mfma_f32_16x16x32_bf16 v[80:83], v[182:185], v[206:209], v[80:83]
	v_mfma_f32_16x16x32_bf16 v[68:71], v[172:175], v[214:217], v[68:71]
	v_mfma_f32_16x16x32_bf16 v[64:67], v[182:185], v[214:217], v[64:67]
	v_mfma_f32_16x16x32_bf16 v[112:115], v[178:181], v[194:197], v[112:115]
	v_mfma_f32_16x16x32_bf16 v[108:111], v[186:189], v[194:197], v[108:111]
	v_mfma_f32_16x16x32_bf16 v[100:103], v[178:181], v[202:205], v[100:103]
	v_mfma_f32_16x16x32_bf16 v[96:99], v[186:189], v[202:205], v[96:99]
	v_mfma_f32_16x16x32_bf16 v[84:87], v[178:181], v[210:213], v[84:87]
	v_mfma_f32_16x16x32_bf16 v[80:83], v[186:189], v[210:213], v[80:83]
	v_mfma_f32_16x16x32_bf16 v[68:71], v[178:181], v[218:221], v[68:71]
	v_mfma_f32_16x16x32_bf16 v[64:67], v[186:189], v[218:221], v[64:67]
	s_setprio 0
	s_barrier
	s_add_i32 s64, s52, s43
	v_lshl_add_u64 v[146:147], s[2:3], 0, v[130:131]
	s_mov_b32 m0, s64
	ds_read_b128 v[190:193], v159 offset:16384
	ds_read_b128 v[194:197], v159 offset:17408
	ds_read_b128 v[198:201], v159 offset:18432
	ds_read_b128 v[202:205], v159 offset:19456
	ds_read_b128 v[206:209], v159 offset:20480
	ds_read_b128 v[210:213], v159 offset:21504
	ds_read_b128 v[214:217], v159 offset:22528
	ds_read_b128 v[218:221], v159 offset:23552
	global_load_lds_dwordx4 v[146:147], off
	s_add_i32 m0, s64, 0x2000
	s_add_u32 s70, s2, 0x40000
	v_lshl_add_u64 v[222:223], s[2:3], 0, v[134:135]
	s_addc_u32 s71, s3, 0
	s_add_i32 s64, s53, s43
	global_load_lds_dwordx4 v[222:223], off
	v_lshl_add_u64 v[224:225], s[70:71], 0, v[130:131]
	s_mov_b32 m0, s64
	v_lshl_add_u64 v[226:227], s[18:19], 0, v[132:133]
	global_load_lds_dwordx4 v[224:225], off
	v_lshl_add_u64 v[224:225], s[70:71], 0, v[134:135]
	s_add_i32 m0, s64, 0x2000
	s_nop 0
	global_load_lds_dwordx4 v[224:225], off
	v_lshl_add_u64 v[224:225], s[18:19], 0, v[128:129]
	s_mov_b32 m0, s31
	s_nop 0
	global_load_lds_dwordx4 v[224:225], off
	s_mov_b32 m0, s46
	s_nop 0
	global_load_lds_dwordx4 v[226:227], off
	s_waitcnt vmcnt(8)
	s_waitcnt lgkmcnt(0)
	s_barrier
; #define PG8_STAGE(bufoff, gbase, voff) do { _Pragma("unroll") for (int _i = 0; _i < 2; ++_i) \
;         __builtin_amdgcn_global_load_lds((const unsigned*)((const char*)(gbase) + (voff)[_i]), (PG8_LAS unsigned*)(lds + (bufoff) + ldsw + _i * 8192), 16, 0, 0); } while (0)
; #define PG8_LDA(dst, b, h) do { _Pragma("unroll") for (int m = 0; m < 4; ++m) _Pragma("unroll") for (int k = 0; k < 2; ++k) dst[m][k] = *(const PG8_LAS bf16x8*)(lds + PG8_SA(b, h) + aoff + m * 2048 + k * 1024); } while (0)
; #define PG8_LDB(dst, b, h) do { _Pragma("unroll") for (int n = 0; n < 2; ++n) _Pragma("unroll") for (int k = 0; k < 2; ++k) dst[n][k] = *(const PG8_LAS bf16x8*)(lds + PG8_SB(b, h) + boff + n * 2048 + k * 1024); } while (0)
; #define PG8_MMA(ai, bj, At, Bt) do { __builtin_amdgcn_s_setprio(1); _Pragma("unroll") for (int m = 0; m < 4; ++m) _Pragma("unroll") for (int n = 0; n < 2; ++n) _Pragma("unroll") for (int k = 0; k < 2; ++k) \
;         acc[ai][bj][m][n] = __builtin_amdgcn_mfma_f32_16x16x32_bf16(Bt[n][k], At[m][k], acc[ai][bj][m][n], 0, 0, 0); __builtin_amdgcn_s_setprio(0); } while (0)
; #define PG8_WAIT_V(n) asm volatile("s_waitcnt vmcnt(" #n ")" ::: "memory")
; #define PG8_WAIT_L(n) asm volatile("s_waitcnt lgkmcnt(" #n ")" ::: "memory")
; #define PG8_BAR __builtin_amdgcn_s_barrier()
; #define PG8_SCHED __builtin_amdgcn_sched_barrier(0)
; template <class Epi, class Sched, bool ALIGN_EPI = false, bool SP2 = false>
; __device__ __forceinline__ void gemm_phase(PG8_LAS unsigned char* lds, const Gemm g, const Sched& S, const Epi& E) {
;     ...
;             PG8_WAIT_V(8); PG8_WAIT_L(0); PG8_BAR; PG8_MMA(1, 0, At, B0); PG8_MMA(1, 1, At, B1); PG8_BAR; PG8_SCHED;
;             PG8_LDB(B0, 1, 0); PG8_LDB(B1, 1, 1); PG8_SCHED; PG8_LDA(At, 1, 0); PG8_STAGE(PG8_SA(0, 1), a2 + hstep, voffA);
;             PG8_WAIT_V(8); PG8_WAIT_L(0); PG8_BAR; PG8_MMA(0, 0, At, B0); PG8_MMA(0, 1, At, B1); PG8_BAR; PG8_SCHED;
	s_setprio 1
	s_waitcnt lgkmcnt(0)
	v_mfma_f32_16x16x32_bf16 v[60:63], v[154:157], v[190:193], v[60:63]
	v_mfma_f32_16x16x32_bf16 v[56:59], v[164:167], v[190:193], v[56:59]
	v_mfma_f32_16x16x32_bf16 v[44:47], v[154:157], v[198:201], v[44:47]
	v_mfma_f32_16x16x32_bf16 v[40:43], v[164:167], v[198:201], v[40:43]
	v_mfma_f32_16x16x32_bf16 v[28:31], v[154:157], v[206:209], v[28:31]
	v_mfma_f32_16x16x32_bf16 v[24:27], v[164:167], v[206:209], v[24:27]
	v_mfma_f32_16x16x32_bf16 v[12:15], v[154:157], v[214:217], v[12:15]
	v_mfma_f32_16x16x32_bf16 v[8:11], v[164:167], v[214:217], v[8:11]
	v_mfma_f32_16x16x32_bf16 v[60:63], v[160:163], v[194:197], v[60:63]
	v_mfma_f32_16x16x32_bf16 v[56:59], v[168:171], v[194:197], v[56:59]
	v_mfma_f32_16x16x32_bf16 v[44:47], v[160:163], v[202:205], v[44:47]
	v_mfma_f32_16x16x32_bf16 v[40:43], v[168:171], v[202:205], v[40:43]
	v_mfma_f32_16x16x32_bf16 v[28:31], v[160:163], v[210:213], v[28:31]
	v_mfma_f32_16x16x32_bf16 v[24:27], v[168:171], v[210:213], v[24:27]
	v_mfma_f32_16x16x32_bf16 v[12:15], v[160:163], v[218:221], v[12:15]
	v_mfma_f32_16x16x32_bf16 v[8:11], v[168:171], v[218:221], v[8:11]
	s_setprio 0
	s_setprio 1
	v_mfma_f32_16x16x32_bf16 v[52:55], v[172:175], v[190:193], v[52:55]
	v_mfma_f32_16x16x32_bf16 v[48:51], v[182:185], v[190:193], v[48:51]
	v_mfma_f32_16x16x32_bf16 v[36:39], v[172:175], v[198:201], v[36:39]
	v_mfma_f32_16x16x32_bf16 v[32:35], v[182:185], v[198:201], v[32:35]
	v_mfma_f32_16x16x32_bf16 v[20:23], v[172:175], v[206:209], v[20:23]
	v_mfma_f32_16x16x32_bf16 v[16:19], v[182:185], v[206:209], v[16:19]
	v_mfma_f32_16x16x32_bf16 v[4:7], v[172:175], v[214:217], v[4:7]
	v_mfma_f32_16x16x32_bf16 v[0:3], v[182:185], v[214:217], v[0:3]
	v_mfma_f32_16x16x32_bf16 v[52:55], v[178:181], v[194:197], v[52:55]
	v_mfma_f32_16x16x32_bf16 v[48:51], v[186:189], v[194:197], v[48:51]
	v_mfma_f32_16x16x32_bf16 v[36:39], v[178:181], v[202:205], v[36:39]
	v_mfma_f32_16x16x32_bf16 v[32:35], v[186:189], v[202:205], v[32:35]
	v_mfma_f32_16x16x32_bf16 v[20:23], v[178:181], v[210:213], v[20:23]
	v_mfma_f32_16x16x32_bf16 v[16:19], v[186:189], v[210:213], v[16:19]
	v_mfma_f32_16x16x32_bf16 v[4:7], v[178:181], v[218:221], v[4:7]
	v_mfma_f32_16x16x32_bf16 v[0:3], v[186:189], v[218:221], v[0:3]
	s_setprio 0
	s_barrier
	s_add_i32 s64, 0, 0x18000
	v_add_u32_e32 v144, s64, v149
	s_add_i32 s69, 0, 0x1c000
	ds_read_b128 v[154:157], v144
	ds_read_b128 v[160:163], v144 offset:1024
	ds_read_b128 v[164:167], v144 offset:2048
	ds_read_b128 v[168:171], v144 offset:3072
	v_add_u32_e32 v144, s69, v149
	ds_read_b128 v[172:175], v144
	ds_read_b128 v[178:181], v144 offset:1024
	ds_read_b128 v[182:185], v144 offset:2048
	ds_read_b128 v[186:189], v144 offset:3072
	s_add_u32 s18, s18, 0x40000
	s_addc_u32 s19, s19, 0
	s_mov_b32 m0, s47
	v_lshl_add_u64 v[228:229], s[18:19], 0, v[128:129]
	ds_read_b128 v[190:193], v159 offset:32768
	ds_read_b128 v[194:197], v159 offset:33792
	ds_read_b128 v[198:201], v159 offset:34816
	ds_read_b128 v[202:205], v159 offset:35840
	ds_read_b128 v[206:209], v159 offset:36864
	ds_read_b128 v[210:213], v159 offset:37888
	ds_read_b128 v[214:217], v159 offset:38912
	ds_read_b128 v[218:221], v159 offset:39936
	global_load_lds_dwordx4 v[228:229], off
	v_lshl_add_u64 v[228:229], s[18:19], 0, v[132:133]
	s_mov_b32 m0, s48
	s_nop 0
	global_load_lds_dwordx4 v[228:229], off
	s_waitcnt vmcnt(8)
	s_waitcnt lgkmcnt(0)
	s_barrier
	s_setprio 1
	s_waitcnt lgkmcnt(0)
	v_mfma_f32_16x16x32_bf16 v[124:127], v[154:157], v[190:193], v[124:127]
	v_mfma_f32_16x16x32_bf16 v[120:123], v[164:167], v[190:193], v[120:123]
	v_mfma_f32_16x16x32_bf16 v[116:119], v[154:157], v[198:201], v[116:119]
	v_mfma_f32_16x16x32_bf16 v[104:107], v[164:167], v[198:201], v[104:107]
	v_mfma_f32_16x16x32_bf16 v[92:95], v[154:157], v[206:209], v[92:95]
	v_mfma_f32_16x16x32_bf16 v[88:91], v[164:167], v[206:209], v[88:91]
	v_mfma_f32_16x16x32_bf16 v[76:79], v[154:157], v[214:217], v[76:79]
	v_mfma_f32_16x16x32_bf16 v[72:75], v[164:167], v[214:217], v[72:75]
	v_mfma_f32_16x16x32_bf16 v[124:127], v[160:163], v[194:197], v[124:127]
	v_mfma_f32_16x16x32_bf16 v[120:123], v[168:171], v[194:197], v[120:123]
	v_mfma_f32_16x16x32_bf16 v[116:119], v[160:163], v[202:205], v[116:119]
	v_mfma_f32_16x16x32_bf16 v[104:107], v[168:171], v[202:205], v[104:107]
	v_mfma_f32_16x16x32_bf16 v[92:95], v[160:163], v[210:213], v[92:95]
	v_mfma_f32_16x16x32_bf16 v[88:91], v[168:171], v[210:213], v[88:91]
	v_mfma_f32_16x16x32_bf16 v[76:79], v[160:163], v[218:221], v[76:79]
	v_mfma_f32_16x16x32_bf16 v[72:75], v[168:171], v[218:221], v[72:75]
	s_setprio 0
	s_setprio 1
	v_mfma_f32_16x16x32_bf16 v[112:115], v[172:175], v[190:193], v[112:115]
	v_mfma_f32_16x16x32_bf16 v[108:111], v[182:185], v[190:193], v[108:111]
	v_mfma_f32_16x16x32_bf16 v[100:103], v[172:175], v[198:201], v[100:103]
	v_mfma_f32_16x16x32_bf16 v[96:99], v[182:185], v[198:201], v[96:99]
	v_mfma_f32_16x16x32_bf16 v[84:87], v[172:175], v[206:209], v[84:87]
	v_mfma_f32_16x16x32_bf16 v[80:83], v[182:185], v[206:209], v[80:83]
	v_mfma_f32_16x16x32_bf16 v[68:71], v[172:175], v[214:217], v[68:71]
	v_mfma_f32_16x16x32_bf16 v[64:67], v[182:185], v[214:217], v[64:67]
	v_mfma_f32_16x16x32_bf16 v[112:115], v[178:181], v[194:197], v[112:115]
	v_mfma_f32_16x16x32_bf16 v[108:111], v[186:189], v[194:197], v[108:111]
	v_mfma_f32_16x16x32_bf16 v[100:103], v[178:181], v[202:205], v[100:103]
	v_mfma_f32_16x16x32_bf16 v[96:99], v[186:189], v[202:205], v[96:99]
	v_mfma_f32_16x16x32_bf16 v[84:87], v[178:181], v[210:213], v[84:87]
	v_mfma_f32_16x16x32_bf16 v[80:83], v[186:189], v[210:213], v[80:83]
	v_mfma_f32_16x16x32_bf16 v[68:71], v[178:181], v[218:221], v[68:71]
	v_mfma_f32_16x16x32_bf16 v[64:67], v[186:189], v[218:221], v[64:67]
	s_setprio 0
	s_barrier
; #define PG8_STAGE(bufoff, gbase, voff) do { _Pragma("unroll") for (int _i = 0; _i < 2; ++_i) \
;         __builtin_amdgcn_global_load_lds((const unsigned*)((const char*)(gbase) + (voff)[_i]), (PG8_LAS unsigned*)(lds + (bufoff) + ldsw + _i * 8192), 16, 0, 0); } while (0)
; #define PG8_LDA(dst, b, h) do { _Pragma("unroll") for (int m = 0; m < 4; ++m) _Pragma("unroll") for (int k = 0; k < 2; ++k) dst[m][k] = *(const PG8_LAS bf16x8*)(lds + PG8_SA(b, h) + aoff + m * 2048 + k * 1024); } while (0)
; #define PG8_MMA(ai, bj, At, Bt) do { __builtin_amdgcn_s_setprio(1); _Pragma("unroll") for (int m = 0; m < 4; ++m) _Pragma("unroll") for (int n = 0; n < 2; ++n) _Pragma("unroll") for (int k = 0; k < 2; ++k) \
;         acc[ai][bj][m][n] = __builtin_amdgcn_mfma_f32_16x16x32_bf16(Bt[n][k], At[m][k], acc[ai][bj][m][n], 0, 0, 0); __builtin_amdgcn_s_setprio(0); } while (0)
; #define PG8_WAIT_V(n) asm volatile("s_waitcnt vmcnt(" #n ")" ::: "memory")
; #define PG8_WAIT_L(n) asm volatile("s_waitcnt lgkmcnt(" #n ")" ::: "memory")
; #define PG8_BAR __builtin_amdgcn_s_barrier()
; #define PG8_SCHED __builtin_amdgcn_sched_barrier(0)
; template <class Epi, class Sched, bool ALIGN_EPI = false, bool SP2 = false>
; __device__ __forceinline__ void gemm_phase(PG8_LAS unsigned char* lds, const Gemm g, const Sched& S, const Epi& E) {
;     ...
;         for (int t = 0; t < nt; t += 2) {
;     ...
;             PG8_LDA(At, 1, 1); PG8_STAGE(PG8_SB(1, 0), b3, voffB); PG8_STAGE(PG8_SB(1, 1), b3 + hstep, voffB); PG8_STAGE(PG8_SA(1, 0), a3, voffA);
;             PG8_WAIT_V(8); PG8_WAIT_L(0); PG8_BAR; PG8_MMA(1, 0, At, B0); PG8_MMA(1, 1, At, B1); PG8_BAR; PG8_SCHED;
	s_add_i32 s18, s64, s43
	v_lshl_add_u64 v[146:147], v[146:147], 0, s[6:7]
	s_mov_b32 m0, s18
	ds_read_b128 v[190:193], v159 offset:49152
	ds_read_b128 v[194:197], v159 offset:50176
	ds_read_b128 v[198:201], v159 offset:51200
	ds_read_b128 v[202:205], v159 offset:52224
	ds_read_b128 v[206:209], v159 offset:53248
	ds_read_b128 v[210:213], v159 offset:54272
	ds_read_b128 v[214:217], v159 offset:55296
	ds_read_b128 v[218:221], v159 offset:56320
	global_load_lds_dwordx4 v[146:147], off
	s_add_i32 m0, s18, 0x2000
	s_add_u32 s2, s2, 0x40080
	v_lshl_add_u64 v[146:147], v[222:223], 0, s[6:7]
	s_addc_u32 s3, s3, 0
	s_add_i32 s18, s69, s43
	global_load_lds_dwordx4 v[146:147], off
	v_lshl_add_u64 v[146:147], s[2:3], 0, v[130:131]
	s_mov_b32 m0, s18
	s_nop 0
	global_load_lds_dwordx4 v[146:147], off
	v_lshl_add_u64 v[146:147], s[2:3], 0, v[134:135]
	s_add_i32 m0, s18, 0x2000
	s_nop 0
	global_load_lds_dwordx4 v[146:147], off
	v_lshl_add_u64 v[146:147], v[224:225], 0, s[6:7]
	s_mov_b32 m0, s50
	s_nop 0
	global_load_lds_dwordx4 v[146:147], off
	v_lshl_add_u64 v[146:147], v[226:227], 0, s[6:7]
	s_mov_b32 m0, s51
	s_nop 0
	global_load_lds_dwordx4 v[146:147], off
	s_waitcnt vmcnt(8)
	s_waitcnt lgkmcnt(0)
	s_barrier
	s_setprio 1
	s_waitcnt lgkmcnt(0)
	v_mfma_f32_16x16x32_bf16 v[60:63], v[154:157], v[190:193], v[60:63]
	v_mfma_f32_16x16x32_bf16 v[56:59], v[164:167], v[190:193], v[56:59]
	v_mfma_f32_16x16x32_bf16 v[44:47], v[154:157], v[198:201], v[44:47]
	v_mfma_f32_16x16x32_bf16 v[40:43], v[164:167], v[198:201], v[40:43]
	v_mfma_f32_16x16x32_bf16 v[28:31], v[154:157], v[206:209], v[28:31]
	v_mfma_f32_16x16x32_bf16 v[24:27], v[164:167], v[206:209], v[24:27]
	v_mfma_f32_16x16x32_bf16 v[12:15], v[154:157], v[214:217], v[12:15]
	v_mfma_f32_16x16x32_bf16 v[8:11], v[164:167], v[214:217], v[8:11]
	v_mfma_f32_16x16x32_bf16 v[60:63], v[160:163], v[194:197], v[60:63]
	v_mfma_f32_16x16x32_bf16 v[56:59], v[168:171], v[194:197], v[56:59]
	v_mfma_f32_16x16x32_bf16 v[44:47], v[160:163], v[202:205], v[44:47]
	v_mfma_f32_16x16x32_bf16 v[40:43], v[168:171], v[202:205], v[40:43]
	v_mfma_f32_16x16x32_bf16 v[28:31], v[160:163], v[210:213], v[28:31]
	v_mfma_f32_16x16x32_bf16 v[24:27], v[168:171], v[210:213], v[24:27]
	v_mfma_f32_16x16x32_bf16 v[12:15], v[160:163], v[218:221], v[12:15]
	v_mfma_f32_16x16x32_bf16 v[8:11], v[168:171], v[218:221], v[8:11]
	s_setprio 0
	s_setprio 1
	v_mfma_f32_16x16x32_bf16 v[52:55], v[172:175], v[190:193], v[52:55]
	v_mfma_f32_16x16x32_bf16 v[48:51], v[182:185], v[190:193], v[48:51]
	v_mfma_f32_16x16x32_bf16 v[36:39], v[172:175], v[198:201], v[36:39]
	v_mfma_f32_16x16x32_bf16 v[32:35], v[182:185], v[198:201], v[32:35]
	v_mfma_f32_16x16x32_bf16 v[20:23], v[172:175], v[206:209], v[20:23]
	v_mfma_f32_16x16x32_bf16 v[16:19], v[182:185], v[206:209], v[16:19]
	v_mfma_f32_16x16x32_bf16 v[4:7], v[172:175], v[214:217], v[4:7]
	v_mfma_f32_16x16x32_bf16 v[0:3], v[182:185], v[214:217], v[0:3]
	v_mfma_f32_16x16x32_bf16 v[52:55], v[178:181], v[194:197], v[52:55]
	v_mfma_f32_16x16x32_bf16 v[48:51], v[186:189], v[194:197], v[48:51]
	v_mfma_f32_16x16x32_bf16 v[36:39], v[178:181], v[202:205], v[36:39]
	v_mfma_f32_16x16x32_bf16 v[32:35], v[186:189], v[202:205], v[32:35]
	v_mfma_f32_16x16x32_bf16 v[20:23], v[178:181], v[210:213], v[20:23]
	v_mfma_f32_16x16x32_bf16 v[16:19], v[186:189], v[210:213], v[16:19]
	v_mfma_f32_16x16x32_bf16 v[4:7], v[178:181], v[218:221], v[4:7]
	v_mfma_f32_16x16x32_bf16 v[0:3], v[186:189], v[218:221], v[0:3]
	s_setprio 0
	s_add_i32 s68, s68, 2
	s_add_u32 s34, s34, 0x100
	s_addc_u32 s35, s35, 0
	s_add_u32 s66, s66, 0x100
	s_addc_u32 s67, s67, 0
	s_cmp_gt_u32 s68, 13
	s_barrier
	s_cbranch_scc0 .LBB0_537
	s_and_b64 vcc, exec, s[8:9]
	s_cbranch_vccz .LBB0_540
	s_barrier

; #define PG8_STAGE(bufoff, gbase, voff) do { _Pragma("unroll") for (int _i = 0; _i < 2; ++_i) \
;         __builtin_amdgcn_global_load_lds((const unsigned*)((const char*)(gbase) + (voff)[_i]), (PG8_LAS unsigned*)(lds + (bufoff) + ldsw + _i * 8192), 16, 0, 0); } while (0)
; #define PG8_LDA(dst, b, h) do { _Pragma("unroll") for (int m = 0; m < 4; ++m) _Pragma("unroll") for (int k = 0; k < 2; ++k) dst[m][k] = *(const PG8_LAS bf16x8*)(lds + PG8_SA(b, h) + aoff + m * 2048 + k * 1024); } while (0)
; #define PG8_LDB(dst, b, h) do { _Pragma("unroll") for (int n = 0; n < 2; ++n) _Pragma("unroll") for (int k = 0; k < 2; ++k) dst[n][k] = *(const PG8_LAS bf16x8*)(lds + PG8_SB(b, h) + boff + n * 2048 + k * 1024); } while (0)
; #define PG8_MMA(ai, bj, At, Bt) do { __builtin_amdgcn_s_setprio(1); _Pragma("unroll") for (int m = 0; m < 4; ++m) _Pragma("unroll") for (int n = 0; n < 2; ++n) _Pragma("unroll") for (int k = 0; k < 2; ++k) \
;         acc[ai][bj][m][n] = __builtin_amdgcn_mfma_f32_16x16x32_bf16(Bt[n][k], At[m][k], acc[ai][bj][m][n], 0, 0, 0); __builtin_amdgcn_s_setprio(0); } while (0)
; #define PG8_WAIT_V(n) asm volatile("s_waitcnt vmcnt(" #n ")" ::: "memory")
; #define PG8_WAIT_L(n) asm volatile("s_waitcnt lgkmcnt(" #n ")" ::: "memory")
; #define PG8_BAR __builtin_amdgcn_s_barrier()
; #define PG8_SCHED __builtin_amdgcn_sched_barrier(0)
; template <class Epi, class Sched, bool ALIGN_EPI = false, bool SP2 = false>
; __device__ __forceinline__ void gemm_phase(PG8_LAS unsigned char* lds, const Gemm g, const Sched& S, const Epi& E) {
;     ...
;             PG8_LDB(B0, 0, 0); PG8_LDB(B1, 0, 1); PG8_SCHED; PG8_LDA(At, 0, 0); PG8_STAGE(PG8_SA(1, 1), a1 + hstep, voffA);
;             PG8_WAIT_V(8); PG8_WAIT_L(0); PG8_BAR; PG8_MMA(0, 0, At, B0); PG8_MMA(0, 1, At, B1); PG8_BAR; PG8_SCHED;
;             PG8_LDA(At, 0, 1); PG8_STAGE(PG8_SB(0, 0), b2, voffB); PG8_STAGE(PG8_SB(0, 1), b2 + hstep, voffB); PG8_STAGE(PG8_SA(0, 0), a2, voffA);
;             PG8_WAIT_V(8); PG8_WAIT_L(0); PG8_BAR; PG8_MMA(1, 0, At, B0); PG8_MMA(1, 1, At, B1); PG8_BAR; PG8_SCHED;
.LBB0_615:
	ds_read_b128 v[144:147], v151
	ds_read_b128 v[156:159], v151 offset:1024
	ds_read_b128 v[160:163], v151 offset:2048
	ds_read_b128 v[164:167], v151 offset:3072
	ds_read_b128 v[168:171], v152
	ds_read_b128 v[172:175], v152 offset:1024
	ds_read_b128 v[178:181], v152 offset:2048
	ds_read_b128 v[182:185], v152 offset:3072
	s_add_u32 s2, s28, 0xfff00080
	s_addc_u32 s3, s29, -1
	s_cmp_eq_u32 s60, 60
	s_cselect_b32 s19, s17, s3
	s_cselect_b32 s18, s27, s2
	s_cselect_b32 s3, s15, s55
	s_cselect_b32 s2, s53, s54
	v_lshl_add_u64 v[218:219], s[28:29], 0, v[136:137]
	s_add_i32 m0, s34, 0xc000
	ds_read_b128 v[186:189], v153
	ds_read_b128 v[190:193], v153 offset:1024
	ds_read_b128 v[194:197], v153 offset:2048
	ds_read_b128 v[198:201], v153 offset:3072
	ds_read_b128 v[202:205], v153 offset:4096
	ds_read_b128 v[206:209], v153 offset:5120
	ds_read_b128 v[210:213], v153 offset:6144
	ds_read_b128 v[214:217], v153 offset:7168
	global_load_lds_dwordx4 v[218:219], off
	v_lshl_add_u64 v[218:219], s[28:29], 0, v[138:139]
	s_add_i32 m0, s34, 0xe000
	s_nop 0
	global_load_lds_dwordx4 v[218:219], off
	s_waitcnt vmcnt(8)
	s_waitcnt lgkmcnt(0)
	s_barrier
	s_setprio 1
	s_waitcnt lgkmcnt(0)
	v_mfma_f32_16x16x32_bf16 v[124:127], v[144:147], v[186:189], v[124:127]
	v_mfma_f32_16x16x32_bf16 v[120:123], v[160:163], v[186:189], v[120:123]
	v_mfma_f32_16x16x32_bf16 v[108:111], v[144:147], v[194:197], v[108:111]
	v_mfma_f32_16x16x32_bf16 v[104:107], v[160:163], v[194:197], v[104:107]
	v_mfma_f32_16x16x32_bf16 v[92:95], v[144:147], v[202:205], v[92:95]
	v_mfma_f32_16x16x32_bf16 v[88:91], v[160:163], v[202:205], v[88:91]
	v_mfma_f32_16x16x32_bf16 v[76:79], v[144:147], v[210:213], v[76:79]
	v_mfma_f32_16x16x32_bf16 v[72:75], v[160:163], v[210:213], v[72:75]
	v_mfma_f32_16x16x32_bf16 v[124:127], v[156:159], v[190:193], v[124:127]
	v_mfma_f32_16x16x32_bf16 v[120:123], v[164:167], v[190:193], v[120:123]
	v_mfma_f32_16x16x32_bf16 v[108:111], v[156:159], v[198:201], v[108:111]
	v_mfma_f32_16x16x32_bf16 v[104:107], v[164:167], v[198:201], v[104:107]
	v_mfma_f32_16x16x32_bf16 v[92:95], v[156:159], v[206:209], v[92:95]
	v_mfma_f32_16x16x32_bf16 v[88:91], v[164:167], v[206:209], v[88:91]
	v_mfma_f32_16x16x32_bf16 v[76:79], v[156:159], v[214:217], v[76:79]
	v_mfma_f32_16x16x32_bf16 v[72:75], v[164:167], v[214:217], v[72:75]
	s_setprio 0
	s_setprio 1
	v_mfma_f32_16x16x32_bf16 v[116:119], v[168:171], v[186:189], v[116:119]
	v_mfma_f32_16x16x32_bf16 v[112:115], v[178:181], v[186:189], v[112:115]
	v_mfma_f32_16x16x32_bf16 v[100:103], v[168:171], v[194:197], v[100:103]
	v_mfma_f32_16x16x32_bf16 v[96:99], v[178:181], v[194:197], v[96:99]
	v_mfma_f32_16x16x32_bf16 v[84:87], v[168:171], v[202:205], v[84:87]
	v_mfma_f32_16x16x32_bf16 v[80:83], v[178:181], v[202:205], v[80:83]
	v_mfma_f32_16x16x32_bf16 v[68:71], v[168:171], v[210:213], v[68:71]
	v_mfma_f32_16x16x32_bf16 v[64:67], v[178:181], v[210:213], v[64:67]
	v_mfma_f32_16x16x32_bf16 v[116:119], v[172:175], v[190:193], v[116:119]
	v_mfma_f32_16x16x32_bf16 v[112:115], v[182:185], v[190:193], v[112:115]
	v_mfma_f32_16x16x32_bf16 v[100:103], v[172:175], v[198:201], v[100:103]
	v_mfma_f32_16x16x32_bf16 v[96:99], v[182:185], v[198:201], v[96:99]
	v_mfma_f32_16x16x32_bf16 v[84:87], v[172:175], v[206:209], v[84:87]
	v_mfma_f32_16x16x32_bf16 v[80:83], v[182:185], v[206:209], v[80:83]
	v_mfma_f32_16x16x32_bf16 v[68:71], v[172:175], v[214:217], v[68:71]
	v_mfma_f32_16x16x32_bf16 v[64:67], v[182:185], v[214:217], v[64:67]
	s_setprio 0
	s_barrier
	s_add_i32 s61, s50, s33
	v_lshl_add_u64 v[218:219], s[2:3], 0, v[130:131]
	s_mov_b32 m0, s61
	ds_read_b128 v[186:189], v153 offset:16384
	ds_read_b128 v[190:193], v153 offset:17408
	ds_read_b128 v[194:197], v153 offset:18432
	ds_read_b128 v[198:201], v153 offset:19456
	ds_read_b128 v[202:205], v153 offset:20480
	ds_read_b128 v[206:209], v153 offset:21504
	ds_read_b128 v[210:213], v153 offset:22528
	ds_read_b128 v[214:217], v153 offset:23552
	global_load_lds_dwordx4 v[218:219], off
	s_add_i32 m0, s61, 0x2000
	s_add_u32 s62, s2, 0x100000
	v_lshl_add_u64 v[220:221], s[2:3], 0, v[134:135]
	s_addc_u32 s63, s3, 0
	s_add_i32 s61, s51, s33
	global_load_lds_dwordx4 v[220:221], off
	v_lshl_add_u64 v[222:223], s[62:63], 0, v[130:131]
	s_mov_b32 m0, s61
	v_lshl_add_u64 v[224:225], s[18:19], 0, v[132:133]
	global_load_lds_dwordx4 v[222:223], off
	v_lshl_add_u64 v[222:223], s[62:63], 0, v[134:135]
	s_add_i32 m0, s61, 0x2000
	s_nop 0
	global_load_lds_dwordx4 v[222:223], off
	v_lshl_add_u64 v[222:223], s[18:19], 0, v[128:129]
	s_mov_b32 m0, s34
	s_nop 0
	global_load_lds_dwordx4 v[222:223], off
	s_mov_b32 m0, s35
	s_nop 0
	global_load_lds_dwordx4 v[224:225], off
	s_waitcnt vmcnt(8)
	s_waitcnt lgkmcnt(0)
	s_barrier
; #define PG8_STAGE(bufoff, gbase, voff) do { _Pragma("unroll") for (int _i = 0; _i < 2; ++_i) \
;         __builtin_amdgcn_global_load_lds((const unsigned*)((const char*)(gbase) + (voff)[_i]), (PG8_LAS unsigned*)(lds + (bufoff) + ldsw + _i * 8192), 16, 0, 0); } while (0)
; #define PG8_LDA(dst, b, h) do { _Pragma("unroll") for (int m = 0; m < 4; ++m) _Pragma("unroll") for (int k = 0; k < 2; ++k) dst[m][k] = *(const PG8_LAS bf16x8*)(lds + PG8_SA(b, h) + aoff + m * 2048 + k * 1024); } while (0)
; #define PG8_LDB(dst, b, h) do { _Pragma("unroll") for (int n = 0; n < 2; ++n) _Pragma("unroll") for (int k = 0; k < 2; ++k) dst[n][k] = *(const PG8_LAS bf16x8*)(lds + PG8_SB(b, h) + boff + n * 2048 + k * 1024); } while (0)
; #define PG8_MMA(ai, bj, At, Bt) do { __builtin_amdgcn_s_setprio(1); _Pragma("unroll") for (int m = 0; m < 4; ++m) _Pragma("unroll") for (int n = 0; n < 2; ++n) _Pragma("unroll") for (int k = 0; k < 2; ++k) \
;         acc[ai][bj][m][n] = __builtin_amdgcn_mfma_f32_16x16x32_bf16(Bt[n][k], At[m][k], acc[ai][bj][m][n], 0, 0, 0); __builtin_amdgcn_s_setprio(0); } while (0)
; #define PG8_WAIT_V(n) asm volatile("s_waitcnt vmcnt(" #n ")" ::: "memory")
; #define PG8_WAIT_L(n) asm volatile("s_waitcnt lgkmcnt(" #n ")" ::: "memory")
; #define PG8_BAR __builtin_amdgcn_s_barrier()
; #define PG8_SCHED __builtin_amdgcn_sched_barrier(0)
; template <class Epi, class Sched, bool ALIGN_EPI = false, bool SP2 = false>
; __device__ __forceinline__ void gemm_phase(PG8_LAS unsigned char* lds, const Gemm g, const Sched& S, const Epi& E) {
;     ...
;             PG8_WAIT_V(8); PG8_WAIT_L(0); PG8_BAR; PG8_MMA(1, 0, At, B0); PG8_MMA(1, 1, At, B1); PG8_BAR; PG8_SCHED;
;             PG8_LDB(B0, 1, 0); PG8_LDB(B1, 1, 1); PG8_SCHED; PG8_LDA(At, 1, 0); PG8_STAGE(PG8_SA(0, 1), a2 + hstep, voffA);
;             PG8_WAIT_V(8); PG8_WAIT_L(0); PG8_BAR; PG8_MMA(0, 0, At, B0); PG8_MMA(0, 1, At, B1); PG8_BAR; PG8_SCHED;
	s_setprio 1
	s_waitcnt lgkmcnt(0)
	v_mfma_f32_16x16x32_bf16 v[60:63], v[144:147], v[186:189], v[60:63]
	v_mfma_f32_16x16x32_bf16 v[56:59], v[160:163], v[186:189], v[56:59]
	v_mfma_f32_16x16x32_bf16 v[44:47], v[144:147], v[194:197], v[44:47]
	v_mfma_f32_16x16x32_bf16 v[40:43], v[160:163], v[194:197], v[40:43]
	v_mfma_f32_16x16x32_bf16 v[28:31], v[144:147], v[202:205], v[28:31]
	v_mfma_f32_16x16x32_bf16 v[24:27], v[160:163], v[202:205], v[24:27]
	v_mfma_f32_16x16x32_bf16 v[12:15], v[144:147], v[210:213], v[12:15]
	v_mfma_f32_16x16x32_bf16 v[8:11], v[160:163], v[210:213], v[8:11]
	v_mfma_f32_16x16x32_bf16 v[60:63], v[156:159], v[190:193], v[60:63]
	v_mfma_f32_16x16x32_bf16 v[56:59], v[164:167], v[190:193], v[56:59]
	v_mfma_f32_16x16x32_bf16 v[44:47], v[156:159], v[198:201], v[44:47]
	v_mfma_f32_16x16x32_bf16 v[40:43], v[164:167], v[198:201], v[40:43]
	v_mfma_f32_16x16x32_bf16 v[28:31], v[156:159], v[206:209], v[28:31]
	v_mfma_f32_16x16x32_bf16 v[24:27], v[164:167], v[206:209], v[24:27]
	v_mfma_f32_16x16x32_bf16 v[12:15], v[156:159], v[214:217], v[12:15]
	v_mfma_f32_16x16x32_bf16 v[8:11], v[164:167], v[214:217], v[8:11]
	s_setprio 0
	s_setprio 1
	v_mfma_f32_16x16x32_bf16 v[52:55], v[168:171], v[186:189], v[52:55]
	v_mfma_f32_16x16x32_bf16 v[48:51], v[178:181], v[186:189], v[48:51]
	v_mfma_f32_16x16x32_bf16 v[36:39], v[168:171], v[194:197], v[36:39]
	v_mfma_f32_16x16x32_bf16 v[32:35], v[178:181], v[194:197], v[32:35]
	v_mfma_f32_16x16x32_bf16 v[20:23], v[168:171], v[202:205], v[20:23]
	v_mfma_f32_16x16x32_bf16 v[16:19], v[178:181], v[202:205], v[16:19]
	v_mfma_f32_16x16x32_bf16 v[4:7], v[168:171], v[210:213], v[4:7]
	v_mfma_f32_16x16x32_bf16 v[0:3], v[178:181], v[210:213], v[0:3]
	v_mfma_f32_16x16x32_bf16 v[52:55], v[172:175], v[190:193], v[52:55]
	v_mfma_f32_16x16x32_bf16 v[48:51], v[182:185], v[190:193], v[48:51]
	v_mfma_f32_16x16x32_bf16 v[36:39], v[172:175], v[198:201], v[36:39]
	v_mfma_f32_16x16x32_bf16 v[32:35], v[182:185], v[198:201], v[32:35]
	v_mfma_f32_16x16x32_bf16 v[20:23], v[172:175], v[206:209], v[20:23]
	v_mfma_f32_16x16x32_bf16 v[16:19], v[182:185], v[206:209], v[16:19]
	v_mfma_f32_16x16x32_bf16 v[4:7], v[172:175], v[214:217], v[4:7]
	v_mfma_f32_16x16x32_bf16 v[0:3], v[182:185], v[214:217], v[0:3]
	s_setprio 0
	s_barrier
	s_add_i32 s61, 0, 0x18000
	v_add_u32_e32 v155, s61, v149
	s_add_i32 s62, 0, 0x1c000
	ds_read_b128 v[144:147], v155
	ds_read_b128 v[156:159], v155 offset:1024
	ds_read_b128 v[160:163], v155 offset:2048
	ds_read_b128 v[164:167], v155 offset:3072
	v_add_u32_e32 v155, s62, v149
	ds_read_b128 v[168:171], v155
	ds_read_b128 v[172:175], v155 offset:1024
	ds_read_b128 v[178:181], v155 offset:2048
	ds_read_b128 v[182:185], v155 offset:3072
	s_add_u32 s18, s18, 0x100000
	s_addc_u32 s19, s19, 0
	s_mov_b32 m0, s36
	v_lshl_add_u64 v[226:227], s[18:19], 0, v[128:129]
	ds_read_b128 v[186:189], v153 offset:32768
	ds_read_b128 v[190:193], v153 offset:33792
	ds_read_b128 v[194:197], v153 offset:34816
	ds_read_b128 v[198:201], v153 offset:35840
	ds_read_b128 v[202:205], v153 offset:36864
	ds_read_b128 v[206:209], v153 offset:37888
	ds_read_b128 v[210:213], v153 offset:38912
	ds_read_b128 v[214:217], v153 offset:39936
	global_load_lds_dwordx4 v[226:227], off
	v_lshl_add_u64 v[226:227], s[18:19], 0, v[132:133]
	s_mov_b32 m0, s37
	s_nop 0
	global_load_lds_dwordx4 v[226:227], off
	s_waitcnt vmcnt(8)
	s_waitcnt lgkmcnt(0)
	s_barrier
	s_setprio 1
	s_waitcnt lgkmcnt(0)
	v_mfma_f32_16x16x32_bf16 v[124:127], v[144:147], v[186:189], v[124:127]
	v_mfma_f32_16x16x32_bf16 v[120:123], v[160:163], v[186:189], v[120:123]
	v_mfma_f32_16x16x32_bf16 v[108:111], v[144:147], v[194:197], v[108:111]
	v_mfma_f32_16x16x32_bf16 v[104:107], v[160:163], v[194:197], v[104:107]
	v_mfma_f32_16x16x32_bf16 v[92:95], v[144:147], v[202:205], v[92:95]
	v_mfma_f32_16x16x32_bf16 v[88:91], v[160:163], v[202:205], v[88:91]
	v_mfma_f32_16x16x32_bf16 v[76:79], v[144:147], v[210:213], v[76:79]
	v_mfma_f32_16x16x32_bf16 v[72:75], v[160:163], v[210:213], v[72:75]
	v_mfma_f32_16x16x32_bf16 v[124:127], v[156:159], v[190:193], v[124:127]
	v_mfma_f32_16x16x32_bf16 v[120:123], v[164:167], v[190:193], v[120:123]
	v_mfma_f32_16x16x32_bf16 v[108:111], v[156:159], v[198:201], v[108:111]
	v_mfma_f32_16x16x32_bf16 v[104:107], v[164:167], v[198:201], v[104:107]
	v_mfma_f32_16x16x32_bf16 v[92:95], v[156:159], v[206:209], v[92:95]
	v_mfma_f32_16x16x32_bf16 v[88:91], v[164:167], v[206:209], v[88:91]
	v_mfma_f32_16x16x32_bf16 v[76:79], v[156:159], v[214:217], v[76:79]
	v_mfma_f32_16x16x32_bf16 v[72:75], v[164:167], v[214:217], v[72:75]
	s_setprio 0
	s_setprio 1
	v_mfma_f32_16x16x32_bf16 v[116:119], v[168:171], v[186:189], v[116:119]
	v_mfma_f32_16x16x32_bf16 v[112:115], v[178:181], v[186:189], v[112:115]
	v_mfma_f32_16x16x32_bf16 v[100:103], v[168:171], v[194:197], v[100:103]
	v_mfma_f32_16x16x32_bf16 v[96:99], v[178:181], v[194:197], v[96:99]
	v_mfma_f32_16x16x32_bf16 v[84:87], v[168:171], v[202:205], v[84:87]
	v_mfma_f32_16x16x32_bf16 v[80:83], v[178:181], v[202:205], v[80:83]
	v_mfma_f32_16x16x32_bf16 v[68:71], v[168:171], v[210:213], v[68:71]
	v_mfma_f32_16x16x32_bf16 v[64:67], v[178:181], v[210:213], v[64:67]
	v_mfma_f32_16x16x32_bf16 v[116:119], v[172:175], v[190:193], v[116:119]
	v_mfma_f32_16x16x32_bf16 v[112:115], v[182:185], v[190:193], v[112:115]
	v_mfma_f32_16x16x32_bf16 v[100:103], v[172:175], v[198:201], v[100:103]
	v_mfma_f32_16x16x32_bf16 v[96:99], v[182:185], v[198:201], v[96:99]
	v_mfma_f32_16x16x32_bf16 v[84:87], v[172:175], v[206:209], v[84:87]
	v_mfma_f32_16x16x32_bf16 v[80:83], v[182:185], v[206:209], v[80:83]
	v_mfma_f32_16x16x32_bf16 v[68:71], v[172:175], v[214:217], v[68:71]
	v_mfma_f32_16x16x32_bf16 v[64:67], v[182:185], v[214:217], v[64:67]
	s_setprio 0
	s_barrier
; #define PG8_STAGE(bufoff, gbase, voff) do { _Pragma("unroll") for (int _i = 0; _i < 2; ++_i) \
;         __builtin_amdgcn_global_load_lds((const unsigned*)((const char*)(gbase) + (voff)[_i]), (PG8_LAS unsigned*)(lds + (bufoff) + ldsw + _i * 8192), 16, 0, 0); } while (0)
; #define PG8_LDA(dst, b, h) do { _Pragma("unroll") for (int m = 0; m < 4; ++m) _Pragma("unroll") for (int k = 0; k < 2; ++k) dst[m][k] = *(const PG8_LAS bf16x8*)(lds + PG8_SA(b, h) + aoff + m * 2048 + k * 1024); } while (0)
; #define PG8_MMA(ai, bj, At, Bt) do { __builtin_amdgcn_s_setprio(1); _Pragma("unroll") for (int m = 0; m < 4; ++m) _Pragma("unroll") for (int n = 0; n < 2; ++n) _Pragma("unroll") for (int k = 0; k < 2; ++k) \
;         acc[ai][bj][m][n] = __builtin_amdgcn_mfma_f32_16x16x32_bf16(Bt[n][k], At[m][k], acc[ai][bj][m][n], 0, 0, 0); __builtin_amdgcn_s_setprio(0); } while (0)
; #define PG8_WAIT_V(n) asm volatile("s_waitcnt vmcnt(" #n ")" ::: "memory")
; #define PG8_WAIT_L(n) asm volatile("s_waitcnt lgkmcnt(" #n ")" ::: "memory")
; #define PG8_BAR __builtin_amdgcn_s_barrier()
; #define PG8_SCHED __builtin_amdgcn_sched_barrier(0)
; template <class Epi, class Sched, bool ALIGN_EPI = false, bool SP2 = false>
; __device__ __forceinline__ void gemm_phase(PG8_LAS unsigned char* lds, const Gemm g, const Sched& S, const Epi& E) {
;     ...
;         for (int t = 0; t < nt; t += 2) {
;     ...
;             PG8_LDA(At, 1, 1); PG8_STAGE(PG8_SB(1, 0), b3, voffB); PG8_STAGE(PG8_SB(1, 1), b3 + hstep, voffB); PG8_STAGE(PG8_SA(1, 0), a3, voffA);
;             PG8_WAIT_V(8); PG8_WAIT_L(0); PG8_BAR; PG8_MMA(1, 0, At, B0); PG8_MMA(1, 1, At, B1); PG8_BAR; PG8_SCHED;
	s_add_i32 s18, s61, s33
	v_lshl_add_u64 v[218:219], v[218:219], 0, s[10:11]
	s_mov_b32 m0, s18
	ds_read_b128 v[186:189], v153 offset:49152
	ds_read_b128 v[190:193], v153 offset:50176
	ds_read_b128 v[194:197], v153 offset:51200
	ds_read_b128 v[198:201], v153 offset:52224
	ds_read_b128 v[202:205], v153 offset:53248
	ds_read_b128 v[206:209], v153 offset:54272
	ds_read_b128 v[210:213], v153 offset:55296
	ds_read_b128 v[214:217], v153 offset:56320
	global_load_lds_dwordx4 v[218:219], off
	s_add_i32 m0, s18, 0x2000
	s_add_u32 s2, s2, 0x100080
	v_lshl_add_u64 v[218:219], v[220:221], 0, s[10:11]
	s_addc_u32 s3, s3, 0
	s_add_i32 s18, s62, s33
	global_load_lds_dwordx4 v[218:219], off
	v_lshl_add_u64 v[218:219], s[2:3], 0, v[130:131]
	s_mov_b32 m0, s18
	s_nop 0
	global_load_lds_dwordx4 v[218:219], off
	v_lshl_add_u64 v[218:219], s[2:3], 0, v[134:135]
	s_add_i32 m0, s18, 0x2000
	s_nop 0
	global_load_lds_dwordx4 v[218:219], off
	v_lshl_add_u64 v[218:219], v[222:223], 0, s[10:11]
	s_mov_b32 m0, s43
	s_nop 0
	global_load_lds_dwordx4 v[218:219], off
	v_lshl_add_u64 v[218:219], v[224:225], 0, s[10:11]
	s_mov_b32 m0, s46
	s_nop 0
	global_load_lds_dwordx4 v[218:219], off
	s_waitcnt vmcnt(8)
	s_waitcnt lgkmcnt(0)
	s_barrier
	s_setprio 1
	s_waitcnt lgkmcnt(0)
	v_mfma_f32_16x16x32_bf16 v[60:63], v[144:147], v[186:189], v[60:63]
	v_mfma_f32_16x16x32_bf16 v[56:59], v[160:163], v[186:189], v[56:59]
	v_mfma_f32_16x16x32_bf16 v[44:47], v[144:147], v[194:197], v[44:47]
	v_mfma_f32_16x16x32_bf16 v[40:43], v[160:163], v[194:197], v[40:43]
	v_mfma_f32_16x16x32_bf16 v[28:31], v[144:147], v[202:205], v[28:31]
	v_mfma_f32_16x16x32_bf16 v[24:27], v[160:163], v[202:205], v[24:27]
	v_mfma_f32_16x16x32_bf16 v[12:15], v[144:147], v[210:213], v[12:15]
	v_mfma_f32_16x16x32_bf16 v[8:11], v[160:163], v[210:213], v[8:11]
	v_mfma_f32_16x16x32_bf16 v[60:63], v[156:159], v[190:193], v[60:63]
	v_mfma_f32_16x16x32_bf16 v[56:59], v[164:167], v[190:193], v[56:59]
	v_mfma_f32_16x16x32_bf16 v[44:47], v[156:159], v[198:201], v[44:47]
	v_mfma_f32_16x16x32_bf16 v[40:43], v[164:167], v[198:201], v[40:43]
	v_mfma_f32_16x16x32_bf16 v[28:31], v[156:159], v[206:209], v[28:31]
	v_mfma_f32_16x16x32_bf16 v[24:27], v[164:167], v[206:209], v[24:27]
	v_mfma_f32_16x16x32_bf16 v[12:15], v[156:159], v[214:217], v[12:15]
	v_mfma_f32_16x16x32_bf16 v[8:11], v[164:167], v[214:217], v[8:11]
	s_setprio 0
	s_setprio 1
	v_mfma_f32_16x16x32_bf16 v[52:55], v[168:171], v[186:189], v[52:55]
	v_mfma_f32_16x16x32_bf16 v[48:51], v[178:181], v[186:189], v[48:51]
	v_mfma_f32_16x16x32_bf16 v[36:39], v[168:171], v[194:197], v[36:39]
	v_mfma_f32_16x16x32_bf16 v[32:35], v[178:181], v[194:197], v[32:35]
	v_mfma_f32_16x16x32_bf16 v[20:23], v[168:171], v[202:205], v[20:23]
	v_mfma_f32_16x16x32_bf16 v[16:19], v[178:181], v[202:205], v[16:19]
	v_mfma_f32_16x16x32_bf16 v[4:7], v[168:171], v[210:213], v[4:7]
	v_mfma_f32_16x16x32_bf16 v[0:3], v[178:181], v[210:213], v[0:3]
	v_mfma_f32_16x16x32_bf16 v[52:55], v[172:175], v[190:193], v[52:55]
	v_mfma_f32_16x16x32_bf16 v[48:51], v[182:185], v[190:193], v[48:51]
	v_mfma_f32_16x16x32_bf16 v[36:39], v[172:175], v[198:201], v[36:39]
	v_mfma_f32_16x16x32_bf16 v[32:35], v[182:185], v[198:201], v[32:35]
	v_mfma_f32_16x16x32_bf16 v[20:23], v[172:175], v[206:209], v[20:23]
	v_mfma_f32_16x16x32_bf16 v[16:19], v[182:185], v[206:209], v[16:19]
	v_mfma_f32_16x16x32_bf16 v[4:7], v[172:175], v[214:217], v[4:7]
	v_mfma_f32_16x16x32_bf16 v[0:3], v[182:185], v[214:217], v[0:3]
	s_setprio 0
	s_add_i32 s60, s60, 2
	s_add_u32 s28, s28, 0x100
	s_addc_u32 s29, s29, 0
	s_add_u32 s54, s54, 0x100
	s_addc_u32 s55, s55, 0
	s_cmp_gt_u32 s60, 61
	s_barrier
	s_cbranch_scc0 .LBB0_615
	s_and_b64 vcc, exec, s[12:13]
	s_cbranch_vccz .LBB0_618
	s_barrier

; #define PG8_STAGE(bufoff, gbase, voff) do { _Pragma("unroll") for (int _i = 0; _i < 2; ++_i) \
;         __builtin_amdgcn_global_load_lds((const unsigned*)((const char*)(gbase) + (voff)[_i]), (PG8_LAS unsigned*)(lds + (bufoff) + ldsw + _i * 8192), 16, 0, 0); } while (0)
; #define PG8_LDA(dst, b, h) do { _Pragma("unroll") for (int m = 0; m < 4; ++m) _Pragma("unroll") for (int k = 0; k < 2; ++k) dst[m][k] = *(const PG8_LAS bf16x8*)(lds + PG8_SA(b, h) + aoff + m * 2048 + k * 1024); } while (0)
; #define PG8_LDB(dst, b, h) do { _Pragma("unroll") for (int n = 0; n < 2; ++n) _Pragma("unroll") for (int k = 0; k < 2; ++k) dst[n][k] = *(const PG8_LAS bf16x8*)(lds + PG8_SB(b, h) + boff + n * 2048 + k * 1024); } while (0)
; #define PG8_MMA(ai, bj, At, Bt) do { __builtin_amdgcn_s_setprio(1); _Pragma("unroll") for (int m = 0; m < 4; ++m) _Pragma("unroll") for (int n = 0; n < 2; ++n) _Pragma("unroll") for (int k = 0; k < 2; ++k) \
;         acc[ai][bj][m][n] = __builtin_amdgcn_mfma_f32_16x16x32_bf16(Bt[n][k], At[m][k], acc[ai][bj][m][n], 0, 0, 0); __builtin_amdgcn_s_setprio(0); } while (0)
; #define PG8_WAIT_V(n) asm volatile("s_waitcnt vmcnt(" #n ")" ::: "memory")
; #define PG8_WAIT_L(n) asm volatile("s_waitcnt lgkmcnt(" #n ")" ::: "memory")
; #define PG8_BAR __builtin_amdgcn_s_barrier()
; #define PG8_SCHED __builtin_amdgcn_sched_barrier(0)
; template <class Epi, class Sched, bool ALIGN_EPI = false, bool SP2 = false>
; __device__ __forceinline__ void gemm_phase(PG8_LAS unsigned char* lds, const Gemm g, const Sched& S, const Epi& E) {
;     ...
;             PG8_LDB(B0, 0, 0); PG8_LDB(B1, 0, 1); PG8_SCHED; PG8_LDA(At, 0, 0); PG8_STAGE(PG8_SA(1, 1), a1 + hstep, voffA);
;             PG8_WAIT_V(8); PG8_WAIT_L(0); PG8_BAR; PG8_MMA(0, 0, At, B0); PG8_MMA(0, 1, At, B1); PG8_BAR; PG8_SCHED;
;             PG8_LDA(At, 0, 1); PG8_STAGE(PG8_SB(0, 0), b2, voffB); PG8_STAGE(PG8_SB(0, 1), b2 + hstep, voffB); PG8_STAGE(PG8_SA(0, 0), a2, voffA);
;             PG8_WAIT_V(8); PG8_WAIT_L(0); PG8_BAR; PG8_MMA(1, 0, At, B0); PG8_MMA(1, 1, At, B1); PG8_BAR; PG8_SCHED;
.LBB0_727:
	s_waitcnt lgkmcnt(0)
	ds_read_b128 v[140:143], v193
	ds_read_b128 v[152:155], v193 offset:1024
	ds_read_b128 v[156:159], v193 offset:2048
	ds_read_b128 v[160:163], v193 offset:3072
	ds_read_b128 v[164:167], v194
	ds_read_b128 v[168:171], v194 offset:1024
	ds_read_b128 v[172:175], v194 offset:2048
	ds_read_b128 v[196:199], v194 offset:3072
	s_add_u32 s2, s28, 0xfffc0080
	s_addc_u32 s3, s29, -1
	s_cmp_eq_u32 s63, 12
	s_cselect_b32 s19, s15, s3
	s_cselect_b32 s18, s55, s2
	s_cselect_b32 s3, s13, s62
	s_cselect_b32 s2, s60, s61
	v_lshl_add_u64 v[232:233], s[28:29], 0, v[132:133]
	s_add_i32 m0, s25, 0xc000
	ds_read_b128 v[200:203], v195
	ds_read_b128 v[204:207], v195 offset:1024
	ds_read_b128 v[208:211], v195 offset:2048
	ds_read_b128 v[212:215], v195 offset:3072
	ds_read_b128 v[216:219], v195 offset:4096
	ds_read_b128 v[220:223], v195 offset:5120
	ds_read_b128 v[224:227], v195 offset:6144
	ds_read_b128 v[228:231], v195 offset:7168
	global_load_lds_dwordx4 v[232:233], off
	v_lshl_add_u64 v[232:233], s[28:29], 0, v[134:135]
	s_add_i32 m0, s25, 0xe000
	s_nop 0
	global_load_lds_dwordx4 v[232:233], off
	s_waitcnt vmcnt(8)
	s_waitcnt lgkmcnt(0)
	s_barrier
	s_setprio 1
	s_waitcnt lgkmcnt(0)
	v_mfma_f32_16x16x32_bf16 v[124:127], v[140:143], v[200:203], v[124:127]
	v_mfma_f32_16x16x32_bf16 v[120:123], v[156:159], v[200:203], v[120:123]
	v_mfma_f32_16x16x32_bf16 v[108:111], v[140:143], v[208:211], v[108:111]
	v_mfma_f32_16x16x32_bf16 v[104:107], v[156:159], v[208:211], v[104:107]
	v_mfma_f32_16x16x32_bf16 v[92:95], v[140:143], v[216:219], v[92:95]
	v_mfma_f32_16x16x32_bf16 v[88:91], v[156:159], v[216:219], v[88:91]
	v_mfma_f32_16x16x32_bf16 v[76:79], v[140:143], v[224:227], v[76:79]
	v_mfma_f32_16x16x32_bf16 v[72:75], v[156:159], v[224:227], v[72:75]
	v_mfma_f32_16x16x32_bf16 v[124:127], v[152:155], v[204:207], v[124:127]
	v_mfma_f32_16x16x32_bf16 v[120:123], v[160:163], v[204:207], v[120:123]
	v_mfma_f32_16x16x32_bf16 v[108:111], v[152:155], v[212:215], v[108:111]
	v_mfma_f32_16x16x32_bf16 v[104:107], v[160:163], v[212:215], v[104:107]
	v_mfma_f32_16x16x32_bf16 v[92:95], v[152:155], v[220:223], v[92:95]
	v_mfma_f32_16x16x32_bf16 v[88:91], v[160:163], v[220:223], v[88:91]
	v_mfma_f32_16x16x32_bf16 v[76:79], v[152:155], v[228:231], v[76:79]
	v_mfma_f32_16x16x32_bf16 v[72:75], v[160:163], v[228:231], v[72:75]
	s_setprio 0
	s_setprio 1
	v_mfma_f32_16x16x32_bf16 v[116:119], v[164:167], v[200:203], v[116:119]
	v_mfma_f32_16x16x32_bf16 v[112:115], v[172:175], v[200:203], v[112:115]
	v_mfma_f32_16x16x32_bf16 v[100:103], v[164:167], v[208:211], v[100:103]
	v_mfma_f32_16x16x32_bf16 v[96:99], v[172:175], v[208:211], v[96:99]
	v_mfma_f32_16x16x32_bf16 v[84:87], v[164:167], v[216:219], v[84:87]
	v_mfma_f32_16x16x32_bf16 v[80:83], v[172:175], v[216:219], v[80:83]
	v_mfma_f32_16x16x32_bf16 v[68:71], v[164:167], v[224:227], v[68:71]
	v_mfma_f32_16x16x32_bf16 v[64:67], v[172:175], v[224:227], v[64:67]
	v_mfma_f32_16x16x32_bf16 v[116:119], v[168:171], v[204:207], v[116:119]
	v_mfma_f32_16x16x32_bf16 v[112:115], v[196:199], v[204:207], v[112:115]
	v_mfma_f32_16x16x32_bf16 v[100:103], v[168:171], v[212:215], v[100:103]
	v_mfma_f32_16x16x32_bf16 v[96:99], v[196:199], v[212:215], v[96:99]
	v_mfma_f32_16x16x32_bf16 v[84:87], v[168:171], v[220:223], v[84:87]
	v_mfma_f32_16x16x32_bf16 v[80:83], v[196:199], v[220:223], v[80:83]
	v_mfma_f32_16x16x32_bf16 v[68:71], v[168:171], v[228:231], v[68:71]
	v_mfma_f32_16x16x32_bf16 v[64:67], v[196:199], v[228:231], v[64:67]
	s_setprio 0
	s_barrier
	s_add_i32 s64, s52, s35
	v_lshl_add_u64 v[232:233], s[2:3], 0, v[146:147]
	s_mov_b32 m0, s64
	ds_read_b128 v[200:203], v195 offset:16384
	ds_read_b128 v[204:207], v195 offset:17408
	ds_read_b128 v[208:211], v195 offset:18432
	ds_read_b128 v[212:215], v195 offset:19456
	ds_read_b128 v[216:219], v195 offset:20480
	ds_read_b128 v[220:223], v195 offset:21504
	ds_read_b128 v[224:227], v195 offset:22528
	ds_read_b128 v[228:231], v195 offset:23552
	global_load_lds_dwordx4 v[232:233], off
	s_add_i32 m0, s64, 0x2000
	s_add_u32 s64, s2, 0x40000
	v_lshl_add_u64 v[234:235], s[2:3], 0, v[150:151]
	s_addc_u32 s65, s3, 0
	s_add_i32 s66, s53, s35
	global_load_lds_dwordx4 v[234:235], off
	v_lshl_add_u64 v[236:237], s[64:65], 0, v[146:147]
	s_mov_b32 m0, s66
	v_lshl_add_u64 v[238:239], s[18:19], 0, v[148:149]
	global_load_lds_dwordx4 v[236:237], off
	v_lshl_add_u64 v[236:237], s[64:65], 0, v[150:151]
	s_add_i32 m0, s66, 0x2000
	s_nop 0
	global_load_lds_dwordx4 v[236:237], off
	v_lshl_add_u64 v[236:237], s[18:19], 0, v[144:145]
	s_mov_b32 m0, s25
	s_nop 0
	global_load_lds_dwordx4 v[236:237], off
	s_mov_b32 m0, s27
	s_nop 0
	global_load_lds_dwordx4 v[238:239], off
	s_waitcnt vmcnt(8)
	s_waitcnt lgkmcnt(0)
	s_barrier
; #define PG8_STAGE(bufoff, gbase, voff) do { _Pragma("unroll") for (int _i = 0; _i < 2; ++_i) \
;         __builtin_amdgcn_global_load_lds((const unsigned*)((const char*)(gbase) + (voff)[_i]), (PG8_LAS unsigned*)(lds + (bufoff) + ldsw + _i * 8192), 16, 0, 0); } while (0)
; #define PG8_LDA(dst, b, h) do { _Pragma("unroll") for (int m = 0; m < 4; ++m) _Pragma("unroll") for (int k = 0; k < 2; ++k) dst[m][k] = *(const PG8_LAS bf16x8*)(lds + PG8_SA(b, h) + aoff + m * 2048 + k * 1024); } while (0)
; #define PG8_LDB(dst, b, h) do { _Pragma("unroll") for (int n = 0; n < 2; ++n) _Pragma("unroll") for (int k = 0; k < 2; ++k) dst[n][k] = *(const PG8_LAS bf16x8*)(lds + PG8_SB(b, h) + boff + n * 2048 + k * 1024); } while (0)
; #define PG8_MMA(ai, bj, At, Bt) do { __builtin_amdgcn_s_setprio(1); _Pragma("unroll") for (int m = 0; m < 4; ++m) _Pragma("unroll") for (int n = 0; n < 2; ++n) _Pragma("unroll") for (int k = 0; k < 2; ++k) \
;         acc[ai][bj][m][n] = __builtin_amdgcn_mfma_f32_16x16x32_bf16(Bt[n][k], At[m][k], acc[ai][bj][m][n], 0, 0, 0); __builtin_amdgcn_s_setprio(0); } while (0)
; #define PG8_WAIT_V(n) asm volatile("s_waitcnt vmcnt(" #n ")" ::: "memory")
; #define PG8_WAIT_L(n) asm volatile("s_waitcnt lgkmcnt(" #n ")" ::: "memory")
; #define PG8_BAR __builtin_amdgcn_s_barrier()
; #define PG8_SCHED __builtin_amdgcn_sched_barrier(0)
; template <class Epi, class Sched, bool ALIGN_EPI = false, bool SP2 = false>
; __device__ __forceinline__ void gemm_phase(PG8_LAS unsigned char* lds, const Gemm g, const Sched& S, const Epi& E) {
;     ...
;             PG8_WAIT_V(8); PG8_WAIT_L(0); PG8_BAR; PG8_MMA(1, 0, At, B0); PG8_MMA(1, 1, At, B1); PG8_BAR; PG8_SCHED;
;             PG8_LDB(B0, 1, 0); PG8_LDB(B1, 1, 1); PG8_SCHED; PG8_LDA(At, 1, 0); PG8_STAGE(PG8_SA(0, 1), a2 + hstep, voffA);
;             PG8_WAIT_V(8); PG8_WAIT_L(0); PG8_BAR; PG8_MMA(0, 0, At, B0); PG8_MMA(0, 1, At, B1); PG8_BAR; PG8_SCHED;
	s_setprio 1
	s_waitcnt lgkmcnt(0)
	v_mfma_f32_16x16x32_bf16 v[60:63], v[140:143], v[200:203], v[60:63]
	v_mfma_f32_16x16x32_bf16 v[56:59], v[156:159], v[200:203], v[56:59]
	v_mfma_f32_16x16x32_bf16 v[44:47], v[140:143], v[208:211], v[44:47]
	v_mfma_f32_16x16x32_bf16 v[40:43], v[156:159], v[208:211], v[40:43]
	v_mfma_f32_16x16x32_bf16 v[28:31], v[140:143], v[216:219], v[28:31]
	v_mfma_f32_16x16x32_bf16 v[24:27], v[156:159], v[216:219], v[24:27]
	v_mfma_f32_16x16x32_bf16 v[12:15], v[140:143], v[224:227], v[12:15]
	v_mfma_f32_16x16x32_bf16 v[8:11], v[156:159], v[224:227], v[8:11]
	v_mfma_f32_16x16x32_bf16 v[60:63], v[152:155], v[204:207], v[60:63]
	v_mfma_f32_16x16x32_bf16 v[56:59], v[160:163], v[204:207], v[56:59]
	v_mfma_f32_16x16x32_bf16 v[44:47], v[152:155], v[212:215], v[44:47]
	v_mfma_f32_16x16x32_bf16 v[40:43], v[160:163], v[212:215], v[40:43]
	v_mfma_f32_16x16x32_bf16 v[28:31], v[152:155], v[220:223], v[28:31]
	v_mfma_f32_16x16x32_bf16 v[24:27], v[160:163], v[220:223], v[24:27]
	v_mfma_f32_16x16x32_bf16 v[12:15], v[152:155], v[228:231], v[12:15]
	v_mfma_f32_16x16x32_bf16 v[8:11], v[160:163], v[228:231], v[8:11]
	s_setprio 0
	s_setprio 1
	v_mfma_f32_16x16x32_bf16 v[52:55], v[164:167], v[200:203], v[52:55]
	v_mfma_f32_16x16x32_bf16 v[48:51], v[172:175], v[200:203], v[48:51]
	v_mfma_f32_16x16x32_bf16 v[36:39], v[164:167], v[208:211], v[36:39]
	v_mfma_f32_16x16x32_bf16 v[32:35], v[172:175], v[208:211], v[32:35]
	v_mfma_f32_16x16x32_bf16 v[20:23], v[164:167], v[216:219], v[20:23]
	v_mfma_f32_16x16x32_bf16 v[16:19], v[172:175], v[216:219], v[16:19]
	v_mfma_f32_16x16x32_bf16 v[4:7], v[164:167], v[224:227], v[4:7]
	v_mfma_f32_16x16x32_bf16 v[0:3], v[172:175], v[224:227], v[0:3]
	v_mfma_f32_16x16x32_bf16 v[52:55], v[168:171], v[204:207], v[52:55]
	v_mfma_f32_16x16x32_bf16 v[48:51], v[196:199], v[204:207], v[48:51]
	v_mfma_f32_16x16x32_bf16 v[36:39], v[168:171], v[212:215], v[36:39]
	v_mfma_f32_16x16x32_bf16 v[32:35], v[196:199], v[212:215], v[32:35]
	v_mfma_f32_16x16x32_bf16 v[20:23], v[168:171], v[220:223], v[20:23]
	v_mfma_f32_16x16x32_bf16 v[16:19], v[196:199], v[220:223], v[16:19]
	v_mfma_f32_16x16x32_bf16 v[4:7], v[168:171], v[228:231], v[4:7]
	v_mfma_f32_16x16x32_bf16 v[0:3], v[196:199], v[228:231], v[0:3]
	s_setprio 0
	s_barrier
	s_add_i32 s64, 0, 0x18000
	s_add_i32 s65, 0, 0x1c000
	v_add_u32_e32 v160, s64, v191
	v_add_u32_e32 v196, s65, v191
	ds_read_b128 v[140:143], v160
	ds_read_b128 v[152:155], v160 offset:1024
	ds_read_b128 v[156:159], v160 offset:2048
	ds_read_b128 v[160:163], v160 offset:3072
	ds_read_b128 v[164:167], v196
	ds_read_b128 v[168:171], v196 offset:1024
	ds_read_b128 v[172:175], v196 offset:2048
	ds_read_b128 v[196:199], v196 offset:3072
	s_add_u32 s18, s18, 0x40000
	s_addc_u32 s19, s19, 0
	s_mov_b32 m0, s36
	v_lshl_add_u64 v[240:241], s[18:19], 0, v[144:145]
	ds_read_b128 v[200:203], v195 offset:32768
	ds_read_b128 v[204:207], v195 offset:33792
	ds_read_b128 v[208:211], v195 offset:34816
	ds_read_b128 v[212:215], v195 offset:35840
	ds_read_b128 v[216:219], v195 offset:36864
	ds_read_b128 v[220:223], v195 offset:37888
	ds_read_b128 v[224:227], v195 offset:38912
	ds_read_b128 v[228:231], v195 offset:39936
	global_load_lds_dwordx4 v[240:241], off
	v_lshl_add_u64 v[240:241], s[18:19], 0, v[148:149]
	s_mov_b32 m0, s37
	s_nop 0
	global_load_lds_dwordx4 v[240:241], off
	s_waitcnt vmcnt(8)
	s_waitcnt lgkmcnt(0)
	s_barrier
	s_setprio 1
	s_waitcnt lgkmcnt(0)
	v_mfma_f32_16x16x32_bf16 v[124:127], v[140:143], v[200:203], v[124:127]
	v_mfma_f32_16x16x32_bf16 v[120:123], v[156:159], v[200:203], v[120:123]
	v_mfma_f32_16x16x32_bf16 v[108:111], v[140:143], v[208:211], v[108:111]
	v_mfma_f32_16x16x32_bf16 v[104:107], v[156:159], v[208:211], v[104:107]
	v_mfma_f32_16x16x32_bf16 v[92:95], v[140:143], v[216:219], v[92:95]
	v_mfma_f32_16x16x32_bf16 v[88:91], v[156:159], v[216:219], v[88:91]
	v_mfma_f32_16x16x32_bf16 v[76:79], v[140:143], v[224:227], v[76:79]
	v_mfma_f32_16x16x32_bf16 v[72:75], v[156:159], v[224:227], v[72:75]
	v_mfma_f32_16x16x32_bf16 v[124:127], v[152:155], v[204:207], v[124:127]
	v_mfma_f32_16x16x32_bf16 v[120:123], v[160:163], v[204:207], v[120:123]
	v_mfma_f32_16x16x32_bf16 v[108:111], v[152:155], v[212:215], v[108:111]
	v_mfma_f32_16x16x32_bf16 v[104:107], v[160:163], v[212:215], v[104:107]
	v_mfma_f32_16x16x32_bf16 v[92:95], v[152:155], v[220:223], v[92:95]
	v_mfma_f32_16x16x32_bf16 v[88:91], v[160:163], v[220:223], v[88:91]
	v_mfma_f32_16x16x32_bf16 v[76:79], v[152:155], v[228:231], v[76:79]
	v_mfma_f32_16x16x32_bf16 v[72:75], v[160:163], v[228:231], v[72:75]
	s_setprio 0
	s_setprio 1
	v_mfma_f32_16x16x32_bf16 v[116:119], v[164:167], v[200:203], v[116:119]
	v_mfma_f32_16x16x32_bf16 v[112:115], v[172:175], v[200:203], v[112:115]
	v_mfma_f32_16x16x32_bf16 v[100:103], v[164:167], v[208:211], v[100:103]
	v_mfma_f32_16x16x32_bf16 v[96:99], v[172:175], v[208:211], v[96:99]
	v_mfma_f32_16x16x32_bf16 v[84:87], v[164:167], v[216:219], v[84:87]
	v_mfma_f32_16x16x32_bf16 v[80:83], v[172:175], v[216:219], v[80:83]
	v_mfma_f32_16x16x32_bf16 v[68:71], v[164:167], v[224:227], v[68:71]
	v_mfma_f32_16x16x32_bf16 v[64:67], v[172:175], v[224:227], v[64:67]
	v_mfma_f32_16x16x32_bf16 v[116:119], v[168:171], v[204:207], v[116:119]
	v_mfma_f32_16x16x32_bf16 v[112:115], v[196:199], v[204:207], v[112:115]
	v_mfma_f32_16x16x32_bf16 v[100:103], v[168:171], v[212:215], v[100:103]
	v_mfma_f32_16x16x32_bf16 v[96:99], v[196:199], v[212:215], v[96:99]
	v_mfma_f32_16x16x32_bf16 v[84:87], v[168:171], v[220:223], v[84:87]
	v_mfma_f32_16x16x32_bf16 v[80:83], v[196:199], v[220:223], v[80:83]
	v_mfma_f32_16x16x32_bf16 v[68:71], v[168:171], v[228:231], v[68:71]
	v_mfma_f32_16x16x32_bf16 v[64:67], v[196:199], v[228:231], v[64:67]
	s_setprio 0
	s_barrier
; #define PG8_STAGE(bufoff, gbase, voff) do { _Pragma("unroll") for (int _i = 0; _i < 2; ++_i) \
;         __builtin_amdgcn_global_load_lds((const unsigned*)((const char*)(gbase) + (voff)[_i]), (PG8_LAS unsigned*)(lds + (bufoff) + ldsw + _i * 8192), 16, 0, 0); } while (0)
; #define PG8_LDA(dst, b, h) do { _Pragma("unroll") for (int m = 0; m < 4; ++m) _Pragma("unroll") for (int k = 0; k < 2; ++k) dst[m][k] = *(const PG8_LAS bf16x8*)(lds + PG8_SA(b, h) + aoff + m * 2048 + k * 1024); } while (0)
; #define PG8_MMA(ai, bj, At, Bt) do { __builtin_amdgcn_s_setprio(1); _Pragma("unroll") for (int m = 0; m < 4; ++m) _Pragma("unroll") for (int n = 0; n < 2; ++n) _Pragma("unroll") for (int k = 0; k < 2; ++k) \
;         acc[ai][bj][m][n] = __builtin_amdgcn_mfma_f32_16x16x32_bf16(Bt[n][k], At[m][k], acc[ai][bj][m][n], 0, 0, 0); __builtin_amdgcn_s_setprio(0); } while (0)
; #define PG8_WAIT_V(n) asm volatile("s_waitcnt vmcnt(" #n ")" ::: "memory")
; #define PG8_WAIT_L(n) asm volatile("s_waitcnt lgkmcnt(" #n ")" ::: "memory")
; #define PG8_BAR __builtin_amdgcn_s_barrier()
; #define PG8_SCHED __builtin_amdgcn_sched_barrier(0)
; template <class Epi, class Sched, bool ALIGN_EPI = false, bool SP2 = false>
; __device__ __forceinline__ void gemm_phase(PG8_LAS unsigned char* lds, const Gemm g, const Sched& S, const Epi& E) {
;     ...
;         for (int t = 0; t < nt; t += 2) {
;     ...
;             PG8_LDA(At, 1, 1); PG8_STAGE(PG8_SB(1, 0), b3, voffB); PG8_STAGE(PG8_SB(1, 1), b3 + hstep, voffB); PG8_STAGE(PG8_SA(1, 0), a3, voffA);
;             PG8_WAIT_V(8); PG8_WAIT_L(0); PG8_BAR; PG8_MMA(1, 0, At, B0); PG8_MMA(1, 1, At, B1); PG8_BAR; PG8_SCHED;
	s_add_i32 s18, s64, s35
	v_lshl_add_u64 v[232:233], v[232:233], 0, s[8:9]
	s_mov_b32 m0, s18
	ds_read_b128 v[200:203], v195 offset:49152
	ds_read_b128 v[204:207], v195 offset:50176
	ds_read_b128 v[208:211], v195 offset:51200
	ds_read_b128 v[212:215], v195 offset:52224
	ds_read_b128 v[216:219], v195 offset:53248
	ds_read_b128 v[220:223], v195 offset:54272
	ds_read_b128 v[224:227], v195 offset:55296
	ds_read_b128 v[228:231], v195 offset:56320
	global_load_lds_dwordx4 v[232:233], off
	s_add_i32 m0, s18, 0x2000
	s_add_u32 s2, s2, 0x40080
	v_lshl_add_u64 v[232:233], v[234:235], 0, s[8:9]
	s_addc_u32 s3, s3, 0
	s_add_i32 s18, s65, s35
	global_load_lds_dwordx4 v[232:233], off
	v_lshl_add_u64 v[232:233], s[2:3], 0, v[146:147]
	s_mov_b32 m0, s18
	s_nop 0
	global_load_lds_dwordx4 v[232:233], off
	v_lshl_add_u64 v[232:233], s[2:3], 0, v[150:151]
	s_add_i32 m0, s18, 0x2000
	s_nop 0
	global_load_lds_dwordx4 v[232:233], off
	v_lshl_add_u64 v[232:233], v[236:237], 0, s[8:9]
	s_mov_b32 m0, s46
	s_nop 0
	global_load_lds_dwordx4 v[232:233], off
	v_lshl_add_u64 v[232:233], v[238:239], 0, s[8:9]
	s_mov_b32 m0, s47
	s_nop 0
	global_load_lds_dwordx4 v[232:233], off
	s_waitcnt vmcnt(8)
	s_waitcnt lgkmcnt(0)
	s_barrier
	s_setprio 1
	s_waitcnt lgkmcnt(0)
	v_mfma_f32_16x16x32_bf16 v[60:63], v[140:143], v[200:203], v[60:63]
	v_mfma_f32_16x16x32_bf16 v[56:59], v[156:159], v[200:203], v[56:59]
	v_mfma_f32_16x16x32_bf16 v[44:47], v[140:143], v[208:211], v[44:47]
	v_mfma_f32_16x16x32_bf16 v[40:43], v[156:159], v[208:211], v[40:43]
	v_mfma_f32_16x16x32_bf16 v[28:31], v[140:143], v[216:219], v[28:31]
	v_mfma_f32_16x16x32_bf16 v[24:27], v[156:159], v[216:219], v[24:27]
	v_mfma_f32_16x16x32_bf16 v[12:15], v[140:143], v[224:227], v[12:15]
	v_mfma_f32_16x16x32_bf16 v[8:11], v[156:159], v[224:227], v[8:11]
	v_mfma_f32_16x16x32_bf16 v[60:63], v[152:155], v[204:207], v[60:63]
	v_mfma_f32_16x16x32_bf16 v[56:59], v[160:163], v[204:207], v[56:59]
	v_mfma_f32_16x16x32_bf16 v[44:47], v[152:155], v[212:215], v[44:47]
	v_mfma_f32_16x16x32_bf16 v[40:43], v[160:163], v[212:215], v[40:43]
	v_mfma_f32_16x16x32_bf16 v[28:31], v[152:155], v[220:223], v[28:31]
	v_mfma_f32_16x16x32_bf16 v[24:27], v[160:163], v[220:223], v[24:27]
	v_mfma_f32_16x16x32_bf16 v[12:15], v[152:155], v[228:231], v[12:15]
	v_mfma_f32_16x16x32_bf16 v[8:11], v[160:163], v[228:231], v[8:11]
	s_setprio 0
	s_setprio 1
	v_mfma_f32_16x16x32_bf16 v[52:55], v[164:167], v[200:203], v[52:55]
	v_mfma_f32_16x16x32_bf16 v[48:51], v[172:175], v[200:203], v[48:51]
	v_mfma_f32_16x16x32_bf16 v[36:39], v[164:167], v[208:211], v[36:39]
	v_mfma_f32_16x16x32_bf16 v[32:35], v[172:175], v[208:211], v[32:35]
	v_mfma_f32_16x16x32_bf16 v[20:23], v[164:167], v[216:219], v[20:23]
	v_mfma_f32_16x16x32_bf16 v[16:19], v[172:175], v[216:219], v[16:19]
	v_mfma_f32_16x16x32_bf16 v[4:7], v[164:167], v[224:227], v[4:7]
	v_mfma_f32_16x16x32_bf16 v[0:3], v[172:175], v[224:227], v[0:3]
	v_mfma_f32_16x16x32_bf16 v[52:55], v[168:171], v[204:207], v[52:55]
	v_mfma_f32_16x16x32_bf16 v[48:51], v[196:199], v[204:207], v[48:51]
	v_mfma_f32_16x16x32_bf16 v[36:39], v[168:171], v[212:215], v[36:39]
	v_mfma_f32_16x16x32_bf16 v[32:35], v[196:199], v[212:215], v[32:35]
	v_mfma_f32_16x16x32_bf16 v[20:23], v[168:171], v[220:223], v[20:23]
	v_mfma_f32_16x16x32_bf16 v[16:19], v[196:199], v[220:223], v[16:19]
	v_mfma_f32_16x16x32_bf16 v[4:7], v[168:171], v[228:231], v[4:7]
	v_mfma_f32_16x16x32_bf16 v[0:3], v[196:199], v[228:231], v[0:3]
	s_setprio 0
	s_add_i32 s63, s63, 2
	s_add_u32 s28, s28, 0x100
	s_addc_u32 s29, s29, 0
	s_add_u32 s61, s61, 0x100
	s_addc_u32 s62, s62, 0
	s_cmp_gt_u32 s63, 13
	s_barrier
	s_cbranch_scc0 .LBB0_727
	s_and_b64 vcc, exec, s[10:11]
	s_cbranch_vccz .LBB0_730
	s_barrier

; #define PG8_STAGE(bufoff, gbase, voff) do { _Pragma("unroll") for (int _i = 0; _i < 2; ++_i) \
;         __builtin_amdgcn_global_load_lds((const unsigned*)((const char*)(gbase) + (voff)[_i]), (PG8_LAS unsigned*)(lds + (bufoff) + ldsw + _i * 8192), 16, 0, 0); } while (0)
; #define PG8_LDA(dst, b, h) do { _Pragma("unroll") for (int m = 0; m < 4; ++m) _Pragma("unroll") for (int k = 0; k < 2; ++k) dst[m][k] = *(const PG8_LAS bf16x8*)(lds + PG8_SA(b, h) + aoff + m * 2048 + k * 1024); } while (0)
; #define PG8_LDB(dst, b, h) do { _Pragma("unroll") for (int n = 0; n < 2; ++n) _Pragma("unroll") for (int k = 0; k < 2; ++k) dst[n][k] = *(const PG8_LAS bf16x8*)(lds + PG8_SB(b, h) + boff + n * 2048 + k * 1024); } while (0)
; #define PG8_MMA(ai, bj, At, Bt) do { __builtin_amdgcn_s_setprio(1); _Pragma("unroll") for (int m = 0; m < 4; ++m) _Pragma("unroll") for (int n = 0; n < 2; ++n) _Pragma("unroll") for (int k = 0; k < 2; ++k) \
;         acc[ai][bj][m][n] = __builtin_amdgcn_mfma_f32_16x16x32_bf16(Bt[n][k], At[m][k], acc[ai][bj][m][n], 0, 0, 0); __builtin_amdgcn_s_setprio(0); } while (0)
; #define PG8_WAIT_V(n) asm volatile("s_waitcnt vmcnt(" #n ")" ::: "memory")
; #define PG8_WAIT_L(n) asm volatile("s_waitcnt lgkmcnt(" #n ")" ::: "memory")
; #define PG8_BAR __builtin_amdgcn_s_barrier()
; #define PG8_SCHED __builtin_amdgcn_sched_barrier(0)
; template <class Epi, class Sched, bool ALIGN_EPI = false, bool SP2 = false>
; __device__ __forceinline__ void gemm_phase(PG8_LAS unsigned char* lds, const Gemm g, const Sched& S, const Epi& E) {
;     ...
;             PG8_LDB(B0, 0, 0); PG8_LDB(B1, 0, 1); PG8_SCHED; PG8_LDA(At, 0, 0); PG8_STAGE(PG8_SA(1, 1), a1 + hstep, voffA);
;             PG8_WAIT_V(8); PG8_WAIT_L(0); PG8_BAR; PG8_MMA(0, 0, At, B0); PG8_MMA(0, 1, At, B1); PG8_BAR; PG8_SCHED;
;             PG8_LDA(At, 0, 1); PG8_STAGE(PG8_SB(0, 0), b2, voffB); PG8_STAGE(PG8_SB(0, 1), b2 + hstep, voffB); PG8_STAGE(PG8_SA(0, 0), a2, voffA);
;             PG8_WAIT_V(8); PG8_WAIT_L(0); PG8_BAR; PG8_MMA(1, 0, At, B0); PG8_MMA(1, 1, At, B1); PG8_BAR; PG8_SCHED;
.LBB0_819:
	ds_read_b128 v[128:131], v161
	ds_read_b128 v[132:135], v161 offset:1024
	ds_read_b128 v[136:139], v161 offset:2048
	s_waitcnt lgkmcnt(0)
	ds_read_b128 v[140:143], v161 offset:3072
	ds_read_b128 v[166:169], v162
	ds_read_b128 v[170:173], v162 offset:1024
	ds_read_b128 v[180:183], v162 offset:2048
	ds_read_b128 v[184:187], v162 offset:3072
	s_add_u32 s2, s24, 0xfffc0080
	s_addc_u32 s3, s25, -1
	s_cmp_eq_u32 s53, 12
	s_cselect_b32 s19, s13, s3
	s_cselect_b32 s18, s49, s2
	s_cselect_b32 s3, s11, s52
	s_cselect_b32 s2, s50, s51
	v_lshl_add_u64 v[174:175], s[24:25], 0, v[152:153]
	s_add_i32 m0, s23, 0xc000
	ds_read_b128 v[188:191], v163
	ds_read_b128 v[192:195], v163 offset:1024
	ds_read_b128 v[196:199], v163 offset:2048
	ds_read_b128 v[200:203], v163 offset:3072
	ds_read_b128 v[204:207], v163 offset:4096
	ds_read_b128 v[208:211], v163 offset:5120
	ds_read_b128 v[212:215], v163 offset:6144
	ds_read_b128 v[216:219], v163 offset:7168
	global_load_lds_dwordx4 v[174:175], off
	v_lshl_add_u64 v[174:175], s[24:25], 0, v[154:155]
	s_add_i32 m0, s23, 0xe000
	s_nop 0
	global_load_lds_dwordx4 v[174:175], off
	s_waitcnt vmcnt(8)
	s_waitcnt lgkmcnt(0)
	s_barrier
	s_setprio 1
	s_waitcnt lgkmcnt(0)
	v_mfma_f32_16x16x32_bf16 v[124:127], v[128:131], v[188:191], v[124:127]
	v_mfma_f32_16x16x32_bf16 v[120:123], v[136:139], v[188:191], v[120:123]
	v_mfma_f32_16x16x32_bf16 v[116:119], v[128:131], v[196:199], v[116:119]
	v_mfma_f32_16x16x32_bf16 v[112:115], v[136:139], v[196:199], v[112:115]
	v_mfma_f32_16x16x32_bf16 v[100:103], v[128:131], v[204:207], v[100:103]
	v_mfma_f32_16x16x32_bf16 v[92:95], v[136:139], v[204:207], v[92:95]
	v_mfma_f32_16x16x32_bf16 v[84:87], v[128:131], v[212:215], v[84:87]
	v_mfma_f32_16x16x32_bf16 v[76:79], v[136:139], v[212:215], v[76:79]
	v_mfma_f32_16x16x32_bf16 v[124:127], v[132:135], v[192:195], v[124:127]
	v_mfma_f32_16x16x32_bf16 v[120:123], v[140:143], v[192:195], v[120:123]
	v_mfma_f32_16x16x32_bf16 v[116:119], v[132:135], v[200:203], v[116:119]
	v_mfma_f32_16x16x32_bf16 v[112:115], v[140:143], v[200:203], v[112:115]
	v_mfma_f32_16x16x32_bf16 v[100:103], v[132:135], v[208:211], v[100:103]
	v_mfma_f32_16x16x32_bf16 v[92:95], v[140:143], v[208:211], v[92:95]
	v_mfma_f32_16x16x32_bf16 v[84:87], v[132:135], v[216:219], v[84:87]
	v_mfma_f32_16x16x32_bf16 v[76:79], v[140:143], v[216:219], v[76:79]
	s_setprio 0
	s_setprio 1
	v_mfma_f32_16x16x32_bf16 v[108:111], v[166:169], v[188:191], v[108:111]
	v_mfma_f32_16x16x32_bf16 v[104:107], v[180:183], v[188:191], v[104:107]
	v_mfma_f32_16x16x32_bf16 v[96:99], v[166:169], v[196:199], v[96:99]
	v_mfma_f32_16x16x32_bf16 v[88:91], v[180:183], v[196:199], v[88:91]
	v_mfma_f32_16x16x32_bf16 v[80:83], v[166:169], v[204:207], v[80:83]
	v_mfma_f32_16x16x32_bf16 v[72:75], v[180:183], v[204:207], v[72:75]
	v_mfma_f32_16x16x32_bf16 v[68:71], v[166:169], v[212:215], v[68:71]
	v_mfma_f32_16x16x32_bf16 v[64:67], v[180:183], v[212:215], v[64:67]
	v_mfma_f32_16x16x32_bf16 v[108:111], v[170:173], v[192:195], v[108:111]
	v_mfma_f32_16x16x32_bf16 v[104:107], v[184:187], v[192:195], v[104:107]
	v_mfma_f32_16x16x32_bf16 v[96:99], v[170:173], v[200:203], v[96:99]
	v_mfma_f32_16x16x32_bf16 v[88:91], v[184:187], v[200:203], v[88:91]
	v_mfma_f32_16x16x32_bf16 v[80:83], v[170:173], v[208:211], v[80:83]
	v_mfma_f32_16x16x32_bf16 v[72:75], v[184:187], v[208:211], v[72:75]
	v_mfma_f32_16x16x32_bf16 v[68:71], v[170:173], v[216:219], v[68:71]
	v_mfma_f32_16x16x32_bf16 v[64:67], v[184:187], v[216:219], v[64:67]
	s_setprio 0
	s_barrier
	s_add_i32 s54, s46, s28
	v_lshl_add_u64 v[174:175], s[2:3], 0, v[146:147]
	s_mov_b32 m0, s54
	ds_read_b128 v[188:191], v163 offset:16384
	ds_read_b128 v[192:195], v163 offset:17408
	ds_read_b128 v[196:199], v163 offset:18432
	ds_read_b128 v[200:203], v163 offset:19456
	ds_read_b128 v[204:207], v163 offset:20480
	ds_read_b128 v[208:211], v163 offset:21504
	ds_read_b128 v[212:215], v163 offset:22528
	ds_read_b128 v[216:219], v163 offset:23552
	global_load_lds_dwordx4 v[174:175], off
	s_add_i32 m0, s54, 0x2000
	s_add_u32 s54, s2, 0x40000
	v_lshl_add_u64 v[220:221], s[2:3], 0, v[150:151]
	s_addc_u32 s55, s3, 0
	s_add_i32 s60, s47, s28
	global_load_lds_dwordx4 v[220:221], off
	v_lshl_add_u64 v[222:223], s[54:55], 0, v[146:147]
	s_mov_b32 m0, s60
	v_lshl_add_u64 v[224:225], s[18:19], 0, v[148:149]
	global_load_lds_dwordx4 v[222:223], off
	v_lshl_add_u64 v[222:223], s[54:55], 0, v[150:151]
	s_add_i32 m0, s60, 0x2000
	s_nop 0
	global_load_lds_dwordx4 v[222:223], off
	v_lshl_add_u64 v[222:223], s[18:19], 0, v[144:145]
	s_mov_b32 m0, s23
	s_nop 0
	global_load_lds_dwordx4 v[222:223], off
	s_mov_b32 m0, s29
	s_nop 0
	global_load_lds_dwordx4 v[224:225], off
	s_waitcnt vmcnt(8)
	s_waitcnt lgkmcnt(0)
	s_barrier
; #define PG8_STAGE(bufoff, gbase, voff) do { _Pragma("unroll") for (int _i = 0; _i < 2; ++_i) \
;         __builtin_amdgcn_global_load_lds((const unsigned*)((const char*)(gbase) + (voff)[_i]), (PG8_LAS unsigned*)(lds + (bufoff) + ldsw + _i * 8192), 16, 0, 0); } while (0)
; #define PG8_LDA(dst, b, h) do { _Pragma("unroll") for (int m = 0; m < 4; ++m) _Pragma("unroll") for (int k = 0; k < 2; ++k) dst[m][k] = *(const PG8_LAS bf16x8*)(lds + PG8_SA(b, h) + aoff + m * 2048 + k * 1024); } while (0)
; #define PG8_LDB(dst, b, h) do { _Pragma("unroll") for (int n = 0; n < 2; ++n) _Pragma("unroll") for (int k = 0; k < 2; ++k) dst[n][k] = *(const PG8_LAS bf16x8*)(lds + PG8_SB(b, h) + boff + n * 2048 + k * 1024); } while (0)
; #define PG8_MMA(ai, bj, At, Bt) do { __builtin_amdgcn_s_setprio(1); _Pragma("unroll") for (int m = 0; m < 4; ++m) _Pragma("unroll") for (int n = 0; n < 2; ++n) _Pragma("unroll") for (int k = 0; k < 2; ++k) \
;         acc[ai][bj][m][n] = __builtin_amdgcn_mfma_f32_16x16x32_bf16(Bt[n][k], At[m][k], acc[ai][bj][m][n], 0, 0, 0); __builtin_amdgcn_s_setprio(0); } while (0)
; #define PG8_WAIT_V(n) asm volatile("s_waitcnt vmcnt(" #n ")" ::: "memory")
; #define PG8_WAIT_L(n) asm volatile("s_waitcnt lgkmcnt(" #n ")" ::: "memory")
; #define PG8_BAR __builtin_amdgcn_s_barrier()
; #define PG8_SCHED __builtin_amdgcn_sched_barrier(0)
; template <class Epi, class Sched, bool ALIGN_EPI = false, bool SP2 = false>
; __device__ __forceinline__ void gemm_phase(PG8_LAS unsigned char* lds, const Gemm g, const Sched& S, const Epi& E) {
;     ...
;             PG8_WAIT_V(8); PG8_WAIT_L(0); PG8_BAR; PG8_MMA(1, 0, At, B0); PG8_MMA(1, 1, At, B1); PG8_BAR; PG8_SCHED;
;             PG8_LDB(B0, 1, 0); PG8_LDB(B1, 1, 1); PG8_SCHED; PG8_LDA(At, 1, 0); PG8_STAGE(PG8_SA(0, 1), a2 + hstep, voffA);
;             PG8_WAIT_V(8); PG8_WAIT_L(0); PG8_BAR; PG8_MMA(0, 0, At, B0); PG8_MMA(0, 1, At, B1); PG8_BAR; PG8_SCHED;
	s_setprio 1
	s_waitcnt lgkmcnt(0)
	v_mfma_f32_16x16x32_bf16 v[60:63], v[128:131], v[188:191], v[60:63]
	v_mfma_f32_16x16x32_bf16 v[56:59], v[136:139], v[188:191], v[56:59]
	v_mfma_f32_16x16x32_bf16 v[48:51], v[128:131], v[196:199], v[48:51]
	v_mfma_f32_16x16x32_bf16 v[40:43], v[136:139], v[196:199], v[40:43]
	v_mfma_f32_16x16x32_bf16 v[36:39], v[128:131], v[204:207], v[36:39]
	v_mfma_f32_16x16x32_bf16 v[28:31], v[136:139], v[204:207], v[28:31]
	v_mfma_f32_16x16x32_bf16 v[20:23], v[128:131], v[212:215], v[20:23]
	v_mfma_f32_16x16x32_bf16 v[12:15], v[136:139], v[212:215], v[12:15]
	v_mfma_f32_16x16x32_bf16 v[60:63], v[132:135], v[192:195], v[60:63]
	v_mfma_f32_16x16x32_bf16 v[56:59], v[140:143], v[192:195], v[56:59]
	v_mfma_f32_16x16x32_bf16 v[48:51], v[132:135], v[200:203], v[48:51]
	v_mfma_f32_16x16x32_bf16 v[40:43], v[140:143], v[200:203], v[40:43]
	v_mfma_f32_16x16x32_bf16 v[36:39], v[132:135], v[208:211], v[36:39]
	v_mfma_f32_16x16x32_bf16 v[28:31], v[140:143], v[208:211], v[28:31]
	v_mfma_f32_16x16x32_bf16 v[20:23], v[132:135], v[216:219], v[20:23]
	v_mfma_f32_16x16x32_bf16 v[12:15], v[140:143], v[216:219], v[12:15]
	s_setprio 0
	s_setprio 1
	v_mfma_f32_16x16x32_bf16 v[52:55], v[166:169], v[188:191], v[52:55]
	v_mfma_f32_16x16x32_bf16 v[44:47], v[180:183], v[188:191], v[44:47]
	v_mfma_f32_16x16x32_bf16 v[32:35], v[166:169], v[196:199], v[32:35]
	v_mfma_f32_16x16x32_bf16 v[24:27], v[180:183], v[196:199], v[24:27]
	v_mfma_f32_16x16x32_bf16 v[16:19], v[166:169], v[204:207], v[16:19]
	v_mfma_f32_16x16x32_bf16 v[8:11], v[180:183], v[204:207], v[8:11]
	v_mfma_f32_16x16x32_bf16 v[4:7], v[166:169], v[212:215], v[4:7]
	v_mfma_f32_16x16x32_bf16 v[0:3], v[180:183], v[212:215], v[0:3]
	v_mfma_f32_16x16x32_bf16 v[52:55], v[170:173], v[192:195], v[52:55]
	v_mfma_f32_16x16x32_bf16 v[44:47], v[184:187], v[192:195], v[44:47]
	v_mfma_f32_16x16x32_bf16 v[32:35], v[170:173], v[200:203], v[32:35]
	v_mfma_f32_16x16x32_bf16 v[24:27], v[184:187], v[200:203], v[24:27]
	v_mfma_f32_16x16x32_bf16 v[16:19], v[170:173], v[208:211], v[16:19]
	v_mfma_f32_16x16x32_bf16 v[8:11], v[184:187], v[208:211], v[8:11]
	v_mfma_f32_16x16x32_bf16 v[4:7], v[170:173], v[216:219], v[4:7]
	v_mfma_f32_16x16x32_bf16 v[0:3], v[184:187], v[216:219], v[0:3]
	s_setprio 0
	s_barrier
	s_add_i32 s54, 0, 0x18000
	s_add_i32 s55, 0, 0x1c000
	v_add_u32_e32 v140, s54, v160
	v_add_u32_e32 v179, s55, v160
	ds_read_b128 v[128:131], v140
	ds_read_b128 v[132:135], v140 offset:1024
	ds_read_b128 v[136:139], v140 offset:2048
	ds_read_b128 v[140:143], v140 offset:3072
	ds_read_b128 v[166:169], v179
	ds_read_b128 v[170:173], v179 offset:1024
	ds_read_b128 v[180:183], v179 offset:2048
	ds_read_b128 v[184:187], v179 offset:3072
	s_add_u32 s18, s18, 0x40000
	s_addc_u32 s19, s19, 0
	s_mov_b32 m0, s33
	v_lshl_add_u64 v[226:227], s[18:19], 0, v[144:145]
	ds_read_b128 v[188:191], v163 offset:32768
	ds_read_b128 v[192:195], v163 offset:33792
	ds_read_b128 v[196:199], v163 offset:34816
	ds_read_b128 v[200:203], v163 offset:35840
	ds_read_b128 v[204:207], v163 offset:36864
	ds_read_b128 v[208:211], v163 offset:37888
	ds_read_b128 v[212:215], v163 offset:38912
	ds_read_b128 v[216:219], v163 offset:39936
	global_load_lds_dwordx4 v[226:227], off
	v_lshl_add_u64 v[226:227], s[18:19], 0, v[148:149]
	s_mov_b32 m0, s34
	s_nop 0
	global_load_lds_dwordx4 v[226:227], off
	s_waitcnt vmcnt(8)
	s_waitcnt lgkmcnt(0)
	s_barrier
	s_setprio 1
	s_waitcnt lgkmcnt(0)
	v_mfma_f32_16x16x32_bf16 v[124:127], v[128:131], v[188:191], v[124:127]
	v_mfma_f32_16x16x32_bf16 v[120:123], v[136:139], v[188:191], v[120:123]
	v_mfma_f32_16x16x32_bf16 v[116:119], v[128:131], v[196:199], v[116:119]
	v_mfma_f32_16x16x32_bf16 v[112:115], v[136:139], v[196:199], v[112:115]
	v_mfma_f32_16x16x32_bf16 v[100:103], v[128:131], v[204:207], v[100:103]
	v_mfma_f32_16x16x32_bf16 v[92:95], v[136:139], v[204:207], v[92:95]
	v_mfma_f32_16x16x32_bf16 v[84:87], v[128:131], v[212:215], v[84:87]
	v_mfma_f32_16x16x32_bf16 v[76:79], v[136:139], v[212:215], v[76:79]
	v_mfma_f32_16x16x32_bf16 v[124:127], v[132:135], v[192:195], v[124:127]
	v_mfma_f32_16x16x32_bf16 v[120:123], v[140:143], v[192:195], v[120:123]
	v_mfma_f32_16x16x32_bf16 v[116:119], v[132:135], v[200:203], v[116:119]
	v_mfma_f32_16x16x32_bf16 v[112:115], v[140:143], v[200:203], v[112:115]
	v_mfma_f32_16x16x32_bf16 v[100:103], v[132:135], v[208:211], v[100:103]
	v_mfma_f32_16x16x32_bf16 v[92:95], v[140:143], v[208:211], v[92:95]
	v_mfma_f32_16x16x32_bf16 v[84:87], v[132:135], v[216:219], v[84:87]
	v_mfma_f32_16x16x32_bf16 v[76:79], v[140:143], v[216:219], v[76:79]
	s_setprio 0
	s_setprio 1
	v_mfma_f32_16x16x32_bf16 v[108:111], v[166:169], v[188:191], v[108:111]
	v_mfma_f32_16x16x32_bf16 v[104:107], v[180:183], v[188:191], v[104:107]
	v_mfma_f32_16x16x32_bf16 v[96:99], v[166:169], v[196:199], v[96:99]
	v_mfma_f32_16x16x32_bf16 v[88:91], v[180:183], v[196:199], v[88:91]
	v_mfma_f32_16x16x32_bf16 v[80:83], v[166:169], v[204:207], v[80:83]
	v_mfma_f32_16x16x32_bf16 v[72:75], v[180:183], v[204:207], v[72:75]
	v_mfma_f32_16x16x32_bf16 v[68:71], v[166:169], v[212:215], v[68:71]
	v_mfma_f32_16x16x32_bf16 v[64:67], v[180:183], v[212:215], v[64:67]
	v_mfma_f32_16x16x32_bf16 v[108:111], v[170:173], v[192:195], v[108:111]
	v_mfma_f32_16x16x32_bf16 v[104:107], v[184:187], v[192:195], v[104:107]
	v_mfma_f32_16x16x32_bf16 v[96:99], v[170:173], v[200:203], v[96:99]
	v_mfma_f32_16x16x32_bf16 v[88:91], v[184:187], v[200:203], v[88:91]
	v_mfma_f32_16x16x32_bf16 v[80:83], v[170:173], v[208:211], v[80:83]
	v_mfma_f32_16x16x32_bf16 v[72:75], v[184:187], v[208:211], v[72:75]
	v_mfma_f32_16x16x32_bf16 v[68:71], v[170:173], v[216:219], v[68:71]
	v_mfma_f32_16x16x32_bf16 v[64:67], v[184:187], v[216:219], v[64:67]
	s_setprio 0
	s_barrier
; #define PG8_STAGE(bufoff, gbase, voff) do { _Pragma("unroll") for (int _i = 0; _i < 2; ++_i) \
;         __builtin_amdgcn_global_load_lds((const unsigned*)((const char*)(gbase) + (voff)[_i]), (PG8_LAS unsigned*)(lds + (bufoff) + ldsw + _i * 8192), 16, 0, 0); } while (0)
; #define PG8_LDA(dst, b, h) do { _Pragma("unroll") for (int m = 0; m < 4; ++m) _Pragma("unroll") for (int k = 0; k < 2; ++k) dst[m][k] = *(const PG8_LAS bf16x8*)(lds + PG8_SA(b, h) + aoff + m * 2048 + k * 1024); } while (0)
; #define PG8_MMA(ai, bj, At, Bt) do { __builtin_amdgcn_s_setprio(1); _Pragma("unroll") for (int m = 0; m < 4; ++m) _Pragma("unroll") for (int n = 0; n < 2; ++n) _Pragma("unroll") for (int k = 0; k < 2; ++k) \
;         acc[ai][bj][m][n] = __builtin_amdgcn_mfma_f32_16x16x32_bf16(Bt[n][k], At[m][k], acc[ai][bj][m][n], 0, 0, 0); __builtin_amdgcn_s_setprio(0); } while (0)
; #define PG8_WAIT_V(n) asm volatile("s_waitcnt vmcnt(" #n ")" ::: "memory")
; #define PG8_WAIT_L(n) asm volatile("s_waitcnt lgkmcnt(" #n ")" ::: "memory")
; #define PG8_BAR __builtin_amdgcn_s_barrier()
; #define PG8_SCHED __builtin_amdgcn_sched_barrier(0)
; template <class Epi, class Sched, bool ALIGN_EPI = false, bool SP2 = false>
; __device__ __forceinline__ void gemm_phase(PG8_LAS unsigned char* lds, const Gemm g, const Sched& S, const Epi& E) {
;     ...
;         for (int t = 0; t < nt; t += 2) {
;     ...
;             PG8_LDA(At, 1, 1); PG8_STAGE(PG8_SB(1, 0), b3, voffB); PG8_STAGE(PG8_SB(1, 1), b3 + hstep, voffB); PG8_STAGE(PG8_SA(1, 0), a3, voffA);
;             PG8_WAIT_V(8); PG8_WAIT_L(0); PG8_BAR; PG8_MMA(1, 0, At, B0); PG8_MMA(1, 1, At, B1); PG8_BAR; PG8_SCHED;
	s_add_i32 s18, s54, s28
	v_lshl_add_u64 v[174:175], v[174:175], 0, s[6:7]
	s_mov_b32 m0, s18
	ds_read_b128 v[188:191], v163 offset:49152
	ds_read_b128 v[192:195], v163 offset:50176
	ds_read_b128 v[196:199], v163 offset:51200
	ds_read_b128 v[200:203], v163 offset:52224
	ds_read_b128 v[204:207], v163 offset:53248
	ds_read_b128 v[208:211], v163 offset:54272
	ds_read_b128 v[212:215], v163 offset:55296
	ds_read_b128 v[216:219], v163 offset:56320
	global_load_lds_dwordx4 v[174:175], off
	s_add_i32 m0, s18, 0x2000
	s_add_u32 s2, s2, 0x40080
	v_lshl_add_u64 v[174:175], v[220:221], 0, s[6:7]
	s_addc_u32 s3, s3, 0
	s_add_i32 s18, s55, s28
	global_load_lds_dwordx4 v[174:175], off
	v_lshl_add_u64 v[174:175], s[2:3], 0, v[146:147]
	s_mov_b32 m0, s18
	s_nop 0
	global_load_lds_dwordx4 v[174:175], off
	v_lshl_add_u64 v[174:175], s[2:3], 0, v[150:151]
	s_add_i32 m0, s18, 0x2000
	s_nop 0
	global_load_lds_dwordx4 v[174:175], off
	v_lshl_add_u64 v[174:175], v[222:223], 0, s[6:7]
	s_mov_b32 m0, s37
	s_nop 0
	global_load_lds_dwordx4 v[174:175], off
	v_lshl_add_u64 v[174:175], v[224:225], 0, s[6:7]
	s_mov_b32 m0, s42
	s_nop 0
	global_load_lds_dwordx4 v[174:175], off
	s_waitcnt vmcnt(8)
	s_waitcnt lgkmcnt(0)
	s_barrier
	s_setprio 1
	s_waitcnt lgkmcnt(0)
	v_mfma_f32_16x16x32_bf16 v[60:63], v[128:131], v[188:191], v[60:63]
	v_mfma_f32_16x16x32_bf16 v[56:59], v[136:139], v[188:191], v[56:59]
	v_mfma_f32_16x16x32_bf16 v[48:51], v[128:131], v[196:199], v[48:51]
	v_mfma_f32_16x16x32_bf16 v[40:43], v[136:139], v[196:199], v[40:43]
	v_mfma_f32_16x16x32_bf16 v[36:39], v[128:131], v[204:207], v[36:39]
	v_mfma_f32_16x16x32_bf16 v[28:31], v[136:139], v[204:207], v[28:31]
	v_mfma_f32_16x16x32_bf16 v[20:23], v[128:131], v[212:215], v[20:23]
	v_mfma_f32_16x16x32_bf16 v[12:15], v[136:139], v[212:215], v[12:15]
	v_mfma_f32_16x16x32_bf16 v[60:63], v[132:135], v[192:195], v[60:63]
	v_mfma_f32_16x16x32_bf16 v[56:59], v[140:143], v[192:195], v[56:59]
	v_mfma_f32_16x16x32_bf16 v[48:51], v[132:135], v[200:203], v[48:51]
	v_mfma_f32_16x16x32_bf16 v[40:43], v[140:143], v[200:203], v[40:43]
	v_mfma_f32_16x16x32_bf16 v[36:39], v[132:135], v[208:211], v[36:39]
	v_mfma_f32_16x16x32_bf16 v[28:31], v[140:143], v[208:211], v[28:31]
	v_mfma_f32_16x16x32_bf16 v[20:23], v[132:135], v[216:219], v[20:23]
	v_mfma_f32_16x16x32_bf16 v[12:15], v[140:143], v[216:219], v[12:15]
	s_setprio 0
	s_setprio 1
	v_mfma_f32_16x16x32_bf16 v[52:55], v[166:169], v[188:191], v[52:55]
	v_mfma_f32_16x16x32_bf16 v[44:47], v[180:183], v[188:191], v[44:47]
	v_mfma_f32_16x16x32_bf16 v[32:35], v[166:169], v[196:199], v[32:35]
	v_mfma_f32_16x16x32_bf16 v[24:27], v[180:183], v[196:199], v[24:27]
	v_mfma_f32_16x16x32_bf16 v[16:19], v[166:169], v[204:207], v[16:19]
	v_mfma_f32_16x16x32_bf16 v[8:11], v[180:183], v[204:207], v[8:11]
	v_mfma_f32_16x16x32_bf16 v[4:7], v[166:169], v[212:215], v[4:7]
	v_mfma_f32_16x16x32_bf16 v[0:3], v[180:183], v[212:215], v[0:3]
	v_mfma_f32_16x16x32_bf16 v[52:55], v[170:173], v[192:195], v[52:55]
	v_mfma_f32_16x16x32_bf16 v[44:47], v[184:187], v[192:195], v[44:47]
	v_mfma_f32_16x16x32_bf16 v[32:35], v[170:173], v[200:203], v[32:35]
	v_mfma_f32_16x16x32_bf16 v[24:27], v[184:187], v[200:203], v[24:27]
	v_mfma_f32_16x16x32_bf16 v[16:19], v[170:173], v[208:211], v[16:19]
	v_mfma_f32_16x16x32_bf16 v[8:11], v[184:187], v[208:211], v[8:11]
	v_mfma_f32_16x16x32_bf16 v[4:7], v[170:173], v[216:219], v[4:7]
	v_mfma_f32_16x16x32_bf16 v[0:3], v[184:187], v[216:219], v[0:3]
	s_setprio 0
	s_add_i32 s53, s53, 2
	s_add_u32 s24, s24, 0x100
	s_addc_u32 s25, s25, 0
	s_add_u32 s51, s51, 0x100
	s_addc_u32 s52, s52, 0
	s_cmp_gt_u32 s53, 13
	s_barrier
	s_cbranch_scc0 .LBB0_819
	s_and_b64 vcc, exec, s[8:9]
	s_cbranch_vccz .LBB0_822
	s_barrier

; #define PG8_STAGE(bufoff, gbase, voff) do { _Pragma("unroll") for (int _i = 0; _i < 2; ++_i) \
;         __builtin_amdgcn_global_load_lds((const unsigned*)((const char*)(gbase) + (voff)[_i]), (PG8_LAS unsigned*)(lds + (bufoff) + ldsw + _i * 8192), 16, 0, 0); } while (0)
; #define PG8_LDA(dst, b, h) do { _Pragma("unroll") for (int m = 0; m < 4; ++m) _Pragma("unroll") for (int k = 0; k < 2; ++k) dst[m][k] = *(const PG8_LAS bf16x8*)(lds + PG8_SA(b, h) + aoff + m * 2048 + k * 1024); } while (0)
; #define PG8_LDB(dst, b, h) do { _Pragma("unroll") for (int n = 0; n < 2; ++n) _Pragma("unroll") for (int k = 0; k < 2; ++k) dst[n][k] = *(const PG8_LAS bf16x8*)(lds + PG8_SB(b, h) + boff + n * 2048 + k * 1024); } while (0)
; #define PG8_MMA(ai, bj, At, Bt) do { __builtin_amdgcn_s_setprio(1); _Pragma("unroll") for (int m = 0; m < 4; ++m) _Pragma("unroll") for (int n = 0; n < 2; ++n) _Pragma("unroll") for (int k = 0; k < 2; ++k) \
;         acc[ai][bj][m][n] = __builtin_amdgcn_mfma_f32_16x16x32_bf16(Bt[n][k], At[m][k], acc[ai][bj][m][n], 0, 0, 0); __builtin_amdgcn_s_setprio(0); } while (0)
; #define PG8_WAIT_V(n) asm volatile("s_waitcnt vmcnt(" #n ")" ::: "memory")
; #define PG8_WAIT_L(n) asm volatile("s_waitcnt lgkmcnt(" #n ")" ::: "memory")
; #define PG8_BAR __builtin_amdgcn_s_barrier()
; #define PG8_SCHED __builtin_amdgcn_sched_barrier(0)
; template <class Epi, class Sched, bool ALIGN_EPI = false, bool SP2 = false>
; __device__ __forceinline__ void gemm_phase(PG8_LAS unsigned char* lds, const Gemm g, const Sched& S, const Epi& E) {
;     ...
;             PG8_LDB(B0, 0, 0); PG8_LDB(B1, 0, 1); PG8_SCHED; PG8_LDA(At, 0, 0); PG8_STAGE(PG8_SA(1, 1), a1 + hstep, voffA);
;             PG8_WAIT_V(8); PG8_WAIT_L(0); PG8_BAR; PG8_MMA(0, 0, At, B0); PG8_MMA(0, 1, At, B1); PG8_BAR; PG8_SCHED;
;             PG8_LDA(At, 0, 1); PG8_STAGE(PG8_SB(0, 0), b2, voffB); PG8_STAGE(PG8_SB(0, 1), b2 + hstep, voffB); PG8_STAGE(PG8_SA(0, 0), a2, voffA);
;             PG8_WAIT_V(8); PG8_WAIT_L(0); PG8_BAR; PG8_MMA(1, 0, At, B0); PG8_MMA(1, 1, At, B1); PG8_BAR; PG8_SCHED;
.LBB0_1151:
	ds_read_b128 v[144:147], v151
	ds_read_b128 v[156:159], v151 offset:1024
	ds_read_b128 v[160:163], v151 offset:2048
	ds_read_b128 v[164:167], v151 offset:3072
	ds_read_b128 v[168:171], v152
	ds_read_b128 v[172:175], v152 offset:1024
	ds_read_b128 v[178:181], v152 offset:2048
	ds_read_b128 v[182:185], v152 offset:3072
	s_add_u32 s2, s28, 0xfffc0080
	s_addc_u32 s3, s29, -1
	s_cmp_eq_u32 s56, 12
	s_cselect_b32 s19, s17, s3
	s_cselect_b32 s18, s27, s2
	s_cselect_b32 s3, s15, s55
	s_cselect_b32 s2, s53, s54
	v_lshl_add_u64 v[218:219], s[28:29], 0, v[136:137]
	s_add_i32 m0, s34, 0xc000
	ds_read_b128 v[186:189], v153
	ds_read_b128 v[190:193], v153 offset:1024
	ds_read_b128 v[194:197], v153 offset:2048
	ds_read_b128 v[198:201], v153 offset:3072
	ds_read_b128 v[202:205], v153 offset:4096
	ds_read_b128 v[206:209], v153 offset:5120
	ds_read_b128 v[210:213], v153 offset:6144
	ds_read_b128 v[214:217], v153 offset:7168
	global_load_lds_dwordx4 v[218:219], off
	v_lshl_add_u64 v[218:219], s[28:29], 0, v[138:139]
	s_add_i32 m0, s34, 0xe000
	s_nop 0
	global_load_lds_dwordx4 v[218:219], off
	s_waitcnt vmcnt(8)
	s_waitcnt lgkmcnt(0)
	s_barrier
	s_setprio 1
	s_waitcnt lgkmcnt(0)
	v_mfma_f32_16x16x32_bf16 v[124:127], v[144:147], v[186:189], v[124:127]
	v_mfma_f32_16x16x32_bf16 v[120:123], v[160:163], v[186:189], v[120:123]
	v_mfma_f32_16x16x32_bf16 v[108:111], v[144:147], v[194:197], v[108:111]
	v_mfma_f32_16x16x32_bf16 v[104:107], v[160:163], v[194:197], v[104:107]
	v_mfma_f32_16x16x32_bf16 v[92:95], v[144:147], v[202:205], v[92:95]
	v_mfma_f32_16x16x32_bf16 v[88:91], v[160:163], v[202:205], v[88:91]
	v_mfma_f32_16x16x32_bf16 v[76:79], v[144:147], v[210:213], v[76:79]
	v_mfma_f32_16x16x32_bf16 v[72:75], v[160:163], v[210:213], v[72:75]
	v_mfma_f32_16x16x32_bf16 v[124:127], v[156:159], v[190:193], v[124:127]
	v_mfma_f32_16x16x32_bf16 v[120:123], v[164:167], v[190:193], v[120:123]
	v_mfma_f32_16x16x32_bf16 v[108:111], v[156:159], v[198:201], v[108:111]
	v_mfma_f32_16x16x32_bf16 v[104:107], v[164:167], v[198:201], v[104:107]
	v_mfma_f32_16x16x32_bf16 v[92:95], v[156:159], v[206:209], v[92:95]
	v_mfma_f32_16x16x32_bf16 v[88:91], v[164:167], v[206:209], v[88:91]
	v_mfma_f32_16x16x32_bf16 v[76:79], v[156:159], v[214:217], v[76:79]
	v_mfma_f32_16x16x32_bf16 v[72:75], v[164:167], v[214:217], v[72:75]
	s_setprio 0
	s_setprio 1
	v_mfma_f32_16x16x32_bf16 v[116:119], v[168:171], v[186:189], v[116:119]
	v_mfma_f32_16x16x32_bf16 v[112:115], v[178:181], v[186:189], v[112:115]
	v_mfma_f32_16x16x32_bf16 v[100:103], v[168:171], v[194:197], v[100:103]
	v_mfma_f32_16x16x32_bf16 v[96:99], v[178:181], v[194:197], v[96:99]
	v_mfma_f32_16x16x32_bf16 v[84:87], v[168:171], v[202:205], v[84:87]
	v_mfma_f32_16x16x32_bf16 v[80:83], v[178:181], v[202:205], v[80:83]
	v_mfma_f32_16x16x32_bf16 v[68:71], v[168:171], v[210:213], v[68:71]
	v_mfma_f32_16x16x32_bf16 v[64:67], v[178:181], v[210:213], v[64:67]
	v_mfma_f32_16x16x32_bf16 v[116:119], v[172:175], v[190:193], v[116:119]
	v_mfma_f32_16x16x32_bf16 v[112:115], v[182:185], v[190:193], v[112:115]
	v_mfma_f32_16x16x32_bf16 v[100:103], v[172:175], v[198:201], v[100:103]
	v_mfma_f32_16x16x32_bf16 v[96:99], v[182:185], v[198:201], v[96:99]
	v_mfma_f32_16x16x32_bf16 v[84:87], v[172:175], v[206:209], v[84:87]
	v_mfma_f32_16x16x32_bf16 v[80:83], v[182:185], v[206:209], v[80:83]
	v_mfma_f32_16x16x32_bf16 v[68:71], v[172:175], v[214:217], v[68:71]
	v_mfma_f32_16x16x32_bf16 v[64:67], v[182:185], v[214:217], v[64:67]
	s_setprio 0
	s_barrier
	s_add_i32 s57, s50, s33
	v_lshl_add_u64 v[218:219], s[2:3], 0, v[130:131]
	s_mov_b32 m0, s57
	ds_read_b128 v[186:189], v153 offset:16384
	ds_read_b128 v[190:193], v153 offset:17408
	ds_read_b128 v[194:197], v153 offset:18432
	ds_read_b128 v[198:201], v153 offset:19456
	ds_read_b128 v[202:205], v153 offset:20480
	ds_read_b128 v[206:209], v153 offset:21504
	ds_read_b128 v[210:213], v153 offset:22528
	ds_read_b128 v[214:217], v153 offset:23552
	global_load_lds_dwordx4 v[218:219], off
	s_add_i32 m0, s57, 0x2000
	s_add_u32 s60, s2, 0x40000
	v_lshl_add_u64 v[220:221], s[2:3], 0, v[134:135]
	s_addc_u32 s61, s3, 0
	s_add_i32 s57, s51, s33
	global_load_lds_dwordx4 v[220:221], off
	v_lshl_add_u64 v[222:223], s[60:61], 0, v[130:131]
	s_mov_b32 m0, s57
	v_lshl_add_u64 v[224:225], s[18:19], 0, v[132:133]
	global_load_lds_dwordx4 v[222:223], off
	v_lshl_add_u64 v[222:223], s[60:61], 0, v[134:135]
	s_add_i32 m0, s57, 0x2000
	s_nop 0
	global_load_lds_dwordx4 v[222:223], off
	v_lshl_add_u64 v[222:223], s[18:19], 0, v[128:129]
	s_mov_b32 m0, s34
	s_nop 0
	global_load_lds_dwordx4 v[222:223], off
	s_mov_b32 m0, s35
	s_nop 0
	global_load_lds_dwordx4 v[224:225], off
	s_waitcnt vmcnt(8)
	s_waitcnt lgkmcnt(0)
	s_barrier
; #define PG8_STAGE(bufoff, gbase, voff) do { _Pragma("unroll") for (int _i = 0; _i < 2; ++_i) \
;         __builtin_amdgcn_global_load_lds((const unsigned*)((const char*)(gbase) + (voff)[_i]), (PG8_LAS unsigned*)(lds + (bufoff) + ldsw + _i * 8192), 16, 0, 0); } while (0)
; #define PG8_LDA(dst, b, h) do { _Pragma("unroll") for (int m = 0; m < 4; ++m) _Pragma("unroll") for (int k = 0; k < 2; ++k) dst[m][k] = *(const PG8_LAS bf16x8*)(lds + PG8_SA(b, h) + aoff + m * 2048 + k * 1024); } while (0)
; #define PG8_LDB(dst, b, h) do { _Pragma("unroll") for (int n = 0; n < 2; ++n) _Pragma("unroll") for (int k = 0; k < 2; ++k) dst[n][k] = *(const PG8_LAS bf16x8*)(lds + PG8_SB(b, h) + boff + n * 2048 + k * 1024); } while (0)
; #define PG8_MMA(ai, bj, At, Bt) do { __builtin_amdgcn_s_setprio(1); _Pragma("unroll") for (int m = 0; m < 4; ++m) _Pragma("unroll") for (int n = 0; n < 2; ++n) _Pragma("unroll") for (int k = 0; k < 2; ++k) \
;         acc[ai][bj][m][n] = __builtin_amdgcn_mfma_f32_16x16x32_bf16(Bt[n][k], At[m][k], acc[ai][bj][m][n], 0, 0, 0); __builtin_amdgcn_s_setprio(0); } while (0)
; #define PG8_WAIT_V(n) asm volatile("s_waitcnt vmcnt(" #n ")" ::: "memory")
; #define PG8_WAIT_L(n) asm volatile("s_waitcnt lgkmcnt(" #n ")" ::: "memory")
; #define PG8_BAR __builtin_amdgcn_s_barrier()
; #define PG8_SCHED __builtin_amdgcn_sched_barrier(0)
; template <class Epi, class Sched, bool ALIGN_EPI = false, bool SP2 = false>
; __device__ __forceinline__ void gemm_phase(PG8_LAS unsigned char* lds, const Gemm g, const Sched& S, const Epi& E) {
;     ...
;             PG8_WAIT_V(8); PG8_WAIT_L(0); PG8_BAR; PG8_MMA(1, 0, At, B0); PG8_MMA(1, 1, At, B1); PG8_BAR; PG8_SCHED;
;             PG8_LDB(B0, 1, 0); PG8_LDB(B1, 1, 1); PG8_SCHED; PG8_LDA(At, 1, 0); PG8_STAGE(PG8_SA(0, 1), a2 + hstep, voffA);
;             PG8_WAIT_V(8); PG8_WAIT_L(0); PG8_BAR; PG8_MMA(0, 0, At, B0); PG8_MMA(0, 1, At, B1); PG8_BAR; PG8_SCHED;
	s_setprio 1
	s_waitcnt lgkmcnt(0)
	v_mfma_f32_16x16x32_bf16 v[60:63], v[144:147], v[186:189], v[60:63]
	v_mfma_f32_16x16x32_bf16 v[56:59], v[160:163], v[186:189], v[56:59]
	v_mfma_f32_16x16x32_bf16 v[44:47], v[144:147], v[194:197], v[44:47]
	v_mfma_f32_16x16x32_bf16 v[40:43], v[160:163], v[194:197], v[40:43]
	v_mfma_f32_16x16x32_bf16 v[28:31], v[144:147], v[202:205], v[28:31]
	v_mfma_f32_16x16x32_bf16 v[24:27], v[160:163], v[202:205], v[24:27]
	v_mfma_f32_16x16x32_bf16 v[12:15], v[144:147], v[210:213], v[12:15]
	v_mfma_f32_16x16x32_bf16 v[8:11], v[160:163], v[210:213], v[8:11]
	v_mfma_f32_16x16x32_bf16 v[60:63], v[156:159], v[190:193], v[60:63]
	v_mfma_f32_16x16x32_bf16 v[56:59], v[164:167], v[190:193], v[56:59]
	v_mfma_f32_16x16x32_bf16 v[44:47], v[156:159], v[198:201], v[44:47]
	v_mfma_f32_16x16x32_bf16 v[40:43], v[164:167], v[198:201], v[40:43]
	v_mfma_f32_16x16x32_bf16 v[28:31], v[156:159], v[206:209], v[28:31]
	v_mfma_f32_16x16x32_bf16 v[24:27], v[164:167], v[206:209], v[24:27]
	v_mfma_f32_16x16x32_bf16 v[12:15], v[156:159], v[214:217], v[12:15]
	v_mfma_f32_16x16x32_bf16 v[8:11], v[164:167], v[214:217], v[8:11]
	s_setprio 0
	s_setprio 1
	v_mfma_f32_16x16x32_bf16 v[52:55], v[168:171], v[186:189], v[52:55]
	v_mfma_f32_16x16x32_bf16 v[48:51], v[178:181], v[186:189], v[48:51]
	v_mfma_f32_16x16x32_bf16 v[36:39], v[168:171], v[194:197], v[36:39]
	v_mfma_f32_16x16x32_bf16 v[32:35], v[178:181], v[194:197], v[32:35]
	v_mfma_f32_16x16x32_bf16 v[20:23], v[168:171], v[202:205], v[20:23]
	v_mfma_f32_16x16x32_bf16 v[16:19], v[178:181], v[202:205], v[16:19]
	v_mfma_f32_16x16x32_bf16 v[4:7], v[168:171], v[210:213], v[4:7]
	v_mfma_f32_16x16x32_bf16 v[0:3], v[178:181], v[210:213], v[0:3]
	v_mfma_f32_16x16x32_bf16 v[52:55], v[172:175], v[190:193], v[52:55]
	v_mfma_f32_16x16x32_bf16 v[48:51], v[182:185], v[190:193], v[48:51]
	v_mfma_f32_16x16x32_bf16 v[36:39], v[172:175], v[198:201], v[36:39]
	v_mfma_f32_16x16x32_bf16 v[32:35], v[182:185], v[198:201], v[32:35]
	v_mfma_f32_16x16x32_bf16 v[20:23], v[172:175], v[206:209], v[20:23]
	v_mfma_f32_16x16x32_bf16 v[16:19], v[182:185], v[206:209], v[16:19]
	v_mfma_f32_16x16x32_bf16 v[4:7], v[172:175], v[214:217], v[4:7]
	v_mfma_f32_16x16x32_bf16 v[0:3], v[182:185], v[214:217], v[0:3]
	s_setprio 0
	s_barrier
	s_add_i32 s57, 0, 0x18000
	v_add_u32_e32 v155, s57, v149
	s_add_i32 s60, 0, 0x1c000
	ds_read_b128 v[144:147], v155
	ds_read_b128 v[156:159], v155 offset:1024
	ds_read_b128 v[160:163], v155 offset:2048
	ds_read_b128 v[164:167], v155 offset:3072
	v_add_u32_e32 v155, s60, v149
	ds_read_b128 v[168:171], v155
	ds_read_b128 v[172:175], v155 offset:1024
	ds_read_b128 v[178:181], v155 offset:2048
	ds_read_b128 v[182:185], v155 offset:3072
	s_add_u32 s18, s18, 0x40000
	s_addc_u32 s19, s19, 0
	s_mov_b32 m0, s36
	v_lshl_add_u64 v[226:227], s[18:19], 0, v[128:129]
	ds_read_b128 v[186:189], v153 offset:32768
	ds_read_b128 v[190:193], v153 offset:33792
	ds_read_b128 v[194:197], v153 offset:34816
	ds_read_b128 v[198:201], v153 offset:35840
	ds_read_b128 v[202:205], v153 offset:36864
	ds_read_b128 v[206:209], v153 offset:37888
	ds_read_b128 v[210:213], v153 offset:38912
	ds_read_b128 v[214:217], v153 offset:39936
	global_load_lds_dwordx4 v[226:227], off
	v_lshl_add_u64 v[226:227], s[18:19], 0, v[132:133]
	s_mov_b32 m0, s37
	s_nop 0
	global_load_lds_dwordx4 v[226:227], off
	s_waitcnt vmcnt(8)
	s_waitcnt lgkmcnt(0)
	s_barrier
	s_setprio 1
	s_waitcnt lgkmcnt(0)
	v_mfma_f32_16x16x32_bf16 v[124:127], v[144:147], v[186:189], v[124:127]
	v_mfma_f32_16x16x32_bf16 v[120:123], v[160:163], v[186:189], v[120:123]
	v_mfma_f32_16x16x32_bf16 v[108:111], v[144:147], v[194:197], v[108:111]
	v_mfma_f32_16x16x32_bf16 v[104:107], v[160:163], v[194:197], v[104:107]
	v_mfma_f32_16x16x32_bf16 v[92:95], v[144:147], v[202:205], v[92:95]
	v_mfma_f32_16x16x32_bf16 v[88:91], v[160:163], v[202:205], v[88:91]
	v_mfma_f32_16x16x32_bf16 v[76:79], v[144:147], v[210:213], v[76:79]
	v_mfma_f32_16x16x32_bf16 v[72:75], v[160:163], v[210:213], v[72:75]
	v_mfma_f32_16x16x32_bf16 v[124:127], v[156:159], v[190:193], v[124:127]
	v_mfma_f32_16x16x32_bf16 v[120:123], v[164:167], v[190:193], v[120:123]
	v_mfma_f32_16x16x32_bf16 v[108:111], v[156:159], v[198:201], v[108:111]
	v_mfma_f32_16x16x32_bf16 v[104:107], v[164:167], v[198:201], v[104:107]
	v_mfma_f32_16x16x32_bf16 v[92:95], v[156:159], v[206:209], v[92:95]
	v_mfma_f32_16x16x32_bf16 v[88:91], v[164:167], v[206:209], v[88:91]
	v_mfma_f32_16x16x32_bf16 v[76:79], v[156:159], v[214:217], v[76:79]
	v_mfma_f32_16x16x32_bf16 v[72:75], v[164:167], v[214:217], v[72:75]
	s_setprio 0
	s_setprio 1
	v_mfma_f32_16x16x32_bf16 v[116:119], v[168:171], v[186:189], v[116:119]
	v_mfma_f32_16x16x32_bf16 v[112:115], v[178:181], v[186:189], v[112:115]
	v_mfma_f32_16x16x32_bf16 v[100:103], v[168:171], v[194:197], v[100:103]
	v_mfma_f32_16x16x32_bf16 v[96:99], v[178:181], v[194:197], v[96:99]
	v_mfma_f32_16x16x32_bf16 v[84:87], v[168:171], v[202:205], v[84:87]
	v_mfma_f32_16x16x32_bf16 v[80:83], v[178:181], v[202:205], v[80:83]
	v_mfma_f32_16x16x32_bf16 v[68:71], v[168:171], v[210:213], v[68:71]
	v_mfma_f32_16x16x32_bf16 v[64:67], v[178:181], v[210:213], v[64:67]
	v_mfma_f32_16x16x32_bf16 v[116:119], v[172:175], v[190:193], v[116:119]
	v_mfma_f32_16x16x32_bf16 v[112:115], v[182:185], v[190:193], v[112:115]
	v_mfma_f32_16x16x32_bf16 v[100:103], v[172:175], v[198:201], v[100:103]
	v_mfma_f32_16x16x32_bf16 v[96:99], v[182:185], v[198:201], v[96:99]
	v_mfma_f32_16x16x32_bf16 v[84:87], v[172:175], v[206:209], v[84:87]
	v_mfma_f32_16x16x32_bf16 v[80:83], v[182:185], v[206:209], v[80:83]
	v_mfma_f32_16x16x32_bf16 v[68:71], v[172:175], v[214:217], v[68:71]
	v_mfma_f32_16x16x32_bf16 v[64:67], v[182:185], v[214:217], v[64:67]
	s_setprio 0
	s_barrier
; #define PG8_STAGE(bufoff, gbase, voff) do { _Pragma("unroll") for (int _i = 0; _i < 2; ++_i) \
;         __builtin_amdgcn_global_load_lds((const unsigned*)((const char*)(gbase) + (voff)[_i]), (PG8_LAS unsigned*)(lds + (bufoff) + ldsw + _i * 8192), 16, 0, 0); } while (0)
; #define PG8_LDA(dst, b, h) do { _Pragma("unroll") for (int m = 0; m < 4; ++m) _Pragma("unroll") for (int k = 0; k < 2; ++k) dst[m][k] = *(const PG8_LAS bf16x8*)(lds + PG8_SA(b, h) + aoff + m * 2048 + k * 1024); } while (0)
; #define PG8_MMA(ai, bj, At, Bt) do { __builtin_amdgcn_s_setprio(1); _Pragma("unroll") for (int m = 0; m < 4; ++m) _Pragma("unroll") for (int n = 0; n < 2; ++n) _Pragma("unroll") for (int k = 0; k < 2; ++k) \
;         acc[ai][bj][m][n] = __builtin_amdgcn_mfma_f32_16x16x32_bf16(Bt[n][k], At[m][k], acc[ai][bj][m][n], 0, 0, 0); __builtin_amdgcn_s_setprio(0); } while (0)
; #define PG8_WAIT_V(n) asm volatile("s_waitcnt vmcnt(" #n ")" ::: "memory")
; #define PG8_WAIT_L(n) asm volatile("s_waitcnt lgkmcnt(" #n ")" ::: "memory")
; #define PG8_BAR __builtin_amdgcn_s_barrier()
; #define PG8_SCHED __builtin_amdgcn_sched_barrier(0)
; template <class Epi, class Sched, bool ALIGN_EPI = false, bool SP2 = false>
; __device__ __forceinline__ void gemm_phase(PG8_LAS unsigned char* lds, const Gemm g, const Sched& S, const Epi& E) {
;     ...
;         for (int t = 0; t < nt; t += 2) {
;     ...
;             PG8_LDA(At, 1, 1); PG8_STAGE(PG8_SB(1, 0), b3, voffB); PG8_STAGE(PG8_SB(1, 1), b3 + hstep, voffB); PG8_STAGE(PG8_SA(1, 0), a3, voffA);
;             PG8_WAIT_V(8); PG8_WAIT_L(0); PG8_BAR; PG8_MMA(1, 0, At, B0); PG8_MMA(1, 1, At, B1); PG8_BAR; PG8_SCHED;
	s_add_i32 s18, s57, s33
	v_lshl_add_u64 v[218:219], v[218:219], 0, s[10:11]
	s_mov_b32 m0, s18
	ds_read_b128 v[186:189], v153 offset:49152
	ds_read_b128 v[190:193], v153 offset:50176
	ds_read_b128 v[194:197], v153 offset:51200
	ds_read_b128 v[198:201], v153 offset:52224
	ds_read_b128 v[202:205], v153 offset:53248
	ds_read_b128 v[206:209], v153 offset:54272
	ds_read_b128 v[210:213], v153 offset:55296
	ds_read_b128 v[214:217], v153 offset:56320
	global_load_lds_dwordx4 v[218:219], off
	s_add_i32 m0, s18, 0x2000
	s_add_u32 s2, s2, 0x40080
	v_lshl_add_u64 v[218:219], v[220:221], 0, s[10:11]
	s_addc_u32 s3, s3, 0
	s_add_i32 s18, s60, s33
	global_load_lds_dwordx4 v[218:219], off
	v_lshl_add_u64 v[218:219], s[2:3], 0, v[130:131]
	s_mov_b32 m0, s18
	s_nop 0
	global_load_lds_dwordx4 v[218:219], off
	v_lshl_add_u64 v[218:219], s[2:3], 0, v[134:135]
	s_add_i32 m0, s18, 0x2000
	s_nop 0
	global_load_lds_dwordx4 v[218:219], off
	v_lshl_add_u64 v[218:219], v[222:223], 0, s[10:11]
	s_mov_b32 m0, s43
	s_nop 0
	global_load_lds_dwordx4 v[218:219], off
	v_lshl_add_u64 v[218:219], v[224:225], 0, s[10:11]
	s_mov_b32 m0, s46
	s_nop 0
	global_load_lds_dwordx4 v[218:219], off
	s_waitcnt vmcnt(8)
	s_waitcnt lgkmcnt(0)
	s_barrier
	s_setprio 1
	s_waitcnt lgkmcnt(0)
	v_mfma_f32_16x16x32_bf16 v[60:63], v[144:147], v[186:189], v[60:63]
	v_mfma_f32_16x16x32_bf16 v[56:59], v[160:163], v[186:189], v[56:59]
	v_mfma_f32_16x16x32_bf16 v[44:47], v[144:147], v[194:197], v[44:47]
	v_mfma_f32_16x16x32_bf16 v[40:43], v[160:163], v[194:197], v[40:43]
	v_mfma_f32_16x16x32_bf16 v[28:31], v[144:147], v[202:205], v[28:31]
	v_mfma_f32_16x16x32_bf16 v[24:27], v[160:163], v[202:205], v[24:27]
	v_mfma_f32_16x16x32_bf16 v[12:15], v[144:147], v[210:213], v[12:15]
	v_mfma_f32_16x16x32_bf16 v[8:11], v[160:163], v[210:213], v[8:11]
	v_mfma_f32_16x16x32_bf16 v[60:63], v[156:159], v[190:193], v[60:63]
	v_mfma_f32_16x16x32_bf16 v[56:59], v[164:167], v[190:193], v[56:59]
	v_mfma_f32_16x16x32_bf16 v[44:47], v[156:159], v[198:201], v[44:47]
	v_mfma_f32_16x16x32_bf16 v[40:43], v[164:167], v[198:201], v[40:43]
	v_mfma_f32_16x16x32_bf16 v[28:31], v[156:159], v[206:209], v[28:31]
	v_mfma_f32_16x16x32_bf16 v[24:27], v[164:167], v[206:209], v[24:27]
	v_mfma_f32_16x16x32_bf16 v[12:15], v[156:159], v[214:217], v[12:15]
	v_mfma_f32_16x16x32_bf16 v[8:11], v[164:167], v[214:217], v[8:11]
	s_setprio 0
	s_setprio 1
	v_mfma_f32_16x16x32_bf16 v[52:55], v[168:171], v[186:189], v[52:55]
	v_mfma_f32_16x16x32_bf16 v[48:51], v[178:181], v[186:189], v[48:51]
	v_mfma_f32_16x16x32_bf16 v[36:39], v[168:171], v[194:197], v[36:39]
	v_mfma_f32_16x16x32_bf16 v[32:35], v[178:181], v[194:197], v[32:35]
	v_mfma_f32_16x16x32_bf16 v[20:23], v[168:171], v[202:205], v[20:23]
	v_mfma_f32_16x16x32_bf16 v[16:19], v[178:181], v[202:205], v[16:19]
	v_mfma_f32_16x16x32_bf16 v[4:7], v[168:171], v[210:213], v[4:7]
	v_mfma_f32_16x16x32_bf16 v[0:3], v[178:181], v[210:213], v[0:3]
	v_mfma_f32_16x16x32_bf16 v[52:55], v[172:175], v[190:193], v[52:55]
	v_mfma_f32_16x16x32_bf16 v[48:51], v[182:185], v[190:193], v[48:51]
	v_mfma_f32_16x16x32_bf16 v[36:39], v[172:175], v[198:201], v[36:39]
	v_mfma_f32_16x16x32_bf16 v[32:35], v[182:185], v[198:201], v[32:35]
	v_mfma_f32_16x16x32_bf16 v[20:23], v[172:175], v[206:209], v[20:23]
	v_mfma_f32_16x16x32_bf16 v[16:19], v[182:185], v[206:209], v[16:19]
	v_mfma_f32_16x16x32_bf16 v[4:7], v[172:175], v[214:217], v[4:7]
	v_mfma_f32_16x16x32_bf16 v[0:3], v[182:185], v[214:217], v[0:3]
	s_setprio 0
	s_add_i32 s56, s56, 2
	s_add_u32 s28, s28, 0x100
	s_addc_u32 s29, s29, 0
	s_add_u32 s54, s54, 0x100
	s_addc_u32 s55, s55, 0
	s_cmp_gt_u32 s56, 13
	s_barrier
	s_cbranch_scc0 .LBB0_1151
	s_and_b64 vcc, exec, s[12:13]
	s_cbranch_vccz .LBB0_1154
	s_barrier

; #define PG8_STAGE(bufoff, gbase, voff) do { _Pragma("unroll") for (int _i = 0; _i < 2; ++_i) \
;         __builtin_amdgcn_global_load_lds((const unsigned*)((const char*)(gbase) + (voff)[_i]), (PG8_LAS unsigned*)(lds + (bufoff) + ldsw + _i * 8192), 16, 0, 0); } while (0)
; #define PG8_LDA(dst, b, h) do { _Pragma("unroll") for (int m = 0; m < 4; ++m) _Pragma("unroll") for (int k = 0; k < 2; ++k) dst[m][k] = *(const PG8_LAS bf16x8*)(lds + PG8_SA(b, h) + aoff + m * 2048 + k * 1024); } while (0)
; #define PG8_LDB(dst, b, h) do { _Pragma("unroll") for (int n = 0; n < 2; ++n) _Pragma("unroll") for (int k = 0; k < 2; ++k) dst[n][k] = *(const PG8_LAS bf16x8*)(lds + PG8_SB(b, h) + boff + n * 2048 + k * 1024); } while (0)
; #define PG8_MMA(ai, bj, At, Bt) do { __builtin_amdgcn_s_setprio(1); _Pragma("unroll") for (int m = 0; m < 4; ++m) _Pragma("unroll") for (int n = 0; n < 2; ++n) _Pragma("unroll") for (int k = 0; k < 2; ++k) \
;         acc[ai][bj][m][n] = __builtin_amdgcn_mfma_f32_16x16x32_bf16(Bt[n][k], At[m][k], acc[ai][bj][m][n], 0, 0, 0); __builtin_amdgcn_s_setprio(0); } while (0)
; #define PG8_WAIT_V(n) asm volatile("s_waitcnt vmcnt(" #n ")" ::: "memory")
; #define PG8_WAIT_L(n) asm volatile("s_waitcnt lgkmcnt(" #n ")" ::: "memory")
; #define PG8_BAR __builtin_amdgcn_s_barrier()
; #define PG8_SCHED __builtin_amdgcn_sched_barrier(0)
; template <class Epi, class Sched, bool ALIGN_EPI = false, bool SP2 = false>
; __device__ __forceinline__ void gemm_phase(PG8_LAS unsigned char* lds, const Gemm g, const Sched& S, const Epi& E) {
;     ...
;         for (int t = 0; t < nt; t += 2) {
;             const bool last = (t == nt - 2);
;             const char* a1 = cA + (size_t)(t + 1) * kstep;
;             const char* a2 = last ? nA : cA + (size_t)(t + 2) * kstep; const char* b2 = last ? nB : cB + (size_t)(t + 2) * kstep;
;             const char* a3 = a2 + kstep; const char* b3 = b2 + kstep;
;             if (last && has_next) S.a_ready(nxt);
;             if constexpr (SP2) {
;             PG8_LDB(B0, 0, 0); PG8_LDB(B1, 0, 1); PG8_SCHED; PG8_LDA(At, 0, 0); PG8_STAGE(PG8_SA(1, 1), a1 + hstep, voffA);
;             PG8_WAIT_V(8); PG8_WAIT_L(0); PG8_BAR; PG8_MMA(0, 0, At, B0); PG8_MMA(0, 1, At, B1); PG8_BAR; PG8_SCHED;
;             PG8_LDA(At, 0, 1); PG8_STAGE(PG8_SB(0, 0), b2, voffB); PG8_STAGE(PG8_SB(0, 1), b2 + hstep, voffB); PG8_STAGE(PG8_SA(0, 0), a2, voffA);
.LBB0_1261:
	ds_read_b128 v[154:157], v153
	ds_read_b128 v[160:163], v153 offset:1024
	ds_read_b128 v[164:167], v153 offset:2048
	ds_read_b128 v[168:171], v153 offset:3072
	ds_read_b128 v[172:175], v158
	ds_read_b128 v[178:181], v158 offset:1024
	ds_read_b128 v[182:185], v158 offset:2048
	ds_read_b128 v[186:189], v158 offset:3072
	s_add_u32 s2, s30, 0xfffc0080
	s_addc_u32 s3, s31, -1
	s_cmp_eq_u32 s61, 12
	s_cselect_b32 s19, s23, s3
	s_cselect_b32 s18, s57, s2
	s_cselect_b32 s3, s21, s60
	s_cselect_b32 s2, s58, s59
	v_lshl_add_u64 v[146:147], s[30:31], 0, v[136:137]
	s_add_i32 m0, s29, 0xc000
	ds_read_b128 v[190:193], v159
	ds_read_b128 v[194:197], v159 offset:1024
	ds_read_b128 v[198:201], v159 offset:2048
	ds_read_b128 v[202:205], v159 offset:3072
	ds_read_b128 v[206:209], v159 offset:4096
	ds_read_b128 v[210:213], v159 offset:5120
	ds_read_b128 v[214:217], v159 offset:6144
	ds_read_b128 v[218:221], v159 offset:7168
	global_load_lds_dwordx4 v[146:147], off
	v_lshl_add_u64 v[146:147], s[30:31], 0, v[138:139]
	s_add_i32 m0, s29, 0xe000
	s_nop 0
	global_load_lds_dwordx4 v[146:147], off
	s_waitcnt vmcnt(8)
	s_waitcnt lgkmcnt(0)
	s_barrier
	s_setprio 1
	s_waitcnt lgkmcnt(0)
	v_mfma_f32_16x16x32_bf16 v[124:127], v[154:157], v[190:193], v[124:127]
	v_mfma_f32_16x16x32_bf16 v[120:123], v[164:167], v[190:193], v[120:123]
	v_mfma_f32_16x16x32_bf16 v[116:119], v[154:157], v[198:201], v[116:119]
	v_mfma_f32_16x16x32_bf16 v[104:107], v[164:167], v[198:201], v[104:107]
	v_mfma_f32_16x16x32_bf16 v[92:95], v[154:157], v[206:209], v[92:95]
	v_mfma_f32_16x16x32_bf16 v[88:91], v[164:167], v[206:209], v[88:91]
	v_mfma_f32_16x16x32_bf16 v[76:79], v[154:157], v[214:217], v[76:79]
	v_mfma_f32_16x16x32_bf16 v[72:75], v[164:167], v[214:217], v[72:75]
	v_mfma_f32_16x16x32_bf16 v[124:127], v[160:163], v[194:197], v[124:127]
	v_mfma_f32_16x16x32_bf16 v[120:123], v[168:171], v[194:197], v[120:123]
	v_mfma_f32_16x16x32_bf16 v[116:119], v[160:163], v[202:205], v[116:119]
	v_mfma_f32_16x16x32_bf16 v[104:107], v[168:171], v[202:205], v[104:107]
	v_mfma_f32_16x16x32_bf16 v[92:95], v[160:163], v[210:213], v[92:95]
	v_mfma_f32_16x16x32_bf16 v[88:91], v[168:171], v[210:213], v[88:91]
	v_mfma_f32_16x16x32_bf16 v[76:79], v[160:163], v[218:221], v[76:79]
	v_mfma_f32_16x16x32_bf16 v[72:75], v[168:171], v[218:221], v[72:75]
	s_setprio 0
	s_setprio 1
	v_mfma_f32_16x16x32_bf16 v[112:115], v[172:175], v[190:193], v[112:115]
	v_mfma_f32_16x16x32_bf16 v[108:111], v[182:185], v[190:193], v[108:111]
	v_mfma_f32_16x16x32_bf16 v[100:103], v[172:175], v[198:201], v[100:103]
	v_mfma_f32_16x16x32_bf16 v[96:99], v[182:185], v[198:201], v[96:99]
	v_mfma_f32_16x16x32_bf16 v[84:87], v[172:175], v[206:209], v[84:87]
	v_mfma_f32_16x16x32_bf16 v[80:83], v[182:185], v[206:209], v[80:83]
	v_mfma_f32_16x16x32_bf16 v[68:71], v[172:175], v[214:217], v[68:71]
	v_mfma_f32_16x16x32_bf16 v[64:67], v[182:185], v[214:217], v[64:67]
	v_mfma_f32_16x16x32_bf16 v[112:115], v[178:181], v[194:197], v[112:115]
	v_mfma_f32_16x16x32_bf16 v[108:111], v[186:189], v[194:197], v[108:111]
	v_mfma_f32_16x16x32_bf16 v[100:103], v[178:181], v[202:205], v[100:103]
	v_mfma_f32_16x16x32_bf16 v[96:99], v[186:189], v[202:205], v[96:99]
	v_mfma_f32_16x16x32_bf16 v[84:87], v[178:181], v[210:213], v[84:87]
	v_mfma_f32_16x16x32_bf16 v[80:83], v[186:189], v[210:213], v[80:83]
	v_mfma_f32_16x16x32_bf16 v[68:71], v[178:181], v[218:221], v[68:71]
	v_mfma_f32_16x16x32_bf16 v[64:67], v[186:189], v[218:221], v[64:67]
	s_setprio 0
	s_barrier
	s_add_i32 s62, s50, s37
	v_lshl_add_u64 v[146:147], s[2:3], 0, v[130:131]
	s_mov_b32 m0, s62
	ds_read_b128 v[190:193], v159 offset:16384
	ds_read_b128 v[194:197], v159 offset:17408
	ds_read_b128 v[198:201], v159 offset:18432
	ds_read_b128 v[202:205], v159 offset:19456
	ds_read_b128 v[206:209], v159 offset:20480
	ds_read_b128 v[210:213], v159 offset:21504
	ds_read_b128 v[214:217], v159 offset:22528
	ds_read_b128 v[218:221], v159 offset:23552
	global_load_lds_dwordx4 v[146:147], off
	s_add_i32 m0, s62, 0x2000
	s_add_u32 s62, s2, 0x40000
	v_lshl_add_u64 v[222:223], s[2:3], 0, v[134:135]
	s_addc_u32 s63, s3, 0
	s_add_i32 s64, s51, s37
	global_load_lds_dwordx4 v[222:223], off
	v_lshl_add_u64 v[224:225], s[62:63], 0, v[130:131]
	s_mov_b32 m0, s64
	v_lshl_add_u64 v[226:227], s[18:19], 0, v[132:133]
	global_load_lds_dwordx4 v[224:225], off
	v_lshl_add_u64 v[224:225], s[62:63], 0, v[134:135]
	s_add_i32 m0, s64, 0x2000
	s_nop 0
	global_load_lds_dwordx4 v[224:225], off
	v_lshl_add_u64 v[224:225], s[18:19], 0, v[128:129]
	s_mov_b32 m0, s29
	s_nop 0
	global_load_lds_dwordx4 v[224:225], off
	s_mov_b32 m0, s42
	s_nop 0
	global_load_lds_dwordx4 v[226:227], off
	s_waitcnt vmcnt(8)
	s_waitcnt lgkmcnt(0)
	s_barrier
; #define PG8_STAGE(bufoff, gbase, voff) do { _Pragma("unroll") for (int _i = 0; _i < 2; ++_i) \
;         __builtin_amdgcn_global_load_lds((const unsigned*)((const char*)(gbase) + (voff)[_i]), (PG8_LAS unsigned*)(lds + (bufoff) + ldsw + _i * 8192), 16, 0, 0); } while (0)
; #define PG8_LDA(dst, b, h) do { _Pragma("unroll") for (int m = 0; m < 4; ++m) _Pragma("unroll") for (int k = 0; k < 2; ++k) dst[m][k] = *(const PG8_LAS bf16x8*)(lds + PG8_SA(b, h) + aoff + m * 2048 + k * 1024); } while (0)
; #define PG8_LDB(dst, b, h) do { _Pragma("unroll") for (int n = 0; n < 2; ++n) _Pragma("unroll") for (int k = 0; k < 2; ++k) dst[n][k] = *(const PG8_LAS bf16x8*)(lds + PG8_SB(b, h) + boff + n * 2048 + k * 1024); } while (0)
; #define PG8_MMA(ai, bj, At, Bt) do { __builtin_amdgcn_s_setprio(1); _Pragma("unroll") for (int m = 0; m < 4; ++m) _Pragma("unroll") for (int n = 0; n < 2; ++n) _Pragma("unroll") for (int k = 0; k < 2; ++k) \
;         acc[ai][bj][m][n] = __builtin_amdgcn_mfma_f32_16x16x32_bf16(Bt[n][k], At[m][k], acc[ai][bj][m][n], 0, 0, 0); __builtin_amdgcn_s_setprio(0); } while (0)
; #define PG8_WAIT_V(n) asm volatile("s_waitcnt vmcnt(" #n ")" ::: "memory")
; #define PG8_WAIT_L(n) asm volatile("s_waitcnt lgkmcnt(" #n ")" ::: "memory")
; #define PG8_BAR __builtin_amdgcn_s_barrier()
; #define PG8_SCHED __builtin_amdgcn_sched_barrier(0)
; template <class Epi, class Sched, bool ALIGN_EPI = false, bool SP2 = false>
; __device__ __forceinline__ void gemm_phase(PG8_LAS unsigned char* lds, const Gemm g, const Sched& S, const Epi& E) {
;     ...
;             PG8_WAIT_V(8); PG8_WAIT_L(0); PG8_BAR; PG8_MMA(1, 0, At, B0); PG8_MMA(1, 1, At, B1); PG8_BAR; PG8_SCHED;
;             PG8_LDB(B0, 1, 0); PG8_LDB(B1, 1, 1); PG8_SCHED; PG8_LDA(At, 1, 0); PG8_STAGE(PG8_SA(0, 1), a2 + hstep, voffA);
;             PG8_WAIT_V(8); PG8_WAIT_L(0); PG8_BAR; PG8_MMA(0, 0, At, B0); PG8_MMA(0, 1, At, B1); PG8_BAR; PG8_SCHED;
	s_setprio 1
	s_waitcnt lgkmcnt(0)
	v_mfma_f32_16x16x32_bf16 v[60:63], v[154:157], v[190:193], v[60:63]
	v_mfma_f32_16x16x32_bf16 v[56:59], v[164:167], v[190:193], v[56:59]
	v_mfma_f32_16x16x32_bf16 v[44:47], v[154:157], v[198:201], v[44:47]
	v_mfma_f32_16x16x32_bf16 v[40:43], v[164:167], v[198:201], v[40:43]
	v_mfma_f32_16x16x32_bf16 v[28:31], v[154:157], v[206:209], v[28:31]
	v_mfma_f32_16x16x32_bf16 v[24:27], v[164:167], v[206:209], v[24:27]
	v_mfma_f32_16x16x32_bf16 v[12:15], v[154:157], v[214:217], v[12:15]
	v_mfma_f32_16x16x32_bf16 v[8:11], v[164:167], v[214:217], v[8:11]
	v_mfma_f32_16x16x32_bf16 v[60:63], v[160:163], v[194:197], v[60:63]
	v_mfma_f32_16x16x32_bf16 v[56:59], v[168:171], v[194:197], v[56:59]
	v_mfma_f32_16x16x32_bf16 v[44:47], v[160:163], v[202:205], v[44:47]
	v_mfma_f32_16x16x32_bf16 v[40:43], v[168:171], v[202:205], v[40:43]
	v_mfma_f32_16x16x32_bf16 v[28:31], v[160:163], v[210:213], v[28:31]
	v_mfma_f32_16x16x32_bf16 v[24:27], v[168:171], v[210:213], v[24:27]
	v_mfma_f32_16x16x32_bf16 v[12:15], v[160:163], v[218:221], v[12:15]
	v_mfma_f32_16x16x32_bf16 v[8:11], v[168:171], v[218:221], v[8:11]
	s_setprio 0
	s_setprio 1
	v_mfma_f32_16x16x32_bf16 v[52:55], v[172:175], v[190:193], v[52:55]
	v_mfma_f32_16x16x32_bf16 v[48:51], v[182:185], v[190:193], v[48:51]
	v_mfma_f32_16x16x32_bf16 v[36:39], v[172:175], v[198:201], v[36:39]
	v_mfma_f32_16x16x32_bf16 v[32:35], v[182:185], v[198:201], v[32:35]
	v_mfma_f32_16x16x32_bf16 v[20:23], v[172:175], v[206:209], v[20:23]
	v_mfma_f32_16x16x32_bf16 v[16:19], v[182:185], v[206:209], v[16:19]
	v_mfma_f32_16x16x32_bf16 v[4:7], v[172:175], v[214:217], v[4:7]
	v_mfma_f32_16x16x32_bf16 v[0:3], v[182:185], v[214:217], v[0:3]
	v_mfma_f32_16x16x32_bf16 v[52:55], v[178:181], v[194:197], v[52:55]
	v_mfma_f32_16x16x32_bf16 v[48:51], v[186:189], v[194:197], v[48:51]
	v_mfma_f32_16x16x32_bf16 v[36:39], v[178:181], v[202:205], v[36:39]
	v_mfma_f32_16x16x32_bf16 v[32:35], v[186:189], v[202:205], v[32:35]
	v_mfma_f32_16x16x32_bf16 v[20:23], v[178:181], v[210:213], v[20:23]
	v_mfma_f32_16x16x32_bf16 v[16:19], v[186:189], v[210:213], v[16:19]
	v_mfma_f32_16x16x32_bf16 v[4:7], v[178:181], v[218:221], v[4:7]
	v_mfma_f32_16x16x32_bf16 v[0:3], v[186:189], v[218:221], v[0:3]
	s_setprio 0
	s_barrier
	s_add_i32 s62, 0, 0x18000
	v_add_u32_e32 v144, s62, v149
	s_add_i32 s63, 0, 0x1c000
	ds_read_b128 v[154:157], v144
	ds_read_b128 v[160:163], v144 offset:1024
	ds_read_b128 v[164:167], v144 offset:2048
	ds_read_b128 v[168:171], v144 offset:3072
	v_add_u32_e32 v144, s63, v149
	ds_read_b128 v[172:175], v144
	ds_read_b128 v[178:181], v144 offset:1024
	ds_read_b128 v[182:185], v144 offset:2048
	ds_read_b128 v[186:189], v144 offset:3072
	s_add_u32 s18, s18, 0x40000
	s_addc_u32 s19, s19, 0
	s_mov_b32 m0, s43
	v_lshl_add_u64 v[228:229], s[18:19], 0, v[128:129]
	ds_read_b128 v[190:193], v159 offset:32768
	ds_read_b128 v[194:197], v159 offset:33792
	ds_read_b128 v[198:201], v159 offset:34816
	ds_read_b128 v[202:205], v159 offset:35840
	ds_read_b128 v[206:209], v159 offset:36864
	ds_read_b128 v[210:213], v159 offset:37888
	ds_read_b128 v[214:217], v159 offset:38912
	ds_read_b128 v[218:221], v159 offset:39936
	global_load_lds_dwordx4 v[228:229], off
	v_lshl_add_u64 v[228:229], s[18:19], 0, v[132:133]
	s_mov_b32 m0, s46
	s_nop 0
	global_load_lds_dwordx4 v[228:229], off
	s_waitcnt vmcnt(8)
	s_waitcnt lgkmcnt(0)
	s_barrier
	s_setprio 1
	s_waitcnt lgkmcnt(0)
	v_mfma_f32_16x16x32_bf16 v[124:127], v[154:157], v[190:193], v[124:127]
	v_mfma_f32_16x16x32_bf16 v[120:123], v[164:167], v[190:193], v[120:123]
	v_mfma_f32_16x16x32_bf16 v[116:119], v[154:157], v[198:201], v[116:119]
	v_mfma_f32_16x16x32_bf16 v[104:107], v[164:167], v[198:201], v[104:107]
	v_mfma_f32_16x16x32_bf16 v[92:95], v[154:157], v[206:209], v[92:95]
	v_mfma_f32_16x16x32_bf16 v[88:91], v[164:167], v[206:209], v[88:91]
	v_mfma_f32_16x16x32_bf16 v[76:79], v[154:157], v[214:217], v[76:79]
	v_mfma_f32_16x16x32_bf16 v[72:75], v[164:167], v[214:217], v[72:75]
	v_mfma_f32_16x16x32_bf16 v[124:127], v[160:163], v[194:197], v[124:127]
	v_mfma_f32_16x16x32_bf16 v[120:123], v[168:171], v[194:197], v[120:123]
	v_mfma_f32_16x16x32_bf16 v[116:119], v[160:163], v[202:205], v[116:119]
	v_mfma_f32_16x16x32_bf16 v[104:107], v[168:171], v[202:205], v[104:107]
	v_mfma_f32_16x16x32_bf16 v[92:95], v[160:163], v[210:213], v[92:95]
	v_mfma_f32_16x16x32_bf16 v[88:91], v[168:171], v[210:213], v[88:91]
	v_mfma_f32_16x16x32_bf16 v[76:79], v[160:163], v[218:221], v[76:79]
	v_mfma_f32_16x16x32_bf16 v[72:75], v[168:171], v[218:221], v[72:75]
	s_setprio 0
	s_setprio 1
	v_mfma_f32_16x16x32_bf16 v[112:115], v[172:175], v[190:193], v[112:115]
	v_mfma_f32_16x16x32_bf16 v[108:111], v[182:185], v[190:193], v[108:111]
	v_mfma_f32_16x16x32_bf16 v[100:103], v[172:175], v[198:201], v[100:103]
	v_mfma_f32_16x16x32_bf16 v[96:99], v[182:185], v[198:201], v[96:99]
	v_mfma_f32_16x16x32_bf16 v[84:87], v[172:175], v[206:209], v[84:87]
	v_mfma_f32_16x16x32_bf16 v[80:83], v[182:185], v[206:209], v[80:83]
	v_mfma_f32_16x16x32_bf16 v[68:71], v[172:175], v[214:217], v[68:71]
	v_mfma_f32_16x16x32_bf16 v[64:67], v[182:185], v[214:217], v[64:67]
	v_mfma_f32_16x16x32_bf16 v[112:115], v[178:181], v[194:197], v[112:115]
	v_mfma_f32_16x16x32_bf16 v[108:111], v[186:189], v[194:197], v[108:111]
	v_mfma_f32_16x16x32_bf16 v[100:103], v[178:181], v[202:205], v[100:103]
	v_mfma_f32_16x16x32_bf16 v[96:99], v[186:189], v[202:205], v[96:99]
	v_mfma_f32_16x16x32_bf16 v[84:87], v[178:181], v[210:213], v[84:87]
	v_mfma_f32_16x16x32_bf16 v[80:83], v[186:189], v[210:213], v[80:83]
	v_mfma_f32_16x16x32_bf16 v[68:71], v[178:181], v[218:221], v[68:71]
	v_mfma_f32_16x16x32_bf16 v[64:67], v[186:189], v[218:221], v[64:67]
	s_setprio 0
	s_barrier
; #define PG8_STAGE(bufoff, gbase, voff) do { _Pragma("unroll") for (int _i = 0; _i < 2; ++_i) \
;         __builtin_amdgcn_global_load_lds((const unsigned*)((const char*)(gbase) + (voff)[_i]), (PG8_LAS unsigned*)(lds + (bufoff) + ldsw + _i * 8192), 16, 0, 0); } while (0)
; #define PG8_LDA(dst, b, h) do { _Pragma("unroll") for (int m = 0; m < 4; ++m) _Pragma("unroll") for (int k = 0; k < 2; ++k) dst[m][k] = *(const PG8_LAS bf16x8*)(lds + PG8_SA(b, h) + aoff + m * 2048 + k * 1024); } while (0)
; #define PG8_MMA(ai, bj, At, Bt) do { __builtin_amdgcn_s_setprio(1); _Pragma("unroll") for (int m = 0; m < 4; ++m) _Pragma("unroll") for (int n = 0; n < 2; ++n) _Pragma("unroll") for (int k = 0; k < 2; ++k) \
;         acc[ai][bj][m][n] = __builtin_amdgcn_mfma_f32_16x16x32_bf16(Bt[n][k], At[m][k], acc[ai][bj][m][n], 0, 0, 0); __builtin_amdgcn_s_setprio(0); } while (0)
; #define PG8_WAIT_V(n) asm volatile("s_waitcnt vmcnt(" #n ")" ::: "memory")
; #define PG8_WAIT_L(n) asm volatile("s_waitcnt lgkmcnt(" #n ")" ::: "memory")
; #define PG8_BAR __builtin_amdgcn_s_barrier()
; #define PG8_SCHED __builtin_amdgcn_sched_barrier(0)
; template <class Epi, class Sched, bool ALIGN_EPI = false, bool SP2 = false>
; __device__ __forceinline__ void gemm_phase(PG8_LAS unsigned char* lds, const Gemm g, const Sched& S, const Epi& E) {
;     ...
;         for (int t = 0; t < nt; t += 2) {
;             const bool last = (t == nt - 2);
;             const char* a1 = cA + (size_t)(t + 1) * kstep;
;             const char* a2 = last ? nA : cA + (size_t)(t + 2) * kstep; const char* b2 = last ? nB : cB + (size_t)(t + 2) * kstep;
;             const char* a3 = a2 + kstep; const char* b3 = b2 + kstep;
;     ...
;             PG8_LDA(At, 1, 1); PG8_STAGE(PG8_SB(1, 0), b3, voffB); PG8_STAGE(PG8_SB(1, 1), b3 + hstep, voffB); PG8_STAGE(PG8_SA(1, 0), a3, voffA);
;             PG8_WAIT_V(8); PG8_WAIT_L(0); PG8_BAR; PG8_MMA(1, 0, At, B0); PG8_MMA(1, 1, At, B1); PG8_BAR; PG8_SCHED;
	s_add_i32 s18, s62, s37
	v_lshl_add_u64 v[146:147], v[146:147], 0, s[6:7]
	s_mov_b32 m0, s18
	ds_read_b128 v[190:193], v159 offset:49152
	ds_read_b128 v[194:197], v159 offset:50176
	ds_read_b128 v[198:201], v159 offset:51200
	ds_read_b128 v[202:205], v159 offset:52224
	ds_read_b128 v[206:209], v159 offset:53248
	ds_read_b128 v[210:213], v159 offset:54272
	ds_read_b128 v[214:217], v159 offset:55296
	ds_read_b128 v[218:221], v159 offset:56320
	global_load_lds_dwordx4 v[146:147], off
	s_add_i32 m0, s18, 0x2000
	s_add_u32 s2, s2, 0x40080
	v_lshl_add_u64 v[146:147], v[222:223], 0, s[6:7]
	s_addc_u32 s3, s3, 0
	s_add_i32 s18, s63, s37
	global_load_lds_dwordx4 v[146:147], off
	v_lshl_add_u64 v[146:147], s[2:3], 0, v[130:131]
	s_mov_b32 m0, s18
	s_nop 0
	global_load_lds_dwordx4 v[146:147], off
	v_lshl_add_u64 v[146:147], s[2:3], 0, v[134:135]
	s_add_i32 m0, s18, 0x2000
	s_nop 0
	global_load_lds_dwordx4 v[146:147], off
	v_lshl_add_u64 v[146:147], v[224:225], 0, s[6:7]
	s_mov_b32 m0, s48
	s_nop 0
	global_load_lds_dwordx4 v[146:147], off
	v_lshl_add_u64 v[146:147], v[226:227], 0, s[6:7]
	s_mov_b32 m0, s49
	s_nop 0
	global_load_lds_dwordx4 v[146:147], off
	s_waitcnt vmcnt(8)
	s_waitcnt lgkmcnt(0)
	s_barrier
	s_setprio 1
	s_waitcnt lgkmcnt(0)
	v_mfma_f32_16x16x32_bf16 v[60:63], v[154:157], v[190:193], v[60:63]
	v_mfma_f32_16x16x32_bf16 v[56:59], v[164:167], v[190:193], v[56:59]
	v_mfma_f32_16x16x32_bf16 v[44:47], v[154:157], v[198:201], v[44:47]
	v_mfma_f32_16x16x32_bf16 v[40:43], v[164:167], v[198:201], v[40:43]
	v_mfma_f32_16x16x32_bf16 v[28:31], v[154:157], v[206:209], v[28:31]
	v_mfma_f32_16x16x32_bf16 v[24:27], v[164:167], v[206:209], v[24:27]
	v_mfma_f32_16x16x32_bf16 v[12:15], v[154:157], v[214:217], v[12:15]
	v_mfma_f32_16x16x32_bf16 v[8:11], v[164:167], v[214:217], v[8:11]
	v_mfma_f32_16x16x32_bf16 v[60:63], v[160:163], v[194:197], v[60:63]
	v_mfma_f32_16x16x32_bf16 v[56:59], v[168:171], v[194:197], v[56:59]
	v_mfma_f32_16x16x32_bf16 v[44:47], v[160:163], v[202:205], v[44:47]
	v_mfma_f32_16x16x32_bf16 v[40:43], v[168:171], v[202:205], v[40:43]
	v_mfma_f32_16x16x32_bf16 v[28:31], v[160:163], v[210:213], v[28:31]
	v_mfma_f32_16x16x32_bf16 v[24:27], v[168:171], v[210:213], v[24:27]
	v_mfma_f32_16x16x32_bf16 v[12:15], v[160:163], v[218:221], v[12:15]
	v_mfma_f32_16x16x32_bf16 v[8:11], v[168:171], v[218:221], v[8:11]
	s_setprio 0
	s_setprio 1
	v_mfma_f32_16x16x32_bf16 v[52:55], v[172:175], v[190:193], v[52:55]
	v_mfma_f32_16x16x32_bf16 v[48:51], v[182:185], v[190:193], v[48:51]
	v_mfma_f32_16x16x32_bf16 v[36:39], v[172:175], v[198:201], v[36:39]
	v_mfma_f32_16x16x32_bf16 v[32:35], v[182:185], v[198:201], v[32:35]
	v_mfma_f32_16x16x32_bf16 v[20:23], v[172:175], v[206:209], v[20:23]
	v_mfma_f32_16x16x32_bf16 v[16:19], v[182:185], v[206:209], v[16:19]
	v_mfma_f32_16x16x32_bf16 v[4:7], v[172:175], v[214:217], v[4:7]
	v_mfma_f32_16x16x32_bf16 v[0:3], v[182:185], v[214:217], v[0:3]
	v_mfma_f32_16x16x32_bf16 v[52:55], v[178:181], v[194:197], v[52:55]
	v_mfma_f32_16x16x32_bf16 v[48:51], v[186:189], v[194:197], v[48:51]
	v_mfma_f32_16x16x32_bf16 v[36:39], v[178:181], v[202:205], v[36:39]
	v_mfma_f32_16x16x32_bf16 v[32:35], v[186:189], v[202:205], v[32:35]
	v_mfma_f32_16x16x32_bf16 v[20:23], v[178:181], v[210:213], v[20:23]
	v_mfma_f32_16x16x32_bf16 v[16:19], v[186:189], v[210:213], v[16:19]
	v_mfma_f32_16x16x32_bf16 v[4:7], v[178:181], v[218:221], v[4:7]
	v_mfma_f32_16x16x32_bf16 v[0:3], v[186:189], v[218:221], v[0:3]
	s_setprio 0
	s_add_i32 s61, s61, 2
	s_add_u32 s30, s30, 0x100
	s_addc_u32 s31, s31, 0
	s_add_u32 s59, s59, 0x100
	s_addc_u32 s60, s60, 0
	s_cmp_gt_u32 s61, 13
	s_barrier
	s_cbranch_scc0 .LBB0_1261
	s_and_b64 vcc, exec, s[8:9]
	s_cbranch_vccz .LBB0_1264
	s_barrier

; #define PG8_STAGE(bufoff, gbase, voff) do { _Pragma("unroll") for (int _i = 0; _i < 2; ++_i) \
;         __builtin_amdgcn_global_load_lds((const unsigned*)((const char*)(gbase) + (voff)[_i]), (PG8_LAS unsigned*)(lds + (bufoff) + ldsw + _i * 8192), 16, 0, 0); } while (0)
; #define PG8_LDA(dst, b, h) do { _Pragma("unroll") for (int m = 0; m < 4; ++m) _Pragma("unroll") for (int k = 0; k < 2; ++k) dst[m][k] = *(const PG8_LAS bf16x8*)(lds + PG8_SA(b, h) + aoff + m * 2048 + k * 1024); } while (0)
; #define PG8_LDB(dst, b, h) do { _Pragma("unroll") for (int n = 0; n < 2; ++n) _Pragma("unroll") for (int k = 0; k < 2; ++k) dst[n][k] = *(const PG8_LAS bf16x8*)(lds + PG8_SB(b, h) + boff + n * 2048 + k * 1024); } while (0)
; #define PG8_MMA(ai, bj, At, Bt) do { __builtin_amdgcn_s_setprio(1); _Pragma("unroll") for (int m = 0; m < 4; ++m) _Pragma("unroll") for (int n = 0; n < 2; ++n) _Pragma("unroll") for (int k = 0; k < 2; ++k) \
;         acc[ai][bj][m][n] = __builtin_amdgcn_mfma_f32_16x16x32_bf16(Bt[n][k], At[m][k], acc[ai][bj][m][n], 0, 0, 0); __builtin_amdgcn_s_setprio(0); } while (0)
; #define PG8_WAIT_V(n) asm volatile("s_waitcnt vmcnt(" #n ")" ::: "memory")
; #define PG8_WAIT_L(n) asm volatile("s_waitcnt lgkmcnt(" #n ")" ::: "memory")
; #define PG8_BAR __builtin_amdgcn_s_barrier()
; #define PG8_SCHED __builtin_amdgcn_sched_barrier(0)
; template <class Epi, class Sched, bool ALIGN_EPI = false, bool SP2 = false>
; __device__ __forceinline__ void gemm_phase(PG8_LAS unsigned char* lds, const Gemm g, const Sched& S, const Epi& E) {
;     ...
;         for (int t = 0; t < nt; t += 2) {
;             const bool last = (t == nt - 2);
;             const char* a1 = cA + (size_t)(t + 1) * kstep;
;             const char* a2 = last ? nA : cA + (size_t)(t + 2) * kstep; const char* b2 = last ? nB : cB + (size_t)(t + 2) * kstep;
;             const char* a3 = a2 + kstep; const char* b3 = b2 + kstep;
;             if (last && has_next) S.a_ready(nxt);
;             if constexpr (SP2) {
;             PG8_LDB(B0, 0, 0); PG8_LDB(B1, 0, 1); PG8_SCHED; PG8_LDA(At, 0, 0); PG8_STAGE(PG8_SA(1, 1), a1 + hstep, voffA);
;             PG8_WAIT_V(8); PG8_WAIT_L(0); PG8_BAR; PG8_MMA(0, 0, At, B0); PG8_MMA(0, 1, At, B1); PG8_BAR; PG8_SCHED;
;             PG8_LDA(At, 0, 1); PG8_STAGE(PG8_SB(0, 0), b2, voffB); PG8_STAGE(PG8_SB(0, 1), b2 + hstep, voffB); PG8_STAGE(PG8_SA(0, 0), a2, voffA);
.LBB0_1340:
	ds_read_b128 v[128:131], v165
	ds_read_b128 v[132:135], v165 offset:1024
	ds_read_b128 v[152:155], v165 offset:2048
	ds_read_b128 v[156:159], v165 offset:3072
	ds_read_b128 v[168:171], v166
	ds_read_b128 v[172:175], v166 offset:1024
	ds_read_b128 v[178:181], v166 offset:2048
	ds_read_b128 v[182:185], v166 offset:3072
	s_add_u32 s2, s22, 0xfff00080
	s_addc_u32 s3, s23, -1
	s_cmp_eq_u32 s48, 60
	s_cselect_b32 s19, s13, s3
	s_cselect_b32 s18, s44, s2
	s_cselect_b32 s3, s11, s47
	s_cselect_b32 s2, s45, s46
	v_lshl_add_u64 v[160:161], s[22:23], 0, v[144:145]
	s_add_i32 m0, s21, 0xc000
	ds_read_b128 v[186:189], v167
	ds_read_b128 v[190:193], v167 offset:1024
	ds_read_b128 v[194:197], v167 offset:2048
	ds_read_b128 v[198:201], v167 offset:3072
	ds_read_b128 v[202:205], v167 offset:4096
	ds_read_b128 v[206:209], v167 offset:5120
	ds_read_b128 v[210:213], v167 offset:6144
	ds_read_b128 v[214:217], v167 offset:7168
	global_load_lds_dwordx4 v[160:161], off
	v_lshl_add_u64 v[160:161], s[22:23], 0, v[146:147]
	s_add_i32 m0, s21, 0xe000
	s_nop 0
	global_load_lds_dwordx4 v[160:161], off
	s_waitcnt vmcnt(8)
	s_waitcnt lgkmcnt(0)
	s_barrier
	s_setprio 1
	s_waitcnt lgkmcnt(0)
	v_mfma_f32_16x16x32_bf16 v[124:127], v[128:131], v[186:189], v[124:127]
	v_mfma_f32_16x16x32_bf16 v[120:123], v[152:155], v[186:189], v[120:123]
	v_mfma_f32_16x16x32_bf16 v[116:119], v[128:131], v[194:197], v[116:119]
	v_mfma_f32_16x16x32_bf16 v[108:111], v[152:155], v[194:197], v[108:111]
	v_mfma_f32_16x16x32_bf16 v[92:95], v[128:131], v[202:205], v[92:95]
	v_mfma_f32_16x16x32_bf16 v[88:91], v[152:155], v[202:205], v[88:91]
	v_mfma_f32_16x16x32_bf16 v[76:79], v[128:131], v[210:213], v[76:79]
	v_mfma_f32_16x16x32_bf16 v[72:75], v[152:155], v[210:213], v[72:75]
	v_mfma_f32_16x16x32_bf16 v[124:127], v[132:135], v[190:193], v[124:127]
	v_mfma_f32_16x16x32_bf16 v[120:123], v[156:159], v[190:193], v[120:123]
	v_mfma_f32_16x16x32_bf16 v[116:119], v[132:135], v[198:201], v[116:119]
	v_mfma_f32_16x16x32_bf16 v[108:111], v[156:159], v[198:201], v[108:111]
	v_mfma_f32_16x16x32_bf16 v[92:95], v[132:135], v[206:209], v[92:95]
	v_mfma_f32_16x16x32_bf16 v[88:91], v[156:159], v[206:209], v[88:91]
	v_mfma_f32_16x16x32_bf16 v[76:79], v[132:135], v[214:217], v[76:79]
	v_mfma_f32_16x16x32_bf16 v[72:75], v[156:159], v[214:217], v[72:75]
	s_setprio 0
	s_setprio 1
	v_mfma_f32_16x16x32_bf16 v[112:115], v[168:171], v[186:189], v[112:115]
	v_mfma_f32_16x16x32_bf16 v[104:107], v[178:181], v[186:189], v[104:107]
	v_mfma_f32_16x16x32_bf16 v[100:103], v[168:171], v[194:197], v[100:103]
	v_mfma_f32_16x16x32_bf16 v[96:99], v[178:181], v[194:197], v[96:99]
	v_mfma_f32_16x16x32_bf16 v[84:87], v[168:171], v[202:205], v[84:87]
	v_mfma_f32_16x16x32_bf16 v[80:83], v[178:181], v[202:205], v[80:83]
	v_mfma_f32_16x16x32_bf16 v[68:71], v[168:171], v[210:213], v[68:71]
	v_mfma_f32_16x16x32_bf16 v[64:67], v[178:181], v[210:213], v[64:67]
	v_mfma_f32_16x16x32_bf16 v[112:115], v[172:175], v[190:193], v[112:115]
	v_mfma_f32_16x16x32_bf16 v[104:107], v[182:185], v[190:193], v[104:107]
	v_mfma_f32_16x16x32_bf16 v[100:103], v[172:175], v[198:201], v[100:103]
	v_mfma_f32_16x16x32_bf16 v[96:99], v[182:185], v[198:201], v[96:99]
	v_mfma_f32_16x16x32_bf16 v[84:87], v[172:175], v[206:209], v[84:87]
	v_mfma_f32_16x16x32_bf16 v[80:83], v[182:185], v[206:209], v[80:83]
	v_mfma_f32_16x16x32_bf16 v[68:71], v[172:175], v[214:217], v[68:71]
	v_mfma_f32_16x16x32_bf16 v[64:67], v[182:185], v[214:217], v[64:67]
	s_setprio 0
	s_barrier
	s_add_i32 s49, s37, s27
	v_lshl_add_u64 v[160:161], s[2:3], 0, v[138:139]
	s_mov_b32 m0, s49
	ds_read_b128 v[186:189], v167 offset:16384
	ds_read_b128 v[190:193], v167 offset:17408
	ds_read_b128 v[194:197], v167 offset:18432
	ds_read_b128 v[198:201], v167 offset:19456
	ds_read_b128 v[202:205], v167 offset:20480
	ds_read_b128 v[206:209], v167 offset:21504
	ds_read_b128 v[210:213], v167 offset:22528
	ds_read_b128 v[214:217], v167 offset:23552
	global_load_lds_dwordx4 v[160:161], off
	s_add_i32 m0, s49, 0x2000
	s_add_u32 s50, s2, 0x100000
	v_lshl_add_u64 v[218:219], s[2:3], 0, v[142:143]
	s_addc_u32 s51, s3, 0
	s_add_i32 s49, s42, s27
	global_load_lds_dwordx4 v[218:219], off
	v_lshl_add_u64 v[220:221], s[50:51], 0, v[138:139]
	s_mov_b32 m0, s49
	v_lshl_add_u64 v[222:223], s[18:19], 0, v[140:141]
	global_load_lds_dwordx4 v[220:221], off
	v_lshl_add_u64 v[220:221], s[50:51], 0, v[142:143]
	s_add_i32 m0, s49, 0x2000
	s_nop 0
	global_load_lds_dwordx4 v[220:221], off
	v_lshl_add_u64 v[220:221], s[18:19], 0, v[136:137]
	s_mov_b32 m0, s21
	s_nop 0
	global_load_lds_dwordx4 v[220:221], off
	s_mov_b32 m0, s28
	s_nop 0
	global_load_lds_dwordx4 v[222:223], off
	s_waitcnt vmcnt(8)
	s_waitcnt lgkmcnt(0)
	s_barrier
; #define PG8_STAGE(bufoff, gbase, voff) do { _Pragma("unroll") for (int _i = 0; _i < 2; ++_i) \
;         __builtin_amdgcn_global_load_lds((const unsigned*)((const char*)(gbase) + (voff)[_i]), (PG8_LAS unsigned*)(lds + (bufoff) + ldsw + _i * 8192), 16, 0, 0); } while (0)
; #define PG8_LDA(dst, b, h) do { _Pragma("unroll") for (int m = 0; m < 4; ++m) _Pragma("unroll") for (int k = 0; k < 2; ++k) dst[m][k] = *(const PG8_LAS bf16x8*)(lds + PG8_SA(b, h) + aoff + m * 2048 + k * 1024); } while (0)
; #define PG8_LDB(dst, b, h) do { _Pragma("unroll") for (int n = 0; n < 2; ++n) _Pragma("unroll") for (int k = 0; k < 2; ++k) dst[n][k] = *(const PG8_LAS bf16x8*)(lds + PG8_SB(b, h) + boff + n * 2048 + k * 1024); } while (0)
; #define PG8_MMA(ai, bj, At, Bt) do { __builtin_amdgcn_s_setprio(1); _Pragma("unroll") for (int m = 0; m < 4; ++m) _Pragma("unroll") for (int n = 0; n < 2; ++n) _Pragma("unroll") for (int k = 0; k < 2; ++k) \
;         acc[ai][bj][m][n] = __builtin_amdgcn_mfma_f32_16x16x32_bf16(Bt[n][k], At[m][k], acc[ai][bj][m][n], 0, 0, 0); __builtin_amdgcn_s_setprio(0); } while (0)
; #define PG8_WAIT_V(n) asm volatile("s_waitcnt vmcnt(" #n ")" ::: "memory")
; #define PG8_WAIT_L(n) asm volatile("s_waitcnt lgkmcnt(" #n ")" ::: "memory")
; #define PG8_BAR __builtin_amdgcn_s_barrier()
; #define PG8_SCHED __builtin_amdgcn_sched_barrier(0)
; template <class Epi, class Sched, bool ALIGN_EPI = false, bool SP2 = false>
; __device__ __forceinline__ void gemm_phase(PG8_LAS unsigned char* lds, const Gemm g, const Sched& S, const Epi& E) {
;     ...
;             PG8_WAIT_V(8); PG8_WAIT_L(0); PG8_BAR; PG8_MMA(1, 0, At, B0); PG8_MMA(1, 1, At, B1); PG8_BAR; PG8_SCHED;
;             PG8_LDB(B0, 1, 0); PG8_LDB(B1, 1, 1); PG8_SCHED; PG8_LDA(At, 1, 0); PG8_STAGE(PG8_SA(0, 1), a2 + hstep, voffA);
;             PG8_WAIT_V(8); PG8_WAIT_L(0); PG8_BAR; PG8_MMA(0, 0, At, B0); PG8_MMA(0, 1, At, B1); PG8_BAR; PG8_SCHED;
	s_setprio 1
	s_waitcnt lgkmcnt(0)
	v_mfma_f32_16x16x32_bf16 v[60:63], v[128:131], v[186:189], v[60:63]
	v_mfma_f32_16x16x32_bf16 v[56:59], v[152:155], v[186:189], v[56:59]
	v_mfma_f32_16x16x32_bf16 v[48:51], v[128:131], v[194:197], v[48:51]
	v_mfma_f32_16x16x32_bf16 v[44:47], v[152:155], v[194:197], v[44:47]
	v_mfma_f32_16x16x32_bf16 v[36:39], v[128:131], v[202:205], v[36:39]
	v_mfma_f32_16x16x32_bf16 v[28:31], v[152:155], v[202:205], v[28:31]
	v_mfma_f32_16x16x32_bf16 v[20:23], v[128:131], v[210:213], v[20:23]
	v_mfma_f32_16x16x32_bf16 v[8:11], v[152:155], v[210:213], v[8:11]
	v_mfma_f32_16x16x32_bf16 v[60:63], v[132:135], v[190:193], v[60:63]
	v_mfma_f32_16x16x32_bf16 v[56:59], v[156:159], v[190:193], v[56:59]
	v_mfma_f32_16x16x32_bf16 v[48:51], v[132:135], v[198:201], v[48:51]
	v_mfma_f32_16x16x32_bf16 v[44:47], v[156:159], v[198:201], v[44:47]
	v_mfma_f32_16x16x32_bf16 v[36:39], v[132:135], v[206:209], v[36:39]
	v_mfma_f32_16x16x32_bf16 v[28:31], v[156:159], v[206:209], v[28:31]
	v_mfma_f32_16x16x32_bf16 v[20:23], v[132:135], v[214:217], v[20:23]
	v_mfma_f32_16x16x32_bf16 v[8:11], v[156:159], v[214:217], v[8:11]
	s_setprio 0
	s_setprio 1
	v_mfma_f32_16x16x32_bf16 v[52:55], v[168:171], v[186:189], v[52:55]
	v_mfma_f32_16x16x32_bf16 v[40:43], v[178:181], v[186:189], v[40:43]
	v_mfma_f32_16x16x32_bf16 v[32:35], v[168:171], v[194:197], v[32:35]
	v_mfma_f32_16x16x32_bf16 v[24:27], v[178:181], v[194:197], v[24:27]
	v_mfma_f32_16x16x32_bf16 v[16:19], v[168:171], v[202:205], v[16:19]
	v_mfma_f32_16x16x32_bf16 v[12:15], v[178:181], v[202:205], v[12:15]
	v_mfma_f32_16x16x32_bf16 v[4:7], v[168:171], v[210:213], v[4:7]
	v_mfma_f32_16x16x32_bf16 v[0:3], v[178:181], v[210:213], v[0:3]
	v_mfma_f32_16x16x32_bf16 v[52:55], v[172:175], v[190:193], v[52:55]
	v_mfma_f32_16x16x32_bf16 v[40:43], v[182:185], v[190:193], v[40:43]
	v_mfma_f32_16x16x32_bf16 v[32:35], v[172:175], v[198:201], v[32:35]
	v_mfma_f32_16x16x32_bf16 v[24:27], v[182:185], v[198:201], v[24:27]
	v_mfma_f32_16x16x32_bf16 v[16:19], v[172:175], v[206:209], v[16:19]
	v_mfma_f32_16x16x32_bf16 v[12:15], v[182:185], v[206:209], v[12:15]
	v_mfma_f32_16x16x32_bf16 v[4:7], v[172:175], v[214:217], v[4:7]
	v_mfma_f32_16x16x32_bf16 v[0:3], v[182:185], v[214:217], v[0:3]
	s_setprio 0
	s_barrier
	s_add_i32 s49, 0, 0x18000
	s_add_i32 s50, 0, 0x1c000
	v_add_u32_e32 v156, s49, v163
	v_add_u32_e32 v177, s50, v163
	ds_read_b128 v[128:131], v156
	ds_read_b128 v[132:135], v156 offset:1024
	ds_read_b128 v[152:155], v156 offset:2048
	ds_read_b128 v[156:159], v156 offset:3072
	ds_read_b128 v[168:171], v177
	ds_read_b128 v[172:175], v177 offset:1024
	ds_read_b128 v[178:181], v177 offset:2048
	ds_read_b128 v[182:185], v177 offset:3072
	s_add_u32 s18, s18, 0x100000
	s_addc_u32 s19, s19, 0
	s_mov_b32 m0, s29
	v_lshl_add_u64 v[224:225], s[18:19], 0, v[136:137]
	ds_read_b128 v[186:189], v167 offset:32768
	ds_read_b128 v[190:193], v167 offset:33792
	ds_read_b128 v[194:197], v167 offset:34816
	ds_read_b128 v[198:201], v167 offset:35840
	ds_read_b128 v[202:205], v167 offset:36864
	ds_read_b128 v[206:209], v167 offset:37888
	ds_read_b128 v[210:213], v167 offset:38912
	ds_read_b128 v[214:217], v167 offset:39936
	global_load_lds_dwordx4 v[224:225], off
	v_lshl_add_u64 v[224:225], s[18:19], 0, v[140:141]
	s_mov_b32 m0, s30
	s_nop 0
	global_load_lds_dwordx4 v[224:225], off
	s_waitcnt vmcnt(8)
	s_waitcnt lgkmcnt(0)
	s_barrier
	s_setprio 1
	s_waitcnt lgkmcnt(0)
	v_mfma_f32_16x16x32_bf16 v[124:127], v[128:131], v[186:189], v[124:127]
	v_mfma_f32_16x16x32_bf16 v[120:123], v[152:155], v[186:189], v[120:123]
	v_mfma_f32_16x16x32_bf16 v[116:119], v[128:131], v[194:197], v[116:119]
	v_mfma_f32_16x16x32_bf16 v[108:111], v[152:155], v[194:197], v[108:111]
	v_mfma_f32_16x16x32_bf16 v[92:95], v[128:131], v[202:205], v[92:95]
	v_mfma_f32_16x16x32_bf16 v[88:91], v[152:155], v[202:205], v[88:91]
	v_mfma_f32_16x16x32_bf16 v[76:79], v[128:131], v[210:213], v[76:79]
	v_mfma_f32_16x16x32_bf16 v[72:75], v[152:155], v[210:213], v[72:75]
	v_mfma_f32_16x16x32_bf16 v[124:127], v[132:135], v[190:193], v[124:127]
	v_mfma_f32_16x16x32_bf16 v[120:123], v[156:159], v[190:193], v[120:123]
	v_mfma_f32_16x16x32_bf16 v[116:119], v[132:135], v[198:201], v[116:119]
	v_mfma_f32_16x16x32_bf16 v[108:111], v[156:159], v[198:201], v[108:111]
	v_mfma_f32_16x16x32_bf16 v[92:95], v[132:135], v[206:209], v[92:95]
	v_mfma_f32_16x16x32_bf16 v[88:91], v[156:159], v[206:209], v[88:91]
	v_mfma_f32_16x16x32_bf16 v[76:79], v[132:135], v[214:217], v[76:79]
	v_mfma_f32_16x16x32_bf16 v[72:75], v[156:159], v[214:217], v[72:75]
	s_setprio 0
	s_setprio 1
	v_mfma_f32_16x16x32_bf16 v[112:115], v[168:171], v[186:189], v[112:115]
	v_mfma_f32_16x16x32_bf16 v[104:107], v[178:181], v[186:189], v[104:107]
	v_mfma_f32_16x16x32_bf16 v[100:103], v[168:171], v[194:197], v[100:103]
	v_mfma_f32_16x16x32_bf16 v[96:99], v[178:181], v[194:197], v[96:99]
	v_mfma_f32_16x16x32_bf16 v[84:87], v[168:171], v[202:205], v[84:87]
	v_mfma_f32_16x16x32_bf16 v[80:83], v[178:181], v[202:205], v[80:83]
	v_mfma_f32_16x16x32_bf16 v[68:71], v[168:171], v[210:213], v[68:71]
	v_mfma_f32_16x16x32_bf16 v[64:67], v[178:181], v[210:213], v[64:67]
	v_mfma_f32_16x16x32_bf16 v[112:115], v[172:175], v[190:193], v[112:115]
	v_mfma_f32_16x16x32_bf16 v[104:107], v[182:185], v[190:193], v[104:107]
	v_mfma_f32_16x16x32_bf16 v[100:103], v[172:175], v[198:201], v[100:103]
	v_mfma_f32_16x16x32_bf16 v[96:99], v[182:185], v[198:201], v[96:99]
	v_mfma_f32_16x16x32_bf16 v[84:87], v[172:175], v[206:209], v[84:87]
	v_mfma_f32_16x16x32_bf16 v[80:83], v[182:185], v[206:209], v[80:83]
	v_mfma_f32_16x16x32_bf16 v[68:71], v[172:175], v[214:217], v[68:71]
	v_mfma_f32_16x16x32_bf16 v[64:67], v[182:185], v[214:217], v[64:67]
	s_setprio 0
	s_barrier
; #define PG8_STAGE(bufoff, gbase, voff) do { _Pragma("unroll") for (int _i = 0; _i < 2; ++_i) \
;         __builtin_amdgcn_global_load_lds((const unsigned*)((const char*)(gbase) + (voff)[_i]), (PG8_LAS unsigned*)(lds + (bufoff) + ldsw + _i * 8192), 16, 0, 0); } while (0)
; #define PG8_LDA(dst, b, h) do { _Pragma("unroll") for (int m = 0; m < 4; ++m) _Pragma("unroll") for (int k = 0; k < 2; ++k) dst[m][k] = *(const PG8_LAS bf16x8*)(lds + PG8_SA(b, h) + aoff + m * 2048 + k * 1024); } while (0)
; #define PG8_MMA(ai, bj, At, Bt) do { __builtin_amdgcn_s_setprio(1); _Pragma("unroll") for (int m = 0; m < 4; ++m) _Pragma("unroll") for (int n = 0; n < 2; ++n) _Pragma("unroll") for (int k = 0; k < 2; ++k) \
;         acc[ai][bj][m][n] = __builtin_amdgcn_mfma_f32_16x16x32_bf16(Bt[n][k], At[m][k], acc[ai][bj][m][n], 0, 0, 0); __builtin_amdgcn_s_setprio(0); } while (0)
; #define PG8_WAIT_V(n) asm volatile("s_waitcnt vmcnt(" #n ")" ::: "memory")
; #define PG8_WAIT_L(n) asm volatile("s_waitcnt lgkmcnt(" #n ")" ::: "memory")
; #define PG8_BAR __builtin_amdgcn_s_barrier()
; #define PG8_SCHED __builtin_amdgcn_sched_barrier(0)
; template <class Epi, class Sched, bool ALIGN_EPI = false, bool SP2 = false>
; __device__ __forceinline__ void gemm_phase(PG8_LAS unsigned char* lds, const Gemm g, const Sched& S, const Epi& E) {
;     ...
;         for (int t = 0; t < nt; t += 2) {
;             const bool last = (t == nt - 2);
;             const char* a1 = cA + (size_t)(t + 1) * kstep;
;             const char* a2 = last ? nA : cA + (size_t)(t + 2) * kstep; const char* b2 = last ? nB : cB + (size_t)(t + 2) * kstep;
;             const char* a3 = a2 + kstep; const char* b3 = b2 + kstep;
;     ...
;             PG8_LDA(At, 1, 1); PG8_STAGE(PG8_SB(1, 0), b3, voffB); PG8_STAGE(PG8_SB(1, 1), b3 + hstep, voffB); PG8_STAGE(PG8_SA(1, 0), a3, voffA);
;             PG8_WAIT_V(8); PG8_WAIT_L(0); PG8_BAR; PG8_MMA(1, 0, At, B0); PG8_MMA(1, 1, At, B1); PG8_BAR; PG8_SCHED;
	s_add_i32 s18, s49, s27
	v_lshl_add_u64 v[160:161], v[160:161], 0, s[6:7]
	s_mov_b32 m0, s18
	ds_read_b128 v[186:189], v167 offset:49152
	ds_read_b128 v[190:193], v167 offset:50176
	ds_read_b128 v[194:197], v167 offset:51200
	ds_read_b128 v[198:201], v167 offset:52224
	ds_read_b128 v[202:205], v167 offset:53248
	ds_read_b128 v[206:209], v167 offset:54272
	ds_read_b128 v[210:213], v167 offset:55296
	ds_read_b128 v[214:217], v167 offset:56320
	global_load_lds_dwordx4 v[160:161], off
	s_add_i32 m0, s18, 0x2000
	s_add_u32 s2, s2, 0x100080
	v_lshl_add_u64 v[160:161], v[218:219], 0, s[6:7]
	s_addc_u32 s3, s3, 0
	s_add_i32 s18, s50, s27
	global_load_lds_dwordx4 v[160:161], off
	v_lshl_add_u64 v[160:161], s[2:3], 0, v[138:139]
	s_mov_b32 m0, s18
	s_nop 0
	global_load_lds_dwordx4 v[160:161], off
	v_lshl_add_u64 v[160:161], s[2:3], 0, v[142:143]
	s_add_i32 m0, s18, 0x2000
	s_nop 0
	global_load_lds_dwordx4 v[160:161], off
	v_lshl_add_u64 v[160:161], v[220:221], 0, s[6:7]
	s_mov_b32 m0, s33
	s_nop 0
	global_load_lds_dwordx4 v[160:161], off
	v_lshl_add_u64 v[160:161], v[222:223], 0, s[6:7]
	s_mov_b32 m0, s34
	s_nop 0
	global_load_lds_dwordx4 v[160:161], off
	s_waitcnt vmcnt(8)
	s_waitcnt lgkmcnt(0)
	s_barrier
	s_setprio 1
	s_waitcnt lgkmcnt(0)
	v_mfma_f32_16x16x32_bf16 v[60:63], v[128:131], v[186:189], v[60:63]
	v_mfma_f32_16x16x32_bf16 v[56:59], v[152:155], v[186:189], v[56:59]
	v_mfma_f32_16x16x32_bf16 v[48:51], v[128:131], v[194:197], v[48:51]
	v_mfma_f32_16x16x32_bf16 v[44:47], v[152:155], v[194:197], v[44:47]
	v_mfma_f32_16x16x32_bf16 v[36:39], v[128:131], v[202:205], v[36:39]
	v_mfma_f32_16x16x32_bf16 v[28:31], v[152:155], v[202:205], v[28:31]
	v_mfma_f32_16x16x32_bf16 v[20:23], v[128:131], v[210:213], v[20:23]
	v_mfma_f32_16x16x32_bf16 v[8:11], v[152:155], v[210:213], v[8:11]
	v_mfma_f32_16x16x32_bf16 v[60:63], v[132:135], v[190:193], v[60:63]
	v_mfma_f32_16x16x32_bf16 v[56:59], v[156:159], v[190:193], v[56:59]
	v_mfma_f32_16x16x32_bf16 v[48:51], v[132:135], v[198:201], v[48:51]
	v_mfma_f32_16x16x32_bf16 v[44:47], v[156:159], v[198:201], v[44:47]
	v_mfma_f32_16x16x32_bf16 v[36:39], v[132:135], v[206:209], v[36:39]
	v_mfma_f32_16x16x32_bf16 v[28:31], v[156:159], v[206:209], v[28:31]
	v_mfma_f32_16x16x32_bf16 v[20:23], v[132:135], v[214:217], v[20:23]
	v_mfma_f32_16x16x32_bf16 v[8:11], v[156:159], v[214:217], v[8:11]
	s_setprio 0
	s_setprio 1
	v_mfma_f32_16x16x32_bf16 v[52:55], v[168:171], v[186:189], v[52:55]
	v_mfma_f32_16x16x32_bf16 v[40:43], v[178:181], v[186:189], v[40:43]
	v_mfma_f32_16x16x32_bf16 v[32:35], v[168:171], v[194:197], v[32:35]
	v_mfma_f32_16x16x32_bf16 v[24:27], v[178:181], v[194:197], v[24:27]
	v_mfma_f32_16x16x32_bf16 v[16:19], v[168:171], v[202:205], v[16:19]
	v_mfma_f32_16x16x32_bf16 v[12:15], v[178:181], v[202:205], v[12:15]
	v_mfma_f32_16x16x32_bf16 v[4:7], v[168:171], v[210:213], v[4:7]
	v_mfma_f32_16x16x32_bf16 v[0:3], v[178:181], v[210:213], v[0:3]
	v_mfma_f32_16x16x32_bf16 v[52:55], v[172:175], v[190:193], v[52:55]
	v_mfma_f32_16x16x32_bf16 v[40:43], v[182:185], v[190:193], v[40:43]
	v_mfma_f32_16x16x32_bf16 v[32:35], v[172:175], v[198:201], v[32:35]
	v_mfma_f32_16x16x32_bf16 v[24:27], v[182:185], v[198:201], v[24:27]
	v_mfma_f32_16x16x32_bf16 v[16:19], v[172:175], v[206:209], v[16:19]
	v_mfma_f32_16x16x32_bf16 v[12:15], v[182:185], v[206:209], v[12:15]
	v_mfma_f32_16x16x32_bf16 v[4:7], v[172:175], v[214:217], v[4:7]
	v_mfma_f32_16x16x32_bf16 v[0:3], v[182:185], v[214:217], v[0:3]
	s_setprio 0
	s_add_i32 s48, s48, 2
	s_add_u32 s22, s22, 0x100
	s_addc_u32 s23, s23, 0
	s_add_u32 s46, s46, 0x100
	s_addc_u32 s47, s47, 0
	s_cmp_gt_u32 s48, 61
	s_barrier
	s_cbranch_scc0 .LBB0_1340
	s_and_b64 vcc, exec, s[8:9]
	s_cbranch_vccz .LBB0_1343
	s_barrier
